# bf16 GEMM / attention / DFT output stores written through at agent scope (sc1): less dirty L2 to flush at the phase barriers
# baseline (speedup 1.0000x reference)
; DI u32x4 pk8(const f32x4& a, const f32x4& b) { u32x4 w; w.x = pk2(a[0], a[1]); w.y = pk2(a[2], a[3]); w.z = pk2(b[0], b[1]); w.w = pk2(b[2], b[3]); return w; }
; #define FOR_AI_M _Pragma("unroll") for (int ai = 0; ai < 2; ++ai) _Pragma("unroll") for (int m = 0; m < 4; ++m)
;     DI void operator()(Acc& acc, const Unit& u, int wr, int wc, int fr, int fq) const {
;         bf16_t* U = (bf16_t*)(F.ws + WS_U);
;         FOR_AI_M { const int r = u.pm * 256 + EPI_ROWS(ai, m);
; #pragma unroll
;             for (int bj = 0; bj < 2; ++bj) { f32x4 a = acc[ai][bj][m][0], b = acc[ai][bj][m][1];
; #pragma unroll
;                 for (int e = 0; e < 4; ++e) { const float x = fmaxf(a[e], 0.f), y = fmaxf(b[e], 0.f); a[e] = x * x; b[e] = y * y; }
;                 *(u32x4*)(U + (size_t)r * DFF + u.pn * 256 + EPI_COL8(bj)) = pk8(a, b); } }
;     }
.LBB0_101:
	s_lshl_b32 s8, s59, 8
	v_max_f32_e32 v122, v122, v122
	v_max_f32_e32 v123, v123, v123
	s_ashr_i32 s9, s8, 31
	v_max_f32_e32 v122, 0, v122
	v_max_f32_e32 v123, 0, v123
	v_lshl_add_u32 v142, s60, 8, v144
	s_lshl_b64 s[8:9], s[8:9], 1
	v_pk_mul_f32 v[150:151], v[122:123], v[122:123]
	v_max_f32_e32 v123, v124, v124
	s_add_u32 s28, s56, s8
	v_ashrrev_i32_e32 v143, 31, v142
	v_max_f32_e32 v126, v126, v126
	v_max_f32_e32 v127, v127, v127
	v_max_f32_e32 v122, v128, v128
	v_max_f32_e32 v124, 0, v123
	v_max_f32_e32 v123, v129, v129
	v_max_f32_e32 v125, v125, v125
	s_addc_u32 s29, s57, s9
	v_lshlrev_b64 v[148:149], 13, v[142:143]
	v_max_f32_e32 v126, 0, v126
	v_max_f32_e32 v127, 0, v127
	v_max_f32_e32 v122, 0, v122
	v_max_f32_e32 v123, 0, v123
	v_max_f32_e32 v125, 0, v125
	v_lshl_add_u64 v[148:149], s[28:29], 0, v[148:149]
	v_pk_mul_f32 v[126:127], v[126:127], v[126:127]
	v_pk_mul_f32 v[128:129], v[122:123], v[122:123]
	v_pk_mul_f32 v[152:153], v[124:125], v[124:125]
	v_max_f32_e32 v114, v114, v114
	v_max_f32_e32 v115, v115, v115
	v_cvt_pk_bf16_f32 v122, v126, v127
	v_cvt_pk_bf16_f32 v123, v128, v129
	v_cvt_pk_bf16_f32 v124, v150, v151
	v_cvt_pk_bf16_f32 v125, v152, v153
	v_lshl_add_u64 v[126:127], v[148:149], 0, v[96:97]
	v_max_f32_e32 v114, 0, v114
	v_max_f32_e32 v115, 0, v115
	global_store_dwordx4 v[126:127], v[122:125], off sc1
	v_max_f32_e32 v118, v118, v118
	v_max_f32_e32 v119, v119, v119
	v_pk_mul_f32 v[122:123], v[114:115], v[114:115]
	v_max_f32_e32 v115, v116, v116
	v_max_f32_e32 v114, v120, v120
	v_max_f32_e32 v116, 0, v115
	v_max_f32_e32 v115, v121, v121
	v_max_f32_e32 v117, v117, v117
	v_max_f32_e32 v118, 0, v118
	v_max_f32_e32 v119, 0, v119
	v_max_f32_e32 v114, 0, v114
	v_max_f32_e32 v115, 0, v115
	v_max_f32_e32 v117, 0, v117
	v_pk_mul_f32 v[118:119], v[118:119], v[118:119]
	v_pk_mul_f32 v[120:121], v[114:115], v[114:115]
	v_pk_mul_f32 v[124:125], v[116:117], v[116:117]
	v_max_f32_e32 v106, v106, v106
	v_max_f32_e32 v107, v107, v107
	v_cvt_pk_bf16_f32 v114, v118, v119
	v_cvt_pk_bf16_f32 v115, v120, v121
	v_cvt_pk_bf16_f32 v116, v122, v123
	v_cvt_pk_bf16_f32 v117, v124, v125
	v_max_f32_e32 v106, 0, v106
	v_max_f32_e32 v107, 0, v107
	global_store_dwordx4 v[126:127], v[114:117], off offset:256 sc1
	v_max_f32_e32 v110, v110, v110
	v_max_f32_e32 v111, v111, v111
	v_or_b32_e32 v114, 16, v142
	v_pk_mul_f32 v[116:117], v[106:107], v[106:107]
	v_max_f32_e32 v107, v108, v108
	v_ashrrev_i32_e32 v115, 31, v114
	v_max_f32_e32 v106, v112, v112
	v_max_f32_e32 v108, 0, v107
	v_max_f32_e32 v107, v113, v113
	v_max_f32_e32 v109, v109, v109
	v_lshlrev_b64 v[114:115], 13, v[114:115]
	v_max_f32_e32 v110, 0, v110
	v_max_f32_e32 v111, 0, v111
	v_max_f32_e32 v106, 0, v106
	v_max_f32_e32 v107, 0, v107
	v_max_f32_e32 v109, 0, v109
	v_lshl_add_u64 v[114:115], s[28:29], 0, v[114:115]
	v_pk_mul_f32 v[110:111], v[110:111], v[110:111]
	v_pk_mul_f32 v[112:113], v[106:107], v[106:107]
	v_pk_mul_f32 v[118:119], v[108:109], v[108:109]
	v_max_f32_e32 v98, v98, v98
	v_max_f32_e32 v99, v99, v99
	v_cvt_pk_bf16_f32 v106, v110, v111
	v_cvt_pk_bf16_f32 v107, v112, v113
	v_cvt_pk_bf16_f32 v108, v116, v117
	v_cvt_pk_bf16_f32 v109, v118, v119
	v_lshl_add_u64 v[110:111], v[114:115], 0, v[96:97]
	v_max_f32_e32 v98, 0, v98
	v_max_f32_e32 v99, 0, v99
	global_store_dwordx4 v[110:111], v[106:109], off sc1
	v_max_f32_e32 v102, v102, v102
	v_max_f32_e32 v103, v103, v103
	v_pk_mul_f32 v[106:107], v[98:99], v[98:99]
	v_max_f32_e32 v99, v100, v100
	v_max_f32_e32 v98, v104, v104
	v_max_f32_e32 v100, 0, v99
	v_max_f32_e32 v99, v105, v105
	v_max_f32_e32 v101, v101, v101
	v_max_f32_e32 v102, 0, v102
	v_max_f32_e32 v103, 0, v103
	v_max_f32_e32 v98, 0, v98
	v_max_f32_e32 v99, 0, v99
	v_max_f32_e32 v101, 0, v101
	v_pk_mul_f32 v[102:103], v[102:103], v[102:103]
	v_pk_mul_f32 v[104:105], v[98:99], v[98:99]
	v_pk_mul_f32 v[108:109], v[100:101], v[100:101]
	v_max_f32_e32 v88, v88, v88
	v_max_f32_e32 v89, v89, v89
	v_cvt_pk_bf16_f32 v98, v102, v103
	v_cvt_pk_bf16_f32 v99, v104, v105
	v_cvt_pk_bf16_f32 v100, v106, v107
	v_cvt_pk_bf16_f32 v101, v108, v109
	v_max_f32_e32 v88, 0, v88
	v_max_f32_e32 v89, 0, v89
	global_store_dwordx4 v[110:111], v[98:101], off offset:256 sc1
	v_max_f32_e32 v92, v92, v92
	v_max_f32_e32 v93, v93, v93
	v_or_b32_e32 v98, 32, v142
	v_pk_mul_f32 v[100:101], v[88:89], v[88:89]
	v_max_f32_e32 v89, v90, v90
	v_ashrrev_i32_e32 v99, 31, v98
	v_max_f32_e32 v88, v94, v94
	v_max_f32_e32 v90, 0, v89
	v_max_f32_e32 v89, v95, v95
	v_max_f32_e32 v91, v91, v91
	v_lshlrev_b64 v[98:99], 13, v[98:99]
	v_max_f32_e32 v92, 0, v92
	v_max_f32_e32 v93, 0, v93
	v_max_f32_e32 v88, 0, v88
	v_max_f32_e32 v89, 0, v89
	v_max_f32_e32 v91, 0, v91
	v_lshl_add_u64 v[98:99], s[28:29], 0, v[98:99]
	v_pk_mul_f32 v[92:93], v[92:93], v[92:93]
	v_pk_mul_f32 v[94:95], v[88:89], v[88:89]
	v_pk_mul_f32 v[102:103], v[90:91], v[90:91]
	v_max_f32_e32 v80, v80, v80
	v_max_f32_e32 v81, v81, v81
	v_cvt_pk_bf16_f32 v88, v92, v93
	v_cvt_pk_bf16_f32 v89, v94, v95
	v_cvt_pk_bf16_f32 v90, v100, v101
	v_cvt_pk_bf16_f32 v91, v102, v103
	v_lshl_add_u64 v[92:93], v[98:99], 0, v[96:97]
	v_max_f32_e32 v80, 0, v80
	v_max_f32_e32 v81, 0, v81
	global_store_dwordx4 v[92:93], v[88:91], off sc1
	v_max_f32_e32 v84, v84, v84
	v_max_f32_e32 v85, v85, v85
	v_pk_mul_f32 v[88:89], v[80:81], v[80:81]
	v_max_f32_e32 v81, v82, v82
	v_max_f32_e32 v80, v86, v86
	v_max_f32_e32 v82, 0, v81
	v_max_f32_e32 v81, v87, v87
	v_max_f32_e32 v83, v83, v83
	v_max_f32_e32 v84, 0, v84
	v_max_f32_e32 v85, 0, v85
	v_max_f32_e32 v80, 0, v80
	v_max_f32_e32 v81, 0, v81
	v_max_f32_e32 v83, 0, v83
	v_pk_mul_f32 v[84:85], v[84:85], v[84:85]
; DI u32x4 pk8(const f32x4& a, const f32x4& b) { u32x4 w; w.x = pk2(a[0], a[1]); w.y = pk2(a[2], a[3]); w.z = pk2(b[0], b[1]); w.w = pk2(b[2], b[3]); return w; }
; #define FOR_AI_M _Pragma("unroll") for (int ai = 0; ai < 2; ++ai) _Pragma("unroll") for (int m = 0; m < 4; ++m)
;     DI void operator()(Acc& acc, const Unit& u, int wr, int wc, int fr, int fq) const {
;     ...
;         FOR_AI_M { const int r = u.pm * 256 + EPI_ROWS(ai, m);
; #pragma unroll
;             for (int bj = 0; bj < 2; ++bj) { f32x4 a = acc[ai][bj][m][0], b = acc[ai][bj][m][1];
; #pragma unroll
;                 for (int e = 0; e < 4; ++e) { const float x = fmaxf(a[e], 0.f), y = fmaxf(b[e], 0.f); a[e] = x * x; b[e] = y * y; }
;                 *(u32x4*)(U + (size_t)r * DFF + u.pn * 256 + EPI_COL8(bj)) = pk8(a, b); } }
	v_pk_mul_f32 v[86:87], v[80:81], v[80:81]
	v_pk_mul_f32 v[90:91], v[82:83], v[82:83]
	v_max_f32_e32 v72, v72, v72
	v_max_f32_e32 v73, v73, v73
	v_cvt_pk_bf16_f32 v80, v84, v85
	v_cvt_pk_bf16_f32 v81, v86, v87
	v_cvt_pk_bf16_f32 v82, v88, v89
	v_cvt_pk_bf16_f32 v83, v90, v91
	v_max_f32_e32 v72, 0, v72
	v_max_f32_e32 v73, 0, v73
	global_store_dwordx4 v[92:93], v[80:83], off offset:256 sc1
	v_max_f32_e32 v76, v76, v76
	v_max_f32_e32 v77, v77, v77
	v_or_b32_e32 v80, 48, v142
	v_pk_mul_f32 v[82:83], v[72:73], v[72:73]
	v_max_f32_e32 v73, v74, v74
	v_ashrrev_i32_e32 v81, 31, v80
	v_max_f32_e32 v72, v78, v78
	v_max_f32_e32 v74, 0, v73
	v_max_f32_e32 v73, v79, v79
	v_max_f32_e32 v75, v75, v75
	v_lshlrev_b64 v[80:81], 13, v[80:81]
	v_max_f32_e32 v76, 0, v76
	v_max_f32_e32 v77, 0, v77
	v_max_f32_e32 v72, 0, v72
	v_max_f32_e32 v73, 0, v73
	v_max_f32_e32 v75, 0, v75
	v_lshl_add_u64 v[80:81], s[28:29], 0, v[80:81]
	v_pk_mul_f32 v[76:77], v[76:77], v[76:77]
	v_pk_mul_f32 v[78:79], v[72:73], v[72:73]
	v_pk_mul_f32 v[84:85], v[74:75], v[74:75]
	v_max_f32_e32 v64, v64, v64
	v_max_f32_e32 v65, v65, v65
	v_cvt_pk_bf16_f32 v72, v76, v77
	v_cvt_pk_bf16_f32 v73, v78, v79
	v_cvt_pk_bf16_f32 v74, v82, v83
	v_cvt_pk_bf16_f32 v75, v84, v85
	v_lshl_add_u64 v[76:77], v[80:81], 0, v[96:97]
	v_max_f32_e32 v64, 0, v64
	v_max_f32_e32 v65, 0, v65
	global_store_dwordx4 v[76:77], v[72:75], off sc1
	v_max_f32_e32 v68, v68, v68
	v_max_f32_e32 v69, v69, v69
	v_pk_mul_f32 v[72:73], v[64:65], v[64:65]
	v_max_f32_e32 v65, v66, v66
	v_max_f32_e32 v64, v70, v70
	v_max_f32_e32 v66, 0, v65
	v_max_f32_e32 v65, v71, v71
	v_max_f32_e32 v67, v67, v67
	v_max_f32_e32 v68, 0, v68
	v_max_f32_e32 v69, 0, v69
	v_max_f32_e32 v64, 0, v64
	v_max_f32_e32 v65, 0, v65
	v_max_f32_e32 v67, 0, v67
	v_pk_mul_f32 v[68:69], v[68:69], v[68:69]
	v_pk_mul_f32 v[70:71], v[64:65], v[64:65]
	v_pk_mul_f32 v[74:75], v[66:67], v[66:67]
	v_max_f32_e32 v56, v56, v56
	v_max_f32_e32 v57, v57, v57
	v_cvt_pk_bf16_f32 v64, v68, v69
	v_cvt_pk_bf16_f32 v65, v70, v71
	v_cvt_pk_bf16_f32 v66, v72, v73
	v_cvt_pk_bf16_f32 v67, v74, v75
	v_max_f32_e32 v56, 0, v56
	v_max_f32_e32 v57, 0, v57
	global_store_dwordx4 v[76:77], v[64:67], off offset:256 sc1
	v_max_f32_e32 v60, v60, v60
	v_max_f32_e32 v61, v61, v61
	v_add_u32_e32 v64, 0x80, v142
	v_pk_mul_f32 v[66:67], v[56:57], v[56:57]
	v_max_f32_e32 v57, v58, v58
	v_ashrrev_i32_e32 v65, 31, v64
	v_max_f32_e32 v56, v62, v62
	v_max_f32_e32 v58, 0, v57
	v_max_f32_e32 v57, v63, v63
	v_max_f32_e32 v59, v59, v59
	v_lshlrev_b64 v[64:65], 13, v[64:65]
	v_max_f32_e32 v60, 0, v60
	v_max_f32_e32 v61, 0, v61
	v_max_f32_e32 v56, 0, v56
	v_max_f32_e32 v57, 0, v57
	v_max_f32_e32 v59, 0, v59
	v_lshl_add_u64 v[64:65], s[28:29], 0, v[64:65]
	v_pk_mul_f32 v[60:61], v[60:61], v[60:61]
	v_pk_mul_f32 v[62:63], v[56:57], v[56:57]
	v_pk_mul_f32 v[68:69], v[58:59], v[58:59]
	v_max_f32_e32 v48, v48, v48
	v_max_f32_e32 v49, v49, v49
	v_cvt_pk_bf16_f32 v56, v60, v61
	v_cvt_pk_bf16_f32 v57, v62, v63
	v_cvt_pk_bf16_f32 v58, v66, v67
	v_cvt_pk_bf16_f32 v59, v68, v69
	v_lshl_add_u64 v[60:61], v[64:65], 0, v[96:97]
	v_max_f32_e32 v48, 0, v48
	v_max_f32_e32 v49, 0, v49
	global_store_dwordx4 v[60:61], v[56:59], off sc1
	v_max_f32_e32 v52, v52, v52
	v_max_f32_e32 v53, v53, v53
	v_pk_mul_f32 v[56:57], v[48:49], v[48:49]
	v_max_f32_e32 v49, v50, v50
	v_max_f32_e32 v48, v54, v54
	v_max_f32_e32 v50, 0, v49
	v_max_f32_e32 v49, v55, v55
	v_max_f32_e32 v51, v51, v51
	v_max_f32_e32 v52, 0, v52
	v_max_f32_e32 v53, 0, v53
	v_max_f32_e32 v48, 0, v48
	v_max_f32_e32 v49, 0, v49
	v_max_f32_e32 v51, 0, v51
	v_pk_mul_f32 v[52:53], v[52:53], v[52:53]
	v_pk_mul_f32 v[54:55], v[48:49], v[48:49]
	v_pk_mul_f32 v[58:59], v[50:51], v[50:51]
	v_max_f32_e32 v40, v40, v40
	v_max_f32_e32 v41, v41, v41
	v_cvt_pk_bf16_f32 v48, v52, v53
	v_cvt_pk_bf16_f32 v49, v54, v55
	v_cvt_pk_bf16_f32 v50, v56, v57
	v_cvt_pk_bf16_f32 v51, v58, v59
	v_max_f32_e32 v40, 0, v40
	v_max_f32_e32 v41, 0, v41
	global_store_dwordx4 v[60:61], v[48:51], off offset:256 sc1
	v_max_f32_e32 v44, v44, v44
	v_max_f32_e32 v45, v45, v45
	v_add_u32_e32 v48, 0x90, v142
	v_pk_mul_f32 v[50:51], v[40:41], v[40:41]
	v_max_f32_e32 v41, v42, v42
	v_ashrrev_i32_e32 v49, 31, v48
	v_max_f32_e32 v40, v46, v46
	v_max_f32_e32 v42, 0, v41
	v_max_f32_e32 v41, v47, v47
	v_max_f32_e32 v43, v43, v43
	v_lshlrev_b64 v[48:49], 13, v[48:49]
	v_max_f32_e32 v44, 0, v44
	v_max_f32_e32 v45, 0, v45
	v_max_f32_e32 v40, 0, v40
	v_max_f32_e32 v41, 0, v41
	v_max_f32_e32 v43, 0, v43
	v_lshl_add_u64 v[48:49], s[28:29], 0, v[48:49]
	v_pk_mul_f32 v[44:45], v[44:45], v[44:45]
	v_pk_mul_f32 v[46:47], v[40:41], v[40:41]
	v_pk_mul_f32 v[52:53], v[42:43], v[42:43]
	v_max_f32_e32 v32, v32, v32
; DI u32x4 pk8(const f32x4& a, const f32x4& b) { u32x4 w; w.x = pk2(a[0], a[1]); w.y = pk2(a[2], a[3]); w.z = pk2(b[0], b[1]); w.w = pk2(b[2], b[3]); return w; }
; #define PG8_BAR __builtin_amdgcn_s_barrier()
; #define FOR_AI_M _Pragma("unroll") for (int ai = 0; ai < 2; ++ai) _Pragma("unroll") for (int m = 0; m < 4; ++m)
;     ...
;         if (!has_next) break;
;         if (cur.last) {
; #pragma unroll
;             for (int a = 0; a < 2; ++a)
; #pragma unroll
;                 for (int b = 0; b < 2; ++b)
; #pragma unroll
;                     for (int m = 0; m < 4; ++m)
; #pragma unroll
;                         for (int n = 0; n < 2; ++n) acc[a][b][m][n] = (f32x4){0.f, 0.f, 0.f, 0.f};
;         }
;         cur = nxt; cA = nA; cB = nB; ++ui;
;         if (wr == 1) PG8_BAR;
;     DI void operator()(Acc& acc, const Unit& u, int wr, int wc, int fr, int fq) const {
;     ...
;         FOR_AI_M { const int r = u.pm * 256 + EPI_ROWS(ai, m);
; #pragma unroll
;             for (int bj = 0; bj < 2; ++bj) { f32x4 a = acc[ai][bj][m][0], b = acc[ai][bj][m][1];
; #pragma unroll
;                 for (int e = 0; e < 4; ++e) { const float x = fmaxf(a[e], 0.f), y = fmaxf(b[e], 0.f); a[e] = x * x; b[e] = y * y; }
;                 *(u32x4*)(U + (size_t)r * DFF + u.pn * 256 + EPI_COL8(bj)) = pk8(a, b); } }
	v_max_f32_e32 v33, v33, v33
	v_cvt_pk_bf16_f32 v40, v44, v45
	v_cvt_pk_bf16_f32 v41, v46, v47
	v_cvt_pk_bf16_f32 v42, v50, v51
	v_cvt_pk_bf16_f32 v43, v52, v53
	v_lshl_add_u64 v[44:45], v[48:49], 0, v[96:97]
	v_max_f32_e32 v32, 0, v32
	v_max_f32_e32 v33, 0, v33
	global_store_dwordx4 v[44:45], v[40:43], off sc1
	v_max_f32_e32 v36, v36, v36
	v_max_f32_e32 v37, v37, v37
	v_pk_mul_f32 v[40:41], v[32:33], v[32:33]
	v_max_f32_e32 v33, v34, v34
	v_max_f32_e32 v32, v38, v38
	v_max_f32_e32 v34, 0, v33
	v_max_f32_e32 v33, v39, v39
	v_max_f32_e32 v35, v35, v35
	v_max_f32_e32 v36, 0, v36
	v_max_f32_e32 v37, 0, v37
	v_max_f32_e32 v32, 0, v32
	v_max_f32_e32 v33, 0, v33
	v_max_f32_e32 v35, 0, v35
	v_pk_mul_f32 v[36:37], v[36:37], v[36:37]
	v_pk_mul_f32 v[38:39], v[32:33], v[32:33]
	v_pk_mul_f32 v[42:43], v[34:35], v[34:35]
	v_max_f32_e32 v24, v24, v24
	v_max_f32_e32 v25, v25, v25
	v_cvt_pk_bf16_f32 v32, v36, v37
	v_cvt_pk_bf16_f32 v33, v38, v39
	v_cvt_pk_bf16_f32 v34, v40, v41
	v_cvt_pk_bf16_f32 v35, v42, v43
	v_max_f32_e32 v24, 0, v24
	v_max_f32_e32 v25, 0, v25
	global_store_dwordx4 v[44:45], v[32:35], off offset:256 sc1
	v_max_f32_e32 v28, v28, v28
	v_max_f32_e32 v29, v29, v29
	v_add_u32_e32 v32, 0xa0, v142
	v_pk_mul_f32 v[34:35], v[24:25], v[24:25]
	v_max_f32_e32 v25, v26, v26
	v_ashrrev_i32_e32 v33, 31, v32
	v_max_f32_e32 v24, v30, v30
	v_max_f32_e32 v26, 0, v25
	v_max_f32_e32 v25, v31, v31
	v_max_f32_e32 v27, v27, v27
	v_lshlrev_b64 v[32:33], 13, v[32:33]
	v_max_f32_e32 v28, 0, v28
	v_max_f32_e32 v29, 0, v29
	v_max_f32_e32 v24, 0, v24
	v_max_f32_e32 v25, 0, v25
	v_max_f32_e32 v27, 0, v27
	v_lshl_add_u64 v[32:33], s[28:29], 0, v[32:33]
	v_pk_mul_f32 v[28:29], v[28:29], v[28:29]
	v_pk_mul_f32 v[30:31], v[24:25], v[24:25]
	v_pk_mul_f32 v[36:37], v[26:27], v[26:27]
	v_max_f32_e32 v16, v16, v16
	v_max_f32_e32 v17, v17, v17
	v_cvt_pk_bf16_f32 v24, v28, v29
	v_cvt_pk_bf16_f32 v25, v30, v31
	v_cvt_pk_bf16_f32 v26, v34, v35
	v_cvt_pk_bf16_f32 v27, v36, v37
	v_lshl_add_u64 v[28:29], v[32:33], 0, v[96:97]
	v_max_f32_e32 v16, 0, v16
	v_max_f32_e32 v17, 0, v17
	global_store_dwordx4 v[28:29], v[24:27], off sc1
	v_max_f32_e32 v20, v20, v20
	v_max_f32_e32 v21, v21, v21
	v_pk_mul_f32 v[24:25], v[16:17], v[16:17]
	v_max_f32_e32 v17, v18, v18
	v_max_f32_e32 v16, v22, v22
	v_max_f32_e32 v18, 0, v17
	v_max_f32_e32 v17, v23, v23
	v_max_f32_e32 v19, v19, v19
	v_max_f32_e32 v20, 0, v20
	v_max_f32_e32 v21, 0, v21
	v_max_f32_e32 v16, 0, v16
	v_max_f32_e32 v17, 0, v17
	v_max_f32_e32 v19, 0, v19
	v_pk_mul_f32 v[20:21], v[20:21], v[20:21]
	v_pk_mul_f32 v[22:23], v[16:17], v[16:17]
	v_pk_mul_f32 v[26:27], v[18:19], v[18:19]
	v_max_f32_e32 v8, v8, v8
	v_max_f32_e32 v9, v9, v9
	v_cvt_pk_bf16_f32 v16, v20, v21
	v_cvt_pk_bf16_f32 v17, v22, v23
	v_cvt_pk_bf16_f32 v18, v24, v25
	v_cvt_pk_bf16_f32 v19, v26, v27
	v_max_f32_e32 v8, 0, v8
	v_max_f32_e32 v9, 0, v9
	global_store_dwordx4 v[28:29], v[16:19], off offset:256 sc1
	v_max_f32_e32 v12, v12, v12
	v_max_f32_e32 v13, v13, v13
	v_add_u32_e32 v16, 0xb0, v142
	v_pk_mul_f32 v[18:19], v[8:9], v[8:9]
	v_max_f32_e32 v9, v10, v10
	v_ashrrev_i32_e32 v17, 31, v16
	v_max_f32_e32 v8, v14, v14
	v_max_f32_e32 v10, 0, v9
	v_max_f32_e32 v9, v15, v15
	v_max_f32_e32 v11, v11, v11
	v_lshlrev_b64 v[16:17], 13, v[16:17]
	v_max_f32_e32 v12, 0, v12
	v_max_f32_e32 v13, 0, v13
	v_max_f32_e32 v8, 0, v8
	v_max_f32_e32 v9, 0, v9
	v_max_f32_e32 v11, 0, v11
	v_lshl_add_u64 v[16:17], s[28:29], 0, v[16:17]
	v_pk_mul_f32 v[12:13], v[12:13], v[12:13]
	v_pk_mul_f32 v[14:15], v[8:9], v[8:9]
	v_pk_mul_f32 v[20:21], v[10:11], v[10:11]
	v_max_f32_e32 v0, v0, v0
	v_max_f32_e32 v1, v1, v1
	v_cvt_pk_bf16_f32 v8, v12, v13
	v_cvt_pk_bf16_f32 v9, v14, v15
	v_cvt_pk_bf16_f32 v10, v18, v19
	v_cvt_pk_bf16_f32 v11, v20, v21
	v_lshl_add_u64 v[12:13], v[16:17], 0, v[96:97]
	v_max_f32_e32 v0, 0, v0
	v_max_f32_e32 v1, 0, v1
	global_store_dwordx4 v[12:13], v[8:11], off sc1
	v_max_f32_e32 v4, v4, v4
	v_max_f32_e32 v5, v5, v5
	v_pk_mul_f32 v[8:9], v[0:1], v[0:1]
	v_max_f32_e32 v1, v2, v2
	v_max_f32_e32 v0, v6, v6
	v_max_f32_e32 v2, 0, v1
	v_max_f32_e32 v1, v7, v7
	v_max_f32_e32 v3, v3, v3
	v_max_f32_e32 v4, 0, v4
	v_max_f32_e32 v5, 0, v5
	v_max_f32_e32 v0, 0, v0
	v_max_f32_e32 v1, 0, v1
	v_max_f32_e32 v3, 0, v3
	v_pk_mul_f32 v[4:5], v[4:5], v[4:5]
	v_pk_mul_f32 v[6:7], v[0:1], v[0:1]
	v_pk_mul_f32 v[10:11], v[2:3], v[2:3]
	v_cvt_pk_bf16_f32 v0, v4, v5
	v_cvt_pk_bf16_f32 v1, v6, v7
	v_cvt_pk_bf16_f32 v2, v8, v9
	v_cvt_pk_bf16_f32 v3, v10, v11
	s_andn2_b64 vcc, exec, s[2:3]
	s_mov_b64 s[2:3], -1
	global_store_dwordx4 v[12:13], v[0:3], off offset:256 sc1
	s_cbranch_vccnz .LBB0_93
	s_andn2_b64 vcc, exec, s[4:5]
	s_cbranch_vccnz .LBB0_92
	s_barrier
	s_branch .LBB0_92

; DI u32x4 pk8(const f32x4& a, const f32x4& b) { u32x4 w; w.x = pk2(a[0], a[1]); w.y = pk2(a[2], a[3]); w.z = pk2(b[0], b[1]); w.w = pk2(b[2], b[3]); return w; }
; #define ROW_FENCE asm volatile("" ::: "memory")
;     DI void operator()(Acc& acc, const Unit& u, int wr, int wc, int fr, int fq) const {
;         const bf16_t* gate = (const bf16_t*)(F.ws + WS_GATE); bf16_t* Y = (bf16_t*)(F.ws + WS_HB);
;         const int row0 = u.pm * 256, col0 = u.pn * 256;
;         const int s1 = u.seg < 2 ? u.seg + 1 : u.seg;
; #pragma unroll
;         for (int aim = 0; aim < 4; ++aim) { const int ai = aim >> 1, mb = (aim & 1) * 2;
;             u32x4 ga[4][2], gb[4][2];
; #pragma unroll
;             for (int m = mb; m < mb + 2; ++m)
; #pragma unroll
;                 for (int bj = 0; bj < 2; ++bj) { const size_t o = (size_t)(row0 + EPI_ROWS(ai, m)) * 3072 + col0 + EPI_COL8(bj);
;                     ga[m][bj] = *(const u32x4*)(gate + o + u.seg * 1024); if (u.seg < 2) gb[m][bj] = *(const u32x4*)(gate + o + s1 * 1024); }
; #pragma unroll
;             for (int m = mb; m < mb + 2; ++m) { const int r = row0 + EPI_ROWS(ai, m);
; #pragma unroll
;                 for (int bj = 0; bj < 2; ++bj) {
;                     float g0[8]; unpk8(ga[m][bj], g0);
;                     if (u.seg < 2) { float g1[8]; unpk8(gb[m][bj], g1);
; #pragma unroll
;                         for (int e = 0; e < 8; ++e) g0[e] = g0[e] * __builtin_amdgcn_rcpf(fmaxf(g1[e], 1e-20f)); }
; #pragma unroll
;                     for (int e = 0; e < 4; ++e) { acc[ai][bj][m][0][e] *= g0[e]; acc[ai][bj][m][1][e] *= g0[4 + e]; }
;                     if (u.seg == 2) *(u32x4*)(Y + (size_t)r * 1024 + col0 + EPI_COL8(bj)) = pk8(acc[ai][bj][m][0], acc[ai][bj][m][1]);
;                 }
;             }
;             ROW_FENCE;
.Lg3e_last:
	s_add_u32 s6, s50, 0x0
	s_addc_u32 s7, s51, 0
	global_load_dwordx4 v[130:133], v214, s[6:7]
	global_load_dwordx4 v[134:137], v214, s[6:7] offset:256
	s_add_u32 s6, s50, 0x18000
	s_addc_u32 s7, s51, 0
	global_load_dwordx4 v[138:141], v214, s[6:7]
	global_load_dwordx4 v[142:145], v214, s[6:7] offset:256
	s_add_u32 s6, s50, 0x30000
	s_addc_u32 s7, s51, 0
	global_load_dwordx4 v[146:149], v214, s[6:7]
	global_load_dwordx4 v[150:153], v214, s[6:7] offset:256
	s_add_u32 s6, s50, 0x48000
	s_addc_u32 s7, s51, 0
	global_load_dwordx4 v[154:157], v214, s[6:7]
	global_load_dwordx4 v[158:161], v214, s[6:7] offset:256
	s_add_u32 s6, s50, 0xc0000
	s_addc_u32 s7, s51, 0
	global_load_dwordx4 v[162:165], v214, s[6:7]
	global_load_dwordx4 v[166:169], v214, s[6:7] offset:256
	s_add_u32 s6, s50, 0xd8000
	s_addc_u32 s7, s51, 0
	global_load_dwordx4 v[170:173], v214, s[6:7]
	global_load_dwordx4 v[174:177], v214, s[6:7] offset:256
	s_add_u32 s6, s50, 0xf0000
	s_addc_u32 s7, s51, 0
	global_load_dwordx4 v[200:203], v214, s[6:7]
	global_load_dwordx4 v[204:207], v214, s[6:7] offset:256
	s_add_u32 s6, s50, 0x108000
	s_addc_u32 s7, s51, 0
	global_load_dwordx4 v[208:211], v214, s[6:7]
	global_load_dwordx4 v[230:233], v214, s[6:7] offset:256
	s_waitcnt vmcnt(14)
	s_add_u32 s8, s42, 0x0
	s_addc_u32 s9, s43, 0
	v_lshlrev_b32_e32 v234, 16, v130
	v_and_b32_e32 v235, 0xffff0000, v130
	v_lshlrev_b32_e32 v236, 16, v131
	v_and_b32_e32 v237, 0xffff0000, v131
	v_lshlrev_b32_e32 v238, 16, v132
	v_and_b32_e32 v239, 0xffff0000, v132
	v_lshlrev_b32_e32 v240, 16, v133
	v_and_b32_e32 v241, 0xffff0000, v133
	v_pk_mul_f32 v[126:127], v[126:127], v[234:235]
	v_pk_mul_f32 v[122:123], v[122:123], v[238:239]
	v_pk_mul_f32 v[128:129], v[128:129], v[236:237]
	v_pk_mul_f32 v[124:125], v[124:125], v[240:241]
	v_cvt_pk_bf16_f32 v130, v126, v127
	v_cvt_pk_bf16_f32 v131, v128, v129
	v_cvt_pk_bf16_f32 v132, v122, v123
	v_cvt_pk_bf16_f32 v133, v124, v125
	global_store_dwordx4 v215, v[130:133], s[8:9] sc1
	v_lshlrev_b32_e32 v234, 16, v134
	v_and_b32_e32 v235, 0xffff0000, v134
	v_lshlrev_b32_e32 v236, 16, v135
	v_and_b32_e32 v237, 0xffff0000, v135
	v_lshlrev_b32_e32 v238, 16, v136
	v_and_b32_e32 v239, 0xffff0000, v136
	v_lshlrev_b32_e32 v240, 16, v137
	v_and_b32_e32 v241, 0xffff0000, v137
	v_pk_mul_f32 v[92:93], v[92:93], v[234:235]
	v_pk_mul_f32 v[88:89], v[88:89], v[238:239]
	v_pk_mul_f32 v[94:95], v[94:95], v[236:237]
	v_pk_mul_f32 v[90:91], v[90:91], v[240:241]
	v_cvt_pk_bf16_f32 v134, v92, v93
	v_cvt_pk_bf16_f32 v135, v94, v95
	v_cvt_pk_bf16_f32 v136, v88, v89
	v_cvt_pk_bf16_f32 v137, v90, v91
	global_store_dwordx4 v215, v[134:137], s[8:9] offset:256 sc1
	s_waitcnt vmcnt(14)
	s_add_u32 s8, s42, 0x8000
	s_addc_u32 s9, s43, 0
	v_lshlrev_b32_e32 v234, 16, v138
	v_and_b32_e32 v235, 0xffff0000, v138
	v_lshlrev_b32_e32 v236, 16, v139
	v_and_b32_e32 v237, 0xffff0000, v139
	v_lshlrev_b32_e32 v238, 16, v140
	v_and_b32_e32 v239, 0xffff0000, v140
	v_lshlrev_b32_e32 v240, 16, v141
	v_and_b32_e32 v241, 0xffff0000, v141
	v_pk_mul_f32 v[118:119], v[118:119], v[234:235]
	v_pk_mul_f32 v[114:115], v[114:115], v[238:239]
	v_pk_mul_f32 v[120:121], v[120:121], v[236:237]
	v_pk_mul_f32 v[116:117], v[116:117], v[240:241]
	v_cvt_pk_bf16_f32 v138, v118, v119
	v_cvt_pk_bf16_f32 v139, v120, v121
	v_cvt_pk_bf16_f32 v140, v114, v115
	v_cvt_pk_bf16_f32 v141, v116, v117
	global_store_dwordx4 v215, v[138:141], s[8:9] sc1
	v_lshlrev_b32_e32 v234, 16, v142
	v_and_b32_e32 v235, 0xffff0000, v142
	v_lshlrev_b32_e32 v236, 16, v143
	v_and_b32_e32 v237, 0xffff0000, v143
	v_lshlrev_b32_e32 v238, 16, v144
	v_and_b32_e32 v239, 0xffff0000, v144
	v_lshlrev_b32_e32 v240, 16, v145
	v_and_b32_e32 v241, 0xffff0000, v145
	v_pk_mul_f32 v[84:85], v[84:85], v[234:235]
	v_pk_mul_f32 v[80:81], v[80:81], v[238:239]
	v_pk_mul_f32 v[86:87], v[86:87], v[236:237]
	v_pk_mul_f32 v[82:83], v[82:83], v[240:241]
	v_cvt_pk_bf16_f32 v142, v84, v85
	v_cvt_pk_bf16_f32 v143, v86, v87
	v_cvt_pk_bf16_f32 v144, v80, v81
	v_cvt_pk_bf16_f32 v145, v82, v83
	global_store_dwordx4 v215, v[142:145], s[8:9] offset:256 sc1
	s_waitcnt vmcnt(14)
	s_add_u32 s8, s42, 0x10000
	s_addc_u32 s9, s43, 0
	v_lshlrev_b32_e32 v234, 16, v146
	v_and_b32_e32 v235, 0xffff0000, v146
	v_lshlrev_b32_e32 v236, 16, v147
	v_and_b32_e32 v237, 0xffff0000, v147
	v_lshlrev_b32_e32 v238, 16, v148
	v_and_b32_e32 v239, 0xffff0000, v148
	v_lshlrev_b32_e32 v240, 16, v149
	v_and_b32_e32 v241, 0xffff0000, v149
	v_pk_mul_f32 v[110:111], v[110:111], v[234:235]
	v_pk_mul_f32 v[106:107], v[106:107], v[238:239]
	v_pk_mul_f32 v[112:113], v[112:113], v[236:237]
	v_pk_mul_f32 v[108:109], v[108:109], v[240:241]
	v_cvt_pk_bf16_f32 v146, v110, v111
	v_cvt_pk_bf16_f32 v147, v112, v113
	v_cvt_pk_bf16_f32 v148, v106, v107
	v_cvt_pk_bf16_f32 v149, v108, v109
	global_store_dwordx4 v215, v[146:149], s[8:9] sc1
	v_lshlrev_b32_e32 v234, 16, v150
	v_and_b32_e32 v235, 0xffff0000, v150
	v_lshlrev_b32_e32 v236, 16, v151
	v_and_b32_e32 v237, 0xffff0000, v151
	v_lshlrev_b32_e32 v238, 16, v152
	v_and_b32_e32 v239, 0xffff0000, v152
	v_lshlrev_b32_e32 v240, 16, v153
	v_and_b32_e32 v241, 0xffff0000, v153
	v_pk_mul_f32 v[76:77], v[76:77], v[234:235]
	v_pk_mul_f32 v[72:73], v[72:73], v[238:239]
	v_pk_mul_f32 v[78:79], v[78:79], v[236:237]
	v_pk_mul_f32 v[74:75], v[74:75], v[240:241]
	v_cvt_pk_bf16_f32 v150, v76, v77
	v_cvt_pk_bf16_f32 v151, v78, v79
	v_cvt_pk_bf16_f32 v152, v72, v73
	v_cvt_pk_bf16_f32 v153, v74, v75
	global_store_dwordx4 v215, v[150:153], s[8:9] offset:256 sc1
	s_waitcnt vmcnt(14)
; DI u32x4 pk8(const f32x4& a, const f32x4& b) { u32x4 w; w.x = pk2(a[0], a[1]); w.y = pk2(a[2], a[3]); w.z = pk2(b[0], b[1]); w.w = pk2(b[2], b[3]); return w; }
; #define ROW_FENCE asm volatile("" ::: "memory")
;     DI void operator()(Acc& acc, const Unit& u, int wr, int wc, int fr, int fq) const {
;     ...
;                 for (int bj = 0; bj < 2; ++bj) { const size_t o = (size_t)(row0 + EPI_ROWS(ai, m)) * 3072 + col0 + EPI_COL8(bj);
;                     ga[m][bj] = *(const u32x4*)(gate + o + u.seg * 1024); if (u.seg < 2) gb[m][bj] = *(const u32x4*)(gate + o + s1 * 1024); }
; #pragma unroll
;             for (int m = mb; m < mb + 2; ++m) { const int r = row0 + EPI_ROWS(ai, m);
; #pragma unroll
;                 for (int bj = 0; bj < 2; ++bj) {
;                     float g0[8]; unpk8(ga[m][bj], g0);
;                     if (u.seg < 2) { float g1[8]; unpk8(gb[m][bj], g1);
; #pragma unroll
;                         for (int e = 0; e < 8; ++e) g0[e] = g0[e] * __builtin_amdgcn_rcpf(fmaxf(g1[e], 1e-20f)); }
; #pragma unroll
;                     for (int e = 0; e < 4; ++e) { acc[ai][bj][m][0][e] *= g0[e]; acc[ai][bj][m][1][e] *= g0[4 + e]; }
;                     if (u.seg == 2) *(u32x4*)(Y + (size_t)r * 1024 + col0 + EPI_COL8(bj)) = pk8(acc[ai][bj][m][0], acc[ai][bj][m][1]);
;                 }
;             }
;             ROW_FENCE;
	s_add_u32 s8, s42, 0x18000
	s_addc_u32 s9, s43, 0
	v_lshlrev_b32_e32 v234, 16, v154
	v_and_b32_e32 v235, 0xffff0000, v154
	v_lshlrev_b32_e32 v236, 16, v155
	v_and_b32_e32 v237, 0xffff0000, v155
	v_lshlrev_b32_e32 v238, 16, v156
	v_and_b32_e32 v239, 0xffff0000, v156
	v_lshlrev_b32_e32 v240, 16, v157
	v_and_b32_e32 v241, 0xffff0000, v157
	v_pk_mul_f32 v[102:103], v[102:103], v[234:235]
	v_pk_mul_f32 v[98:99], v[98:99], v[238:239]
	v_pk_mul_f32 v[104:105], v[104:105], v[236:237]
	v_pk_mul_f32 v[100:101], v[100:101], v[240:241]
	v_cvt_pk_bf16_f32 v154, v102, v103
	v_cvt_pk_bf16_f32 v155, v104, v105
	v_cvt_pk_bf16_f32 v156, v98, v99
	v_cvt_pk_bf16_f32 v157, v100, v101
	global_store_dwordx4 v215, v[154:157], s[8:9] sc1
	v_lshlrev_b32_e32 v234, 16, v158
	v_and_b32_e32 v235, 0xffff0000, v158
	v_lshlrev_b32_e32 v236, 16, v159
	v_and_b32_e32 v237, 0xffff0000, v159
	v_lshlrev_b32_e32 v238, 16, v160
	v_and_b32_e32 v239, 0xffff0000, v160
	v_lshlrev_b32_e32 v240, 16, v161
	v_and_b32_e32 v241, 0xffff0000, v161
	v_pk_mul_f32 v[68:69], v[68:69], v[234:235]
	v_pk_mul_f32 v[64:65], v[64:65], v[238:239]
	v_pk_mul_f32 v[70:71], v[70:71], v[236:237]
	v_pk_mul_f32 v[66:67], v[66:67], v[240:241]
	v_cvt_pk_bf16_f32 v158, v68, v69
	v_cvt_pk_bf16_f32 v159, v70, v71
	v_cvt_pk_bf16_f32 v160, v64, v65
	v_cvt_pk_bf16_f32 v161, v66, v67
	global_store_dwordx4 v215, v[158:161], s[8:9] offset:256 sc1
	s_waitcnt vmcnt(14)
	s_add_u32 s8, s42, 0x40000
	s_addc_u32 s9, s43, 0
	v_lshlrev_b32_e32 v234, 16, v162
	v_and_b32_e32 v235, 0xffff0000, v162
	v_lshlrev_b32_e32 v236, 16, v163
	v_and_b32_e32 v237, 0xffff0000, v163
	v_lshlrev_b32_e32 v238, 16, v164
	v_and_b32_e32 v239, 0xffff0000, v164
	v_lshlrev_b32_e32 v240, 16, v165
	v_and_b32_e32 v241, 0xffff0000, v165
	v_pk_mul_f32 v[60:61], v[60:61], v[234:235]
	v_pk_mul_f32 v[56:57], v[56:57], v[238:239]
	v_pk_mul_f32 v[62:63], v[62:63], v[236:237]
	v_pk_mul_f32 v[58:59], v[58:59], v[240:241]
	v_cvt_pk_bf16_f32 v162, v60, v61
	v_cvt_pk_bf16_f32 v163, v62, v63
	v_cvt_pk_bf16_f32 v164, v56, v57
	v_cvt_pk_bf16_f32 v165, v58, v59
	global_store_dwordx4 v215, v[162:165], s[8:9] sc1
	v_lshlrev_b32_e32 v234, 16, v166
	v_and_b32_e32 v235, 0xffff0000, v166
	v_lshlrev_b32_e32 v236, 16, v167
	v_and_b32_e32 v237, 0xffff0000, v167
	v_lshlrev_b32_e32 v238, 16, v168
	v_and_b32_e32 v239, 0xffff0000, v168
	v_lshlrev_b32_e32 v240, 16, v169
	v_and_b32_e32 v241, 0xffff0000, v169
	v_pk_mul_f32 v[28:29], v[28:29], v[234:235]
	v_pk_mul_f32 v[24:25], v[24:25], v[238:239]
	v_pk_mul_f32 v[30:31], v[30:31], v[236:237]
	v_pk_mul_f32 v[26:27], v[26:27], v[240:241]
	v_cvt_pk_bf16_f32 v166, v28, v29
	v_cvt_pk_bf16_f32 v167, v30, v31
	v_cvt_pk_bf16_f32 v168, v24, v25
	v_cvt_pk_bf16_f32 v169, v26, v27
	global_store_dwordx4 v215, v[166:169], s[8:9] offset:256 sc1
	s_waitcnt vmcnt(14)
	s_add_u32 s8, s42, 0x48000
	s_addc_u32 s9, s43, 0
	v_lshlrev_b32_e32 v234, 16, v170
	v_and_b32_e32 v235, 0xffff0000, v170
	v_lshlrev_b32_e32 v236, 16, v171
	v_and_b32_e32 v237, 0xffff0000, v171
	v_lshlrev_b32_e32 v238, 16, v172
	v_and_b32_e32 v239, 0xffff0000, v172
	v_lshlrev_b32_e32 v240, 16, v173
	v_and_b32_e32 v241, 0xffff0000, v173
	v_pk_mul_f32 v[52:53], v[52:53], v[234:235]
	v_pk_mul_f32 v[48:49], v[48:49], v[238:239]
	v_pk_mul_f32 v[54:55], v[54:55], v[236:237]
	v_pk_mul_f32 v[50:51], v[50:51], v[240:241]
	v_cvt_pk_bf16_f32 v170, v52, v53
	v_cvt_pk_bf16_f32 v171, v54, v55
	v_cvt_pk_bf16_f32 v172, v48, v49
	v_cvt_pk_bf16_f32 v173, v50, v51
	global_store_dwordx4 v215, v[170:173], s[8:9] sc1
	v_lshlrev_b32_e32 v234, 16, v174
	v_and_b32_e32 v235, 0xffff0000, v174
	v_lshlrev_b32_e32 v236, 16, v175
	v_and_b32_e32 v237, 0xffff0000, v175
	v_lshlrev_b32_e32 v238, 16, v176
	v_and_b32_e32 v239, 0xffff0000, v176
	v_lshlrev_b32_e32 v240, 16, v177
	v_and_b32_e32 v241, 0xffff0000, v177
	v_pk_mul_f32 v[20:21], v[20:21], v[234:235]
	v_pk_mul_f32 v[16:17], v[16:17], v[238:239]
	v_pk_mul_f32 v[22:23], v[22:23], v[236:237]
	v_pk_mul_f32 v[18:19], v[18:19], v[240:241]
	v_cvt_pk_bf16_f32 v174, v20, v21
	v_cvt_pk_bf16_f32 v175, v22, v23
	v_cvt_pk_bf16_f32 v176, v16, v17
	v_cvt_pk_bf16_f32 v177, v18, v19
	global_store_dwordx4 v215, v[174:177], s[8:9] offset:256 sc1
	s_waitcnt vmcnt(14)
	s_add_u32 s8, s42, 0x50000
	s_addc_u32 s9, s43, 0
	v_lshlrev_b32_e32 v234, 16, v200
	v_and_b32_e32 v235, 0xffff0000, v200
	v_lshlrev_b32_e32 v236, 16, v201
	v_and_b32_e32 v237, 0xffff0000, v201
	v_lshlrev_b32_e32 v238, 16, v202
	v_and_b32_e32 v239, 0xffff0000, v202
	v_lshlrev_b32_e32 v240, 16, v203
	v_and_b32_e32 v241, 0xffff0000, v203
	v_pk_mul_f32 v[44:45], v[44:45], v[234:235]
	v_pk_mul_f32 v[40:41], v[40:41], v[238:239]
	v_pk_mul_f32 v[46:47], v[46:47], v[236:237]
	v_pk_mul_f32 v[42:43], v[42:43], v[240:241]
	v_cvt_pk_bf16_f32 v200, v44, v45
	v_cvt_pk_bf16_f32 v201, v46, v47
	v_cvt_pk_bf16_f32 v202, v40, v41
	v_cvt_pk_bf16_f32 v203, v42, v43
	global_store_dwordx4 v215, v[200:203], s[8:9] sc1
	v_lshlrev_b32_e32 v234, 16, v204
	v_and_b32_e32 v235, 0xffff0000, v204
	v_lshlrev_b32_e32 v236, 16, v205
	v_and_b32_e32 v237, 0xffff0000, v205
	v_lshlrev_b32_e32 v238, 16, v206
	v_and_b32_e32 v239, 0xffff0000, v206
	v_lshlrev_b32_e32 v240, 16, v207
	v_and_b32_e32 v241, 0xffff0000, v207
	v_pk_mul_f32 v[12:13], v[12:13], v[234:235]
	v_pk_mul_f32 v[8:9], v[8:9], v[238:239]
	v_pk_mul_f32 v[14:15], v[14:15], v[236:237]
	v_pk_mul_f32 v[10:11], v[10:11], v[240:241]
	v_cvt_pk_bf16_f32 v204, v12, v13
	v_cvt_pk_bf16_f32 v205, v14, v15
	v_cvt_pk_bf16_f32 v206, v8, v9
	v_cvt_pk_bf16_f32 v207, v10, v11
	global_store_dwordx4 v215, v[204:207], s[8:9] offset:256 sc1
	s_waitcnt vmcnt(14)
	s_add_u32 s8, s42, 0x58000
	s_addc_u32 s9, s43, 0
	v_lshlrev_b32_e32 v234, 16, v208
	v_and_b32_e32 v235, 0xffff0000, v208
	v_lshlrev_b32_e32 v236, 16, v209
	v_and_b32_e32 v237, 0xffff0000, v209
	v_lshlrev_b32_e32 v238, 16, v210
	v_and_b32_e32 v239, 0xffff0000, v210
	v_lshlrev_b32_e32 v240, 16, v211
	v_and_b32_e32 v241, 0xffff0000, v211
	v_pk_mul_f32 v[36:37], v[36:37], v[234:235]
	v_pk_mul_f32 v[32:33], v[32:33], v[238:239]
	v_pk_mul_f32 v[38:39], v[38:39], v[236:237]
	v_pk_mul_f32 v[34:35], v[34:35], v[240:241]
	v_cvt_pk_bf16_f32 v208, v36, v37
	v_cvt_pk_bf16_f32 v209, v38, v39
	v_cvt_pk_bf16_f32 v210, v32, v33
	v_cvt_pk_bf16_f32 v211, v34, v35
	global_store_dwordx4 v215, v[208:211], s[8:9] sc1
	v_lshlrev_b32_e32 v234, 16, v230
	v_and_b32_e32 v235, 0xffff0000, v230
	v_lshlrev_b32_e32 v236, 16, v231
	v_and_b32_e32 v237, 0xffff0000, v231
	v_lshlrev_b32_e32 v238, 16, v232
	v_and_b32_e32 v239, 0xffff0000, v232
	v_lshlrev_b32_e32 v240, 16, v233
	v_and_b32_e32 v241, 0xffff0000, v233
	v_pk_mul_f32 v[4:5], v[4:5], v[234:235]
	v_pk_mul_f32 v[0:1], v[0:1], v[238:239]
	v_pk_mul_f32 v[6:7], v[6:7], v[236:237]
	v_pk_mul_f32 v[2:3], v[2:3], v[240:241]
	v_cvt_pk_bf16_f32 v230, v4, v5
	v_cvt_pk_bf16_f32 v231, v6, v7
	v_cvt_pk_bf16_f32 v232, v0, v1
	v_cvt_pk_bf16_f32 v233, v2, v3
	global_store_dwordx4 v215, v[230:233], s[8:9] offset:256 sc1

; #define LAS __attribute__((address_space(3)))
; DI unsigned pk2(float lo, float hi) { f32x2 v = {lo, hi}; bf16x2_t b = __builtin_convertvector(v, bf16x2_t); return __builtin_bit_cast(unsigned, b); }
; template <int KIND>
; DI void attn_unit(const Frame& F, int qrow0, int head, int ctx_row0, int lat_row0, int ntiles) {
;     ...
;     ATT_PV(pfb, lds + ATT_VB + (vs_c == 0 ? 2 * ATT_VBUF : vs_c - ATT_VBUF));
;     { auto rr = __builtin_amdgcn_permlane32_swap(__float_as_uint(lsum), __float_as_uint(lsum), false, false); lsum = __uint_as_float(rr[0]) + __uint_as_float(rr[1]); }
;     const float inv = 1.f / lsum;
;     {
;         LAS unsigned char* stg = lds + ATT_OST + w * 4608;
;         LAS unsigned char* mine = stg + r32 * 144 + 8 * h5;
; #pragma unroll
;         for (int g = 0; g < 4; ++g) {
;             u32x2 a, b;
;             a.x = pk2(o0[4 * g] * inv, o0[4 * g + 1] * inv); a.y = pk2(o0[4 * g + 2] * inv, o0[4 * g + 3] * inv);
;             b.x = pk2(o1[4 * g] * inv, o1[4 * g + 1] * inv); b.y = pk2(o1[4 * g + 2] * inv, o1[4 * g + 3] * inv);
;             *(LAS u32x2*)(mine + 16 * g) = a; *(LAS u32x2*)(mine + 64 + 16 * g) = b;
;         }
;         asm volatile("s_waitcnt lgkmcnt(0)" ::: "memory");
;         bf16_t* ob = Op + (size_t)(qrow0 + 32 * w) * ldo;
; #pragma unroll
;         for (int it = 0; it < 4; ++it) { const int row = it * 8 + (lane >> 3), ch = lane & 7;
;             const u32x4 v = *(const LAS u32x4*)(stg + row * 144 + ch * 16);
;             *(u32x4*)(ob + (size_t)row * ldo + ch * 8) = v; }
;     }
;     asm volatile("s_waitcnt lgkmcnt(0)\n\ts_barrier" ::: "memory");
.LBB0_355:
	s_add_u32 s2, s6, s23
	s_addc_u32 s3, s7, 0
	s_add_i32 s4, s27, 0x2000
	s_cmpk_lg_i32 s27, 0x4000
	s_cselect_b32 s4, s4, 0
	s_add_i32 s5, s4, 0xffffe000
	s_cmp_lg_u32 s4, 0
	s_cselect_b32 s4, s5, 0x4000
	s_add_i32 s4, s4, 0
	s_waitcnt lgkmcnt(0)
	s_barrier
	v_add_u32_e32 v60, s4, v173
	ds_read_b64_tr_b16 v[48:49], v60 offset:32768
	ds_read_b64_tr_b16 v[50:51], v60 offset:33280
	ds_read_b64_tr_b16 v[52:53], v60 offset:33792
	ds_read_b64_tr_b16 v[54:55], v60 offset:34304
	s_waitcnt lgkmcnt(2)
	v_mfma_f32_32x32x16_bf16 v[0:15], v[48:51], v[40:43], v[0:15]
	ds_read_b64_tr_b16 v[48:49], v60 offset:28672
	ds_read_b64_tr_b16 v[50:51], v60 offset:29184
	ds_read_b64_tr_b16 v[56:57], v60 offset:29696
	ds_read_b64_tr_b16 v[58:59], v60 offset:30208
	s_mulk_i32 s22, 0x1200
	s_add_i32 s8, s22, 0
	s_waitcnt lgkmcnt(2)
	v_mfma_f32_32x32x16_bf16 v[16:31], v[48:51], v[40:43], v[16:31]
	v_mfma_f32_32x32x16_bf16 v[0:15], v[52:55], v[44:47], v[0:15]
	ds_read_b64_tr_b16 v[40:41], v60 offset:34816
	ds_read_b64_tr_b16 v[42:43], v60 offset:35328
	ds_read_b64_tr_b16 v[48:49], v60 offset:30720
	ds_read_b64_tr_b16 v[50:51], v60 offset:31232
	ds_read_b64_tr_b16 v[52:53], v60 offset:31744
	ds_read_b64_tr_b16 v[54:55], v60 offset:32256
	s_waitcnt lgkmcnt(6)
	v_mfma_f32_32x32x16_bf16 v[16:31], v[56:59], v[44:47], v[16:31]
	v_add_f32_e64 v44, v160, v161
	v_add_f32_e64 v45, v161, v160
	v_mov_b32_e32 v45, v44
	s_nop 1
	v_permlane32_swap_b32_e32 v44, v45
	v_add_f32_e32 v56, v44, v45
	v_div_scale_f32 v57, s[4:5], v56, v56, 1.0
	s_waitcnt lgkmcnt(2)
	v_mfma_f32_32x32x16_bf16 v[16:31], v[48:51], v[32:35], v[16:31]
	ds_read_b64_tr_b16 v[44:45], v60 offset:35840
	ds_read_b64_tr_b16 v[46:47], v60 offset:36352
	v_rcp_f32_e32 v48, v57
	s_lshl_b64 s[4:5], s[16:17], 10
	s_add_u32 s2, s2, s4
	s_addc_u32 s3, s3, s5
	v_fma_f32 v49, -v57, v48, 1.0
	v_fmac_f32_e32 v48, v49, v48
	v_mfma_f32_32x32x16_bf16 v[0:15], v[40:43], v[32:35], v[0:15]
	v_div_scale_f32 v49, vcc, 1.0, v56, 1.0
	v_mul_f32_e32 v32, v49, v48
	v_fma_f32 v33, -v57, v32, v49
	v_fmac_f32_e32 v32, v33, v48
	v_fma_f32 v33, -v57, v32, v49
	v_div_fmas_f32 v32, v33, v48, v32
	s_waitcnt lgkmcnt(2)
	v_mfma_f32_32x32x16_bf16 v[16:31], v[52:55], v[36:39], v[16:31]
	v_div_fixup_f32 v32, v32, v56, 1.0
	v_add3_u32 v33, s8, v151, v77
	s_waitcnt lgkmcnt(0)
	v_mfma_f32_32x32x16_bf16 v[0:15], v[44:47], v[36:39], v[0:15]
	s_nop 7
	v_mul_f32_e64 v16, v16, v32
	v_mul_f32_e64 v17, v17, v32
	v_mul_f32_e64 v18, v18, v32
	v_mul_f32_e64 v19, v19, v32
	v_cvt_pk_bf16_f32 v16, v16, v17
	v_cvt_pk_bf16_f32 v17, v18, v19
	v_pk_mul_f32 v[18:19], v[22:23], v[32:33] op_sel_hi:[1,0]
	v_pk_mul_f32 v[0:1], v[0:1], v[32:33] op_sel_hi:[1,0]
	v_pk_mul_f32 v[2:3], v[2:3], v[32:33] op_sel_hi:[1,0]
	v_cvt_pk_bf16_f32 v0, v0, v1
	v_cvt_pk_bf16_f32 v1, v2, v3
	v_pk_mul_f32 v[2:3], v[20:21], v[32:33] op_sel_hi:[1,0]
	v_pk_mul_f32 v[4:5], v[4:5], v[32:33] op_sel_hi:[1,0]
	v_cvt_pk_bf16_f32 v2, v2, v3
	v_cvt_pk_bf16_f32 v3, v18, v19
	v_pk_mul_f32 v[6:7], v[6:7], v[32:33] op_sel_hi:[1,0]
	v_add_u32_e32 v18, 0xe000, v33
	v_cvt_pk_bf16_f32 v4, v4, v5
	v_cvt_pk_bf16_f32 v5, v6, v7
	ds_write2_b64 v18, v[16:17], v[2:3] offset1:2
	ds_write2_b64 v18, v[0:1], v[4:5] offset0:8 offset1:10
	v_pk_mul_f32 v[0:1], v[24:25], v[32:33] op_sel_hi:[1,0]
	v_pk_mul_f32 v[2:3], v[26:27], v[32:33] op_sel_hi:[1,0]
	v_cvt_pk_bf16_f32 v0, v0, v1
	v_cvt_pk_bf16_f32 v1, v2, v3
	v_pk_mul_f32 v[2:3], v[8:9], v[32:33] op_sel_hi:[1,0]
	v_pk_mul_f32 v[4:5], v[10:11], v[32:33] op_sel_hi:[1,0]
	v_cvt_pk_bf16_f32 v2, v2, v3
	v_cvt_pk_bf16_f32 v3, v4, v5
	v_pk_mul_f32 v[4:5], v[28:29], v[32:33] op_sel_hi:[1,0]
	v_pk_mul_f32 v[6:7], v[30:31], v[32:33] op_sel_hi:[1,0]
	v_cvt_pk_bf16_f32 v4, v4, v5
	v_cvt_pk_bf16_f32 v5, v6, v7
	v_pk_mul_f32 v[6:7], v[12:13], v[32:33] op_sel_hi:[1,0]
	v_pk_mul_f32 v[8:9], v[14:15], v[32:33] op_sel_hi:[1,0]
	v_cvt_pk_bf16_f32 v6, v6, v7
	v_cvt_pk_bf16_f32 v7, v8, v9
	ds_write2_b64 v18, v[0:1], v[4:5] offset0:4 offset1:6
	ds_write2_b64 v18, v[2:3], v[6:7] offset0:12 offset1:14
	v_lshrrev_b32_e32 v4, 3, v76
	v_mul_u32_u24_e32 v0, 0x90, v4
	s_waitcnt lgkmcnt(0)
	v_add3_u32 v12, s8, v150, v0
	ds_read_b128 v[0:3], v12 offset:57344
	v_lshl_add_u64 v[8:9], s[2:3], 0, v[96:97]
	v_lshlrev_b32_e32 v96, 10, v4
	ds_read_b128 v[4:7], v12 offset:58496
	v_lshl_add_u64 v[10:11], v[8:9], 0, v[96:97]
	s_waitcnt lgkmcnt(1)
	global_store_dwordx4 v[10:11], v[0:3], off sc1
	v_or_b32_e32 v10, 0x4000, v96
	v_mov_b32_e32 v11, v97
	v_or_b32_e32 v0, 0x2000, v96
	v_mov_b32_e32 v1, v97
	v_lshl_add_u64 v[0:1], v[8:9], 0, v[0:1]
	s_waitcnt lgkmcnt(0)
	global_store_dwordx4 v[0:1], v[4:7], off sc1
	ds_read_b128 v[0:3], v12 offset:59648
	ds_read_b128 v[4:7], v12 offset:60800
	v_lshl_add_u64 v[10:11], v[8:9], 0, v[10:11]
	v_or_b32_e32 v96, 0x6000, v96
	s_waitcnt lgkmcnt(1)
	global_store_dwordx4 v[10:11], v[0:3], off sc1
	s_nop 1
	v_lshl_add_u64 v[0:1], v[8:9], 0, v[96:97]
	s_waitcnt lgkmcnt(0)
	global_store_dwordx4 v[0:1], v[4:7], off sc1
	s_waitcnt lgkmcnt(0)
	s_barrier

; #define LAS __attribute__((address_space(3)))
; DI unsigned pk2(float lo, float hi) { f32x2 v = {lo, hi}; bf16x2_t b = __builtin_convertvector(v, bf16x2_t); return __builtin_bit_cast(unsigned, b); }
; template <int KIND>
; DI void attn_unit(const Frame& F, int qrow0, int head, int ctx_row0, int lat_row0, int ntiles) {
;     ...
;     ATT_PV(pfb, lds + ATT_VB + (vs_c == 0 ? 2 * ATT_VBUF : vs_c - ATT_VBUF));
;     { auto rr = __builtin_amdgcn_permlane32_swap(__float_as_uint(lsum), __float_as_uint(lsum), false, false); lsum = __uint_as_float(rr[0]) + __uint_as_float(rr[1]); }
;     const float inv = 1.f / lsum;
;     {
;         LAS unsigned char* stg = lds + ATT_OST + w * 4608;
;         LAS unsigned char* mine = stg + r32 * 144 + 8 * h5;
; #pragma unroll
;         for (int g = 0; g < 4; ++g) {
;             u32x2 a, b;
;             a.x = pk2(o0[4 * g] * inv, o0[4 * g + 1] * inv); a.y = pk2(o0[4 * g + 2] * inv, o0[4 * g + 3] * inv);
;             b.x = pk2(o1[4 * g] * inv, o1[4 * g + 1] * inv); b.y = pk2(o1[4 * g + 2] * inv, o1[4 * g + 3] * inv);
;             *(LAS u32x2*)(mine + 16 * g) = a; *(LAS u32x2*)(mine + 64 + 16 * g) = b;
;         }
;         asm volatile("s_waitcnt lgkmcnt(0)" ::: "memory");
;         bf16_t* ob = Op + (size_t)(qrow0 + 32 * w) * ldo;
; #pragma unroll
;         for (int it = 0; it < 4; ++it) { const int row = it * 8 + (lane >> 3), ch = lane & 7;
;             const u32x4 v = *(const LAS u32x4*)(stg + row * 144 + ch * 16);
;             *(u32x4*)(ob + (size_t)row * ldo + ch * 8) = v; }
;     }
;     asm volatile("s_waitcnt lgkmcnt(0)\n\ts_barrier" ::: "memory");
.LBB0_385:
	s_add_i32 s2, s27, 0x2000
	s_cmpk_lg_i32 s27, 0x4000
	s_cselect_b32 s2, s2, 0
	s_add_i32 s3, s2, 0xffffe000
	s_cmp_lg_u32 s2, 0
	s_cselect_b32 s2, s3, 0x4000
	s_add_i32 s2, s2, 0
	s_waitcnt lgkmcnt(0)
	s_barrier
	v_add_u32_e32 v60, s2, v163
	ds_read_b64_tr_b16 v[50:51], v60 offset:32768
	ds_read_b64_tr_b16 v[52:53], v60 offset:33280
	ds_read_b64_tr_b16 v[54:55], v60 offset:28672
	v_add_f32_e32 v58, v48, v64
	s_mulk_i32 s9, 0x1200
	s_waitcnt lgkmcnt(1)
	v_mfma_f32_32x32x16_bf16 v[16:31], v[50:53], v[44:47], v[16:31]
	ds_read_b64_tr_b16 v[56:57], v60 offset:29184
	ds_read_b64_tr_b16 v[50:51], v60 offset:33792
	s_add_i32 s9, s9, 0
	s_mov_b32 s43, s17
	s_waitcnt lgkmcnt(1)
	v_mfma_f32_32x32x16_bf16 v[0:15], v[54:57], v[44:47], v[0:15]
	ds_read_b64_tr_b16 v[52:53], v60 offset:34304
	ds_read_b64_tr_b16 v[44:45], v60 offset:29696
	ds_read_b64_tr_b16 v[46:47], v60 offset:30208
	s_waitcnt lgkmcnt(0)
	v_mfma_f32_32x32x16_bf16 v[0:15], v[44:47], v[40:43], v[0:15]
	v_mfma_f32_32x32x16_bf16 v[16:31], v[50:53], v[40:43], v[16:31]
	ds_read_b64_tr_b16 v[48:49], v60 offset:34816
	ds_read_b64_tr_b16 v[50:51], v60 offset:35328
	ds_read_b64_tr_b16 v[52:53], v60 offset:30720
	ds_read_b64_tr_b16 v[54:55], v60 offset:31232
	ds_read_b64_tr_b16 v[56:57], v60 offset:31744
	v_mov_b32_e32 v40, v58
	s_nop 1
	v_permlane32_swap_b32_e32 v58, v40
	v_add_f32_e32 v44, v58, v40
	v_div_scale_f32 v45, s[2:3], v44, v44, 1.0
	s_waitcnt lgkmcnt(1)
	v_mfma_f32_32x32x16_bf16 v[0:15], v[52:55], v[32:35], v[0:15]
	v_rcp_f32_e32 v46, v45
	ds_read_b64_tr_b16 v[58:59], v60 offset:32256
	ds_read_b64_tr_b16 v[40:41], v60 offset:35840
	ds_read_b64_tr_b16 v[42:43], v60 offset:36352
	s_lshl_b64 s[2:3], s[42:43], 10
	s_add_u32 s2, s4, s2
	v_fma_f32 v47, -v45, v46, 1.0
	v_fmac_f32_e32 v46, v47, v46
	v_div_scale_f32 v47, vcc, 1.0, v44, 1.0
	v_mfma_f32_32x32x16_bf16 v[16:31], v[48:51], v[32:35], v[16:31]
	v_mul_f32_e32 v32, v47, v46
	v_fma_f32 v33, -v45, v32, v47
	v_fmac_f32_e32 v32, v33, v46
	v_fma_f32 v33, -v45, v32, v47
	v_div_fmas_f32 v32, v33, v46, v32
	v_div_fixup_f32 v32, v32, v44, 1.0
	v_add3_u32 v33, s9, v161, v160
	s_waitcnt lgkmcnt(2)
	v_mfma_f32_32x32x16_bf16 v[0:15], v[56:59], v[36:39], v[0:15]
	s_addc_u32 s3, s5, s3
	s_waitcnt lgkmcnt(0)
	v_mfma_f32_32x32x16_bf16 v[16:31], v[40:43], v[36:39], v[16:31]
	s_nop 8
	v_mul_f32_e64 v0, v0, v32
	v_mul_f32_e64 v1, v1, v32
	v_mul_f32_e64 v2, v2, v32
	v_mul_f32_e64 v3, v3, v32
	v_cvt_pk_bf16_f32 v0, v0, v1
	v_cvt_pk_bf16_f32 v1, v2, v3
	v_pk_mul_f32 v[4:5], v[4:5], v[32:33] op_sel_hi:[1,0]
	v_pk_mul_f32 v[6:7], v[6:7], v[32:33] op_sel_hi:[1,0]
	v_cvt_pk_bf16_f32 v4, v4, v5
	v_pk_mul_f32 v[2:3], v[16:17], v[32:33] op_sel_hi:[1,0]
	v_pk_mul_f32 v[16:17], v[18:19], v[32:33] op_sel_hi:[1,0]
	v_cvt_pk_bf16_f32 v2, v2, v3
	v_cvt_pk_bf16_f32 v3, v16, v17
	v_cvt_pk_bf16_f32 v5, v6, v7
	v_pk_mul_f32 v[6:7], v[20:21], v[32:33] op_sel_hi:[1,0]
	v_pk_mul_f32 v[16:17], v[22:23], v[32:33] op_sel_hi:[1,0]
	v_cvt_pk_bf16_f32 v6, v6, v7
	v_cvt_pk_bf16_f32 v7, v16, v17
	v_add_u32_e32 v16, 0xe000, v33
	ds_write2_b64 v16, v[0:1], v[4:5] offset1:2
	ds_write2_b64 v16, v[2:3], v[6:7] offset0:8 offset1:10
	v_pk_mul_f32 v[0:1], v[8:9], v[32:33] op_sel_hi:[1,0]
	v_pk_mul_f32 v[2:3], v[10:11], v[32:33] op_sel_hi:[1,0]
	v_cvt_pk_bf16_f32 v0, v0, v1
	v_cvt_pk_bf16_f32 v1, v2, v3
	v_pk_mul_f32 v[2:3], v[24:25], v[32:33] op_sel_hi:[1,0]
	v_pk_mul_f32 v[4:5], v[26:27], v[32:33] op_sel_hi:[1,0]
	v_cvt_pk_bf16_f32 v2, v2, v3
	v_cvt_pk_bf16_f32 v3, v4, v5
	v_pk_mul_f32 v[4:5], v[12:13], v[32:33] op_sel_hi:[1,0]
	v_pk_mul_f32 v[6:7], v[14:15], v[32:33] op_sel_hi:[1,0]
	v_cvt_pk_bf16_f32 v4, v4, v5
	v_cvt_pk_bf16_f32 v5, v6, v7
	v_pk_mul_f32 v[6:7], v[28:29], v[32:33] op_sel_hi:[1,0]
	v_pk_mul_f32 v[8:9], v[30:31], v[32:33] op_sel_hi:[1,0]
	v_cvt_pk_bf16_f32 v6, v6, v7
	v_cvt_pk_bf16_f32 v7, v8, v9
	ds_write2_b64 v16, v[0:1], v[4:5] offset0:4 offset1:6
	ds_write2_b64 v16, v[2:3], v[6:7] offset0:12 offset1:14
	v_lshrrev_b32_e32 v4, 3, v147
	v_mul_u32_u24_e32 v0, 0x90, v4
	s_waitcnt lgkmcnt(0)
	v_add3_u32 v12, s9, v146, v0
	ds_read_b128 v[0:3], v12 offset:57344
	v_lshl_add_u64 v[8:9], s[2:3], 0, v[96:97]
	v_lshlrev_b32_e32 v96, 10, v4
	ds_read_b128 v[4:7], v12 offset:58496
	v_lshl_add_u64 v[10:11], v[8:9], 0, v[96:97]
	s_waitcnt lgkmcnt(1)
	global_store_dwordx4 v[10:11], v[0:3], off sc1
	v_or_b32_e32 v10, 0x4000, v96
	v_mov_b32_e32 v11, v97
	v_or_b32_e32 v0, 0x2000, v96
	v_mov_b32_e32 v1, v97
	v_lshl_add_u64 v[0:1], v[8:9], 0, v[0:1]
	s_waitcnt lgkmcnt(0)
	global_store_dwordx4 v[0:1], v[4:7], off sc1
	ds_read_b128 v[0:3], v12 offset:59648
	ds_read_b128 v[4:7], v12 offset:60800
	v_lshl_add_u64 v[10:11], v[8:9], 0, v[10:11]
	v_or_b32_e32 v96, 0x6000, v96
	s_mov_b64 s[2:3], 0
	s_waitcnt lgkmcnt(1)
	global_store_dwordx4 v[10:11], v[0:3], off sc1
	s_nop 1
	v_lshl_add_u64 v[0:1], v[8:9], 0, v[96:97]
	s_waitcnt lgkmcnt(0)
	global_store_dwordx4 v[0:1], v[4:7], off sc1
	s_waitcnt lgkmcnt(0)
	s_barrier

; DI u32x4 pk8(const f32x4& a, const f32x4& b) { u32x4 w; w.x = pk2(a[0], a[1]); w.y = pk2(a[2], a[3]); w.z = pk2(b[0], b[1]); w.w = pk2(b[2], b[3]); return w; }
; #define PG8_BAR __builtin_amdgcn_s_barrier()
; #define FOR_AI_M _Pragma("unroll") for (int ai = 0; ai < 2; ++ai) _Pragma("unroll") for (int m = 0; m < 4; ++m)
;     ...
;         if (wr == 0) PG8_BAR;
;         E(acc, cur, wr, wc, fr, fq);
;         if (!has_next) break;
;         if (cur.last) {
; #pragma unroll
;             for (int a = 0; a < 2; ++a)
; #pragma unroll
;                 for (int b = 0; b < 2; ++b)
; #pragma unroll
;                     for (int m = 0; m < 4; ++m)
; #pragma unroll
;                         for (int n = 0; n < 2; ++n) acc[a][b][m][n] = (f32x4){0.f, 0.f, 0.f, 0.f};
;         }
;         cur = nxt; cA = nA; cB = nB; ++ui;
;         if (wr == 1) PG8_BAR;
;     DI void operator()(Acc& acc, const Unit& u, int wr, int wc, int fr, int fq) const {
;         FOR_AI_M { const int r = u.z * zrows + u.pm * 256 + EPI_ROWS(ai, m);
; #pragma unroll
;             for (int bj = 0; bj < 2; ++bj) *(u32x4*)(dst + (size_t)r * ld + u.pn * 256 + EPI_COL8(bj)) = pk8(acc[ai][bj][m][0], acc[ai][bj][m][1]); }
.LBB0_467:
	s_lshl_b32 s8, s57, 11
	s_lshl_b32 s9, s20, 8
	s_add_i32 s20, s9, s8
	v_add_u32_e32 v148, s20, v142
	v_cvt_pk_bf16_f32 v118, v118, v119
	v_cvt_pk_bf16_f32 v119, v120, v121
	v_cvt_pk_bf16_f32 v120, v114, v115
	v_add_u32_e32 v114, s20, v144
	v_cvt_pk_bf16_f32 v102, v102, v103
	v_cvt_pk_bf16_f32 v103, v104, v105
	v_cvt_pk_bf16_f32 v104, v98, v99
	v_add_u32_e32 v98, s20, v145
	v_cvt_pk_bf16_f32 v84, v84, v85
	v_cvt_pk_bf16_f32 v85, v86, v87
	v_cvt_pk_bf16_f32 v86, v80, v81
	v_add_u32_e32 v80, s20, v146
	v_cvt_pk_bf16_f32 v68, v68, v69
	v_cvt_pk_bf16_f32 v69, v70, v71
	v_cvt_pk_bf16_f32 v70, v64, v65
	v_add_u32_e32 v64, 0x80, v148
	v_cvt_pk_bf16_f32 v52, v52, v53
	v_cvt_pk_bf16_f32 v53, v54, v55
	v_cvt_pk_bf16_f32 v54, v48, v49
	v_add_u32_e32 v48, 0x90, v148
	v_cvt_pk_bf16_f32 v36, v36, v37
	v_cvt_pk_bf16_f32 v37, v38, v39
	v_cvt_pk_bf16_f32 v38, v32, v33
	v_add_u32_e32 v32, 0xa0, v148
	v_cvt_pk_bf16_f32 v20, v20, v21
	v_cvt_pk_bf16_f32 v21, v22, v23
	v_cvt_pk_bf16_f32 v22, v16, v17
	v_add_u32_e32 v16, 0xb0, v148
	v_ashrrev_i32_e32 v149, 31, v148
	s_lshl_b32 s8, s54, 8
	v_ashrrev_i32_e32 v115, 31, v114
	v_ashrrev_i32_e32 v99, 31, v98
	v_ashrrev_i32_e32 v81, 31, v80
	v_ashrrev_i32_e32 v65, 31, v64
	v_ashrrev_i32_e32 v49, 31, v48
	v_ashrrev_i32_e32 v33, 31, v32
	v_ashrrev_i32_e32 v17, 31, v16
	v_cvt_pk_bf16_f32 v126, v126, v127
	v_cvt_pk_bf16_f32 v127, v128, v129
	v_cvt_pk_bf16_f32 v128, v122, v123
	v_lshlrev_b64 v[122:123], 10, v[148:149]
	s_ashr_i32 s9, s8, 31
	v_cvt_pk_bf16_f32 v110, v110, v111
	v_cvt_pk_bf16_f32 v111, v112, v113
	v_cvt_pk_bf16_f32 v112, v106, v107
	v_lshlrev_b64 v[106:107], 10, v[114:115]
	v_cvt_pk_bf16_f32 v92, v92, v93
	v_cvt_pk_bf16_f32 v93, v94, v95
	v_cvt_pk_bf16_f32 v94, v88, v89
	v_lshlrev_b64 v[88:89], 10, v[98:99]
	v_cvt_pk_bf16_f32 v76, v76, v77
	v_cvt_pk_bf16_f32 v77, v78, v79
	v_cvt_pk_bf16_f32 v78, v72, v73
	v_lshlrev_b64 v[72:73], 10, v[80:81]
	v_cvt_pk_bf16_f32 v60, v60, v61
	v_cvt_pk_bf16_f32 v61, v62, v63
	v_cvt_pk_bf16_f32 v62, v56, v57
	v_lshlrev_b64 v[56:57], 10, v[64:65]
	v_cvt_pk_bf16_f32 v44, v44, v45
	v_cvt_pk_bf16_f32 v45, v46, v47
	v_cvt_pk_bf16_f32 v46, v40, v41
	v_lshlrev_b64 v[40:41], 10, v[48:49]
	v_cvt_pk_bf16_f32 v28, v28, v29
	v_cvt_pk_bf16_f32 v29, v30, v31
	v_cvt_pk_bf16_f32 v30, v24, v25
	v_lshlrev_b64 v[24:25], 10, v[32:33]
	v_cvt_pk_bf16_f32 v12, v12, v13
	v_cvt_pk_bf16_f32 v13, v14, v15
	v_cvt_pk_bf16_f32 v14, v8, v9
	v_lshlrev_b64 v[8:9], 10, v[16:17]
	v_lshl_add_u64 v[122:123], s[12:13], 0, v[122:123]
	s_lshl_b64 s[10:11], s[8:9], 1
	v_lshl_add_u64 v[106:107], s[12:13], 0, v[106:107]
	v_lshl_add_u64 v[88:89], s[12:13], 0, v[88:89]
	v_lshl_add_u64 v[72:73], s[12:13], 0, v[72:73]
	v_lshl_add_u64 v[56:57], s[12:13], 0, v[56:57]
	v_lshl_add_u64 v[40:41], s[12:13], 0, v[40:41]
	v_lshl_add_u64 v[24:25], s[12:13], 0, v[24:25]
	v_lshl_add_u64 v[8:9], s[12:13], 0, v[8:9]
	v_lshl_add_u64 v[122:123], v[122:123], 0, s[10:11]
	v_lshl_add_u64 v[106:107], v[106:107], 0, s[10:11]
	v_lshl_add_u64 v[88:89], v[88:89], 0, s[10:11]
	v_lshl_add_u64 v[72:73], v[72:73], 0, s[10:11]
	v_lshl_add_u64 v[56:57], v[56:57], 0, s[10:11]
	v_lshl_add_u64 v[40:41], v[40:41], 0, s[10:11]
	v_lshl_add_u64 v[24:25], v[24:25], 0, s[10:11]
	v_lshl_add_u64 v[8:9], v[8:9], 0, s[10:11]
	v_cvt_pk_bf16_f32 v129, v124, v125
	v_lshl_add_u64 v[122:123], v[122:123], 0, v[96:97]
	v_cvt_pk_bf16_f32 v121, v116, v117
	v_cvt_pk_bf16_f32 v113, v108, v109
	v_lshl_add_u64 v[106:107], v[106:107], 0, v[96:97]
	v_cvt_pk_bf16_f32 v105, v100, v101
	v_cvt_pk_bf16_f32 v95, v90, v91
	v_lshl_add_u64 v[88:89], v[88:89], 0, v[96:97]
	v_cvt_pk_bf16_f32 v87, v82, v83
	v_cvt_pk_bf16_f32 v79, v74, v75
	v_lshl_add_u64 v[72:73], v[72:73], 0, v[96:97]
	v_cvt_pk_bf16_f32 v71, v66, v67
	v_cvt_pk_bf16_f32 v63, v58, v59
	v_lshl_add_u64 v[56:57], v[56:57], 0, v[96:97]
	v_cvt_pk_bf16_f32 v55, v50, v51
	v_cvt_pk_bf16_f32 v47, v42, v43
	v_lshl_add_u64 v[40:41], v[40:41], 0, v[96:97]
	v_cvt_pk_bf16_f32 v39, v34, v35
	v_cvt_pk_bf16_f32 v31, v26, v27
	v_lshl_add_u64 v[24:25], v[24:25], 0, v[96:97]
	v_cvt_pk_bf16_f32 v23, v18, v19
	v_cvt_pk_bf16_f32 v15, v10, v11
	v_lshl_add_u64 v[8:9], v[8:9], 0, v[96:97]
	v_cvt_pk_bf16_f32 v4, v4, v5
	v_cvt_pk_bf16_f32 v5, v6, v7
	v_cvt_pk_bf16_f32 v6, v0, v1
	v_cvt_pk_bf16_f32 v7, v2, v3
	s_andn2_b64 vcc, exec, s[2:3]
	s_mov_b64 s[2:3], -1
	global_store_dwordx4 v[122:123], v[126:129], off sc1
	global_store_dwordx4 v[122:123], v[118:121], off offset:256 sc1
	global_store_dwordx4 v[106:107], v[110:113], off sc1
	global_store_dwordx4 v[106:107], v[102:105], off offset:256 sc1
	global_store_dwordx4 v[88:89], v[92:95], off sc1
	global_store_dwordx4 v[88:89], v[84:87], off offset:256 sc1
	global_store_dwordx4 v[72:73], v[76:79], off sc1
	global_store_dwordx4 v[72:73], v[68:71], off offset:256 sc1
	global_store_dwordx4 v[56:57], v[60:63], off sc1
	global_store_dwordx4 v[56:57], v[52:55], off offset:256 sc1
	global_store_dwordx4 v[40:41], v[44:47], off sc1
	global_store_dwordx4 v[40:41], v[36:39], off offset:256 sc1
	global_store_dwordx4 v[24:25], v[28:31], off sc1
	global_store_dwordx4 v[24:25], v[20:23], off offset:256 sc1
	global_store_dwordx4 v[8:9], v[12:15], off sc1
	global_store_dwordx4 v[8:9], v[4:7], off offset:256 sc1
	s_cbranch_vccnz .LBB0_459
	s_andn2_b64 vcc, exec, s[4:5]
	s_cbranch_vccnz .LBB0_458
	s_barrier
	s_branch .LBB0_458

; DI u32x4 pk8(const f32x4& a, const f32x4& b) { u32x4 w; w.x = pk2(a[0], a[1]); w.y = pk2(a[2], a[3]); w.z = pk2(b[0], b[1]); w.w = pk2(b[2], b[3]); return w; }
; #define PG8_BAR __builtin_amdgcn_s_barrier()
; #define FOR_AI_M _Pragma("unroll") for (int ai = 0; ai < 2; ++ai) _Pragma("unroll") for (int m = 0; m < 4; ++m)
;     ...
;         if (wr == 0) PG8_BAR;
;         E(acc, cur, wr, wc, fr, fq);
;         if (!has_next) break;
;         if (cur.last) {
; #pragma unroll
;             for (int a = 0; a < 2; ++a)
; #pragma unroll
;                 for (int b = 0; b < 2; ++b)
; #pragma unroll
;                     for (int m = 0; m < 4; ++m)
; #pragma unroll
;                         for (int n = 0; n < 2; ++n) acc[a][b][m][n] = (f32x4){0.f, 0.f, 0.f, 0.f};
;         }
;         cur = nxt; cA = nA; cB = nB; ++ui;
;         if (wr == 1) PG8_BAR;
;     DI void operator()(Acc& acc, const Unit& u, int wr, int wc, int fr, int fq) const {
;         FOR_AI_M { const int r = u.z * zrows + u.pm * 256 + EPI_ROWS(ai, m);
; #pragma unroll
;             for (int bj = 0; bj < 2; ++bj) *(u32x4*)(dst + (size_t)r * ld + u.pn * 256 + EPI_COL8(bj)) = pk8(acc[ai][bj][m][0], acc[ai][bj][m][1]); }
.LBB0_486:
	s_lshl_b32 s16, s26, 8
	v_add_u32_e32 v144, s16, v138
	v_cvt_pk_bf16_f32 v118, v118, v119
	v_cvt_pk_bf16_f32 v119, v120, v121
	v_cvt_pk_bf16_f32 v120, v114, v115
	v_add_u32_e32 v114, s16, v140
	v_cvt_pk_bf16_f32 v102, v102, v103
	v_cvt_pk_bf16_f32 v103, v104, v105
	v_cvt_pk_bf16_f32 v104, v98, v99
	v_add_u32_e32 v98, s16, v141
	v_cvt_pk_bf16_f32 v84, v84, v85
	v_cvt_pk_bf16_f32 v85, v86, v87
	v_cvt_pk_bf16_f32 v86, v80, v81
	v_add_u32_e32 v80, s16, v142
	v_cvt_pk_bf16_f32 v68, v68, v69
	v_cvt_pk_bf16_f32 v69, v70, v71
	v_cvt_pk_bf16_f32 v70, v64, v65
	v_add_u32_e32 v64, 0x80, v144
	v_cvt_pk_bf16_f32 v52, v52, v53
	v_cvt_pk_bf16_f32 v53, v54, v55
	v_cvt_pk_bf16_f32 v54, v48, v49
	v_add_u32_e32 v48, 0x90, v144
	v_cvt_pk_bf16_f32 v36, v36, v37
	v_cvt_pk_bf16_f32 v37, v38, v39
	v_cvt_pk_bf16_f32 v38, v32, v33
	v_add_u32_e32 v32, 0xa0, v144
	v_cvt_pk_bf16_f32 v20, v20, v21
	v_cvt_pk_bf16_f32 v21, v22, v23
	v_cvt_pk_bf16_f32 v22, v16, v17
	v_add_u32_e32 v16, 0xb0, v144
	v_ashrrev_i32_e32 v145, 31, v144
	s_lshl_b32 s8, s55, 8
	v_ashrrev_i32_e32 v115, 31, v114
	v_ashrrev_i32_e32 v99, 31, v98
	v_ashrrev_i32_e32 v81, 31, v80
	v_ashrrev_i32_e32 v65, 31, v64
	v_ashrrev_i32_e32 v49, 31, v48
	v_ashrrev_i32_e32 v33, 31, v32
	v_ashrrev_i32_e32 v17, 31, v16
	v_cvt_pk_bf16_f32 v126, v126, v127
	v_cvt_pk_bf16_f32 v127, v128, v129
	v_cvt_pk_bf16_f32 v128, v122, v123
	v_lshlrev_b64 v[122:123], 10, v[144:145]
	s_ashr_i32 s9, s8, 31
	v_cvt_pk_bf16_f32 v110, v110, v111
	v_cvt_pk_bf16_f32 v111, v112, v113
	v_cvt_pk_bf16_f32 v112, v106, v107
	v_lshlrev_b64 v[106:107], 10, v[114:115]
	v_cvt_pk_bf16_f32 v92, v92, v93
	v_cvt_pk_bf16_f32 v93, v94, v95
	v_cvt_pk_bf16_f32 v94, v88, v89
	v_lshlrev_b64 v[88:89], 10, v[98:99]
	v_cvt_pk_bf16_f32 v76, v76, v77
	v_cvt_pk_bf16_f32 v77, v78, v79
	v_cvt_pk_bf16_f32 v78, v72, v73
	v_lshlrev_b64 v[72:73], 10, v[80:81]
	v_cvt_pk_bf16_f32 v60, v60, v61
	v_cvt_pk_bf16_f32 v61, v62, v63
	v_cvt_pk_bf16_f32 v62, v56, v57
	v_lshlrev_b64 v[56:57], 10, v[64:65]
	v_cvt_pk_bf16_f32 v44, v44, v45
	v_cvt_pk_bf16_f32 v45, v46, v47
	v_cvt_pk_bf16_f32 v46, v40, v41
	v_lshlrev_b64 v[40:41], 10, v[48:49]
	v_cvt_pk_bf16_f32 v28, v28, v29
	v_cvt_pk_bf16_f32 v29, v30, v31
	v_cvt_pk_bf16_f32 v30, v24, v25
	v_lshlrev_b64 v[24:25], 10, v[32:33]
	v_cvt_pk_bf16_f32 v12, v12, v13
	v_cvt_pk_bf16_f32 v13, v14, v15
	v_cvt_pk_bf16_f32 v14, v8, v9
	v_lshlrev_b64 v[8:9], 10, v[16:17]
	v_lshl_add_u64 v[122:123], s[12:13], 0, v[122:123]
	s_lshl_b64 s[10:11], s[8:9], 1
	v_lshl_add_u64 v[106:107], s[12:13], 0, v[106:107]
	v_lshl_add_u64 v[88:89], s[12:13], 0, v[88:89]
	v_lshl_add_u64 v[72:73], s[12:13], 0, v[72:73]
	v_lshl_add_u64 v[56:57], s[12:13], 0, v[56:57]
	v_lshl_add_u64 v[40:41], s[12:13], 0, v[40:41]
	v_lshl_add_u64 v[24:25], s[12:13], 0, v[24:25]
	v_lshl_add_u64 v[8:9], s[12:13], 0, v[8:9]
	v_lshl_add_u64 v[122:123], v[122:123], 0, s[10:11]
	v_lshl_add_u64 v[106:107], v[106:107], 0, s[10:11]
	v_lshl_add_u64 v[88:89], v[88:89], 0, s[10:11]
	v_lshl_add_u64 v[72:73], v[72:73], 0, s[10:11]
	v_lshl_add_u64 v[56:57], v[56:57], 0, s[10:11]
	v_lshl_add_u64 v[40:41], v[40:41], 0, s[10:11]
	v_lshl_add_u64 v[24:25], v[24:25], 0, s[10:11]
	v_lshl_add_u64 v[8:9], v[8:9], 0, s[10:11]
	v_cvt_pk_bf16_f32 v129, v124, v125
	v_lshl_add_u64 v[122:123], v[122:123], 0, v[96:97]
	v_cvt_pk_bf16_f32 v121, v116, v117
	v_cvt_pk_bf16_f32 v113, v108, v109
	v_lshl_add_u64 v[106:107], v[106:107], 0, v[96:97]
	v_cvt_pk_bf16_f32 v105, v100, v101
	v_cvt_pk_bf16_f32 v95, v90, v91
	v_lshl_add_u64 v[88:89], v[88:89], 0, v[96:97]
	v_cvt_pk_bf16_f32 v87, v82, v83
	v_cvt_pk_bf16_f32 v79, v74, v75
	v_lshl_add_u64 v[72:73], v[72:73], 0, v[96:97]
	v_cvt_pk_bf16_f32 v71, v66, v67
	v_cvt_pk_bf16_f32 v63, v58, v59
	v_lshl_add_u64 v[56:57], v[56:57], 0, v[96:97]
	v_cvt_pk_bf16_f32 v55, v50, v51
	v_cvt_pk_bf16_f32 v47, v42, v43
	v_lshl_add_u64 v[40:41], v[40:41], 0, v[96:97]
	v_cvt_pk_bf16_f32 v39, v34, v35
	v_cvt_pk_bf16_f32 v31, v26, v27
	v_lshl_add_u64 v[24:25], v[24:25], 0, v[96:97]
	v_cvt_pk_bf16_f32 v23, v18, v19
	v_cvt_pk_bf16_f32 v15, v10, v11
	v_lshl_add_u64 v[8:9], v[8:9], 0, v[96:97]
	v_cvt_pk_bf16_f32 v4, v4, v5
	v_cvt_pk_bf16_f32 v5, v6, v7
	v_cvt_pk_bf16_f32 v6, v0, v1
	v_cvt_pk_bf16_f32 v7, v2, v3
	s_andn2_b64 vcc, exec, s[24:25]
	s_mov_b64 s[8:9], -1
	global_store_dwordx4 v[122:123], v[126:129], off sc1
	global_store_dwordx4 v[122:123], v[118:121], off offset:256 sc1
	global_store_dwordx4 v[106:107], v[110:113], off sc1
	global_store_dwordx4 v[106:107], v[102:105], off offset:256 sc1
	global_store_dwordx4 v[88:89], v[92:95], off sc1
	global_store_dwordx4 v[88:89], v[84:87], off offset:256 sc1
	global_store_dwordx4 v[72:73], v[76:79], off sc1
	global_store_dwordx4 v[72:73], v[68:71], off offset:256 sc1
	global_store_dwordx4 v[56:57], v[60:63], off sc1
	global_store_dwordx4 v[56:57], v[52:55], off offset:256 sc1
	global_store_dwordx4 v[40:41], v[44:47], off sc1
	global_store_dwordx4 v[40:41], v[36:39], off offset:256 sc1
	global_store_dwordx4 v[24:25], v[28:31], off sc1
	global_store_dwordx4 v[24:25], v[20:23], off offset:256 sc1
	global_store_dwordx4 v[8:9], v[12:15], off sc1
	global_store_dwordx4 v[8:9], v[4:7], off offset:256 sc1
	s_cbranch_vccnz .LBB0_478
	s_andn2_b64 vcc, exec, s[6:7]
	s_cbranch_vccnz .LBB0_477
	s_barrier
	s_branch .LBB0_477

; DI u32x4 pk8(const f32x4& a, const f32x4& b) { u32x4 w; w.x = pk2(a[0], a[1]); w.y = pk2(a[2], a[3]); w.z = pk2(b[0], b[1]); w.w = pk2(b[2], b[3]); return w; }
; #define FOR_AI_M _Pragma("unroll") for (int ai = 0; ai < 2; ++ai) _Pragma("unroll") for (int m = 0; m < 4; ++m)
;     DI void operator()(Acc& acc, const Unit& u, int wr, int wc, int fr, int fq) const {
;     ...
;         if (u.job == 1) {
;             bf16_t* base; int ld;
;             if (u.pn < 64) { base = (bf16_t*)(ws + WS_TF) + (size_t)(u.pn >> 3) * 1024 * 2048 + (u.pn & 7) * 256; ld = 2048; }
;             else { base = (bf16_t*)(ws + WS_TFC) + (size_t)(u.pn - 64) * 1024 * 256; ld = 256; }
;             FOR_AI_M { const int r = u.pm * 256 + EPI_ROWS(ai, m);
; #pragma unroll
;                 for (int bj = 0; bj < 2; ++bj) *(u32x4*)(base + (size_t)r * ld + EPI_COL8(bj)) = pk8(acc[ai][bj][m][0], acc[ai][bj][m][1]); }
;             return;
.LBB0_595:
	s_lshl_b32 s9, s30, 8
	s_waitcnt lgkmcnt(0)
	v_add_u32_e32 v132, s9, v173
	v_mad_i64_i32 v[98:99], s[10:11], s8, v132, 0
	v_lshl_add_u64 v[98:99], v[98:99], 1, s[6:7]
	v_lshlrev_b32_e32 v96, 1, v174
	v_cvt_pk_bf16_f32 v128, v128, v129
	v_cvt_pk_bf16_f32 v129, v130, v131
	v_cvt_pk_bf16_f32 v130, v124, v125
	v_cvt_pk_bf16_f32 v131, v126, v127
	v_lshl_add_u64 v[98:99], v[98:99], 0, v[96:97]
	v_cvt_pk_bf16_f32 v116, v116, v117
	v_cvt_pk_bf16_f32 v117, v118, v119
	v_cvt_pk_bf16_f32 v118, v108, v109
	v_cvt_pk_bf16_f32 v119, v110, v111
	global_store_dwordx4 v[98:99], v[128:131], off sc1
	global_store_dwordx4 v[98:99], v[116:119], off offset:256 sc1
	v_or_b32_e32 v98, 16, v173
	v_add_u32_e32 v98, s9, v98
	v_mad_i64_i32 v[98:99], s[10:11], s8, v98, 0
	v_lshl_add_u64 v[98:99], v[98:99], 1, s[6:7]
	v_cvt_pk_bf16_f32 v110, v112, v113
	v_lshl_add_u64 v[112:113], v[98:99], 0, v[96:97]
	v_cvt_pk_bf16_f32 v98, v100, v101
	v_cvt_pk_bf16_f32 v100, v88, v89
	v_add_u32_e32 v88, s9, v196
	v_cvt_pk_bf16_f32 v99, v102, v103
	v_cvt_pk_bf16_f32 v101, v90, v91
	v_mad_i64_i32 v[88:89], s[10:11], s8, v88, 0
	global_store_dwordx4 v[112:113], v[98:101], off offset:256 sc1
	v_cvt_pk_bf16_f32 v80, v80, v81
	v_cvt_pk_bf16_f32 v81, v82, v83
	v_lshl_add_u64 v[98:99], v[88:89], 1, s[6:7]
	v_cvt_pk_bf16_f32 v82, v72, v73
	v_add_u32_e32 v72, s9, v197
	v_cvt_pk_bf16_f32 v68, v68, v69
	v_cvt_pk_bf16_f32 v69, v70, v71
	v_cvt_pk_bf16_f32 v70, v64, v65
	v_add_u32_e32 v64, 0x80, v132
	v_cvt_pk_bf16_f32 v108, v120, v121
	v_cvt_pk_bf16_f32 v109, v122, v123
	v_cvt_pk_bf16_f32 v111, v114, v115
	v_cvt_pk_bf16_f32 v90, v92, v93
	v_lshl_add_u64 v[92:93], v[98:99], 0, v[96:97]
	v_cvt_pk_bf16_f32 v83, v74, v75
	v_mad_i64_i32 v[72:73], s[10:11], s8, v72, 0
	v_mad_i64_i32 v[64:65], s[10:11], s8, v64, 0
	global_store_dwordx4 v[112:113], v[108:111], off sc1
	global_store_dwordx4 v[92:93], v[80:83], off offset:256 sc1
	v_lshl_add_u64 v[64:65], v[64:65], 1, s[6:7]
	v_cvt_pk_bf16_f32 v48, v48, v49
	v_lshl_add_u64 v[80:81], v[72:73], 1, s[6:7]
	v_cvt_pk_bf16_f32 v49, v50, v51
	v_cvt_pk_bf16_f32 v50, v40, v41
	v_add_u32_e32 v40, 0x90, v132
	v_cvt_pk_bf16_f32 v88, v104, v105
	v_cvt_pk_bf16_f32 v89, v106, v107
	v_cvt_pk_bf16_f32 v91, v94, v95
	v_cvt_pk_bf16_f32 v72, v84, v85
	v_cvt_pk_bf16_f32 v73, v86, v87
	v_cvt_pk_bf16_f32 v74, v76, v77
	v_cvt_pk_bf16_f32 v75, v78, v79
	v_lshl_add_u64 v[76:77], v[80:81], 0, v[96:97]
	v_cvt_pk_bf16_f32 v71, v66, v67
	v_cvt_pk_bf16_f32 v60, v60, v61
	v_cvt_pk_bf16_f32 v61, v62, v63
	v_cvt_pk_bf16_f32 v62, v56, v57
	v_lshl_add_u64 v[56:57], v[64:65], 0, v[96:97]
	v_cvt_pk_bf16_f32 v51, v42, v43
	v_mad_i64_i32 v[40:41], s[10:11], s8, v40, 0
	global_store_dwordx4 v[92:93], v[88:91], off sc1
	global_store_dwordx4 v[76:77], v[72:75], off sc1
	global_store_dwordx4 v[76:77], v[68:71], off offset:256 sc1
	global_store_dwordx4 v[56:57], v[48:51], off offset:256 sc1
	v_cvt_pk_bf16_f32 v32, v32, v33
	v_cvt_pk_bf16_f32 v33, v34, v35
	v_lshl_add_u64 v[48:49], v[40:41], 1, s[6:7]
	v_cvt_pk_bf16_f32 v34, v24, v25
	v_add_u32_e32 v24, 0xa0, v132
	v_cvt_pk_bf16_f32 v63, v58, v59
	v_cvt_pk_bf16_f32 v42, v44, v45
	v_lshl_add_u64 v[44:45], v[48:49], 0, v[96:97]
	v_cvt_pk_bf16_f32 v35, v26, v27
	v_mad_i64_i32 v[24:25], s[10:11], s8, v24, 0
	global_store_dwordx4 v[56:57], v[60:63], off sc1
	global_store_dwordx4 v[44:45], v[32:35], off offset:256 sc1
	v_cvt_pk_bf16_f32 v16, v16, v17
	v_cvt_pk_bf16_f32 v17, v18, v19
	v_lshl_add_u64 v[32:33], v[24:25], 1, s[6:7]
	v_cvt_pk_bf16_f32 v18, v8, v9
	v_add_u32_e32 v8, 0xb0, v132
	v_cvt_pk_bf16_f32 v40, v52, v53
	v_cvt_pk_bf16_f32 v41, v54, v55
	v_cvt_pk_bf16_f32 v43, v46, v47
	v_cvt_pk_bf16_f32 v26, v28, v29
	v_lshl_add_u64 v[28:29], v[32:33], 0, v[96:97]
	v_cvt_pk_bf16_f32 v19, v10, v11
	v_mad_i64_i32 v[8:9], s[8:9], s8, v8, 0
	global_store_dwordx4 v[44:45], v[40:43], off sc1
	global_store_dwordx4 v[28:29], v[16:19], off offset:256 sc1
	v_cvt_pk_bf16_f32 v24, v36, v37
	v_cvt_pk_bf16_f32 v25, v38, v39
	v_lshl_add_u64 v[16:17], v[8:9], 1, s[6:7]
	v_cvt_pk_bf16_f32 v27, v30, v31
	v_cvt_pk_bf16_f32 v8, v20, v21
	v_cvt_pk_bf16_f32 v9, v22, v23
	v_cvt_pk_bf16_f32 v10, v12, v13
	v_cvt_pk_bf16_f32 v11, v14, v15
	v_lshl_add_u64 v[12:13], v[16:17], 0, v[96:97]
	v_cvt_pk_bf16_f32 v4, v4, v5
	v_cvt_pk_bf16_f32 v5, v6, v7
	v_cvt_pk_bf16_f32 v6, v0, v1
	v_cvt_pk_bf16_f32 v7, v2, v3
	global_store_dwordx4 v[28:29], v[24:27], off sc1
	global_store_dwordx4 v[12:13], v[8:11], off sc1
	global_store_dwordx4 v[12:13], v[4:7], off offset:256 sc1
	s_andn2_b64 vcc, exec, s[4:5]
	s_mov_b64 s[4:5], -1
	s_cbranch_vccnz .LBB0_579
	s_branch .LBB0_659

; DI u32x4 pk8(const f32x4& a, const f32x4& b) { u32x4 w; w.x = pk2(a[0], a[1]); w.y = pk2(a[2], a[3]); w.z = pk2(b[0], b[1]); w.w = pk2(b[2], b[3]); return w; }
; DI float shx(float v, int m, int lane) { return __int_as_float(__builtin_amdgcn_ds_bpermute((lane ^ m) << 2, __float_as_int(v))); }
; #define FOR_AI_M _Pragma("unroll") for (int ai = 0; ai < 2; ++ai) _Pragma("unroll") for (int m = 0; m < 4; ++m)
; #define ROW_FENCE asm volatile("" ::: "memory")
;     DI void operator()(Acc& acc, const Unit& u, int wr, int wc, int fr, int fq) const {
;     ...
;         FOR_AI_M { const int r = row0 + EPI_ROWS(ai, m);
;             f32x4 x[2][2];
; #pragma unroll
;             for (int bj = 0; bj < 2; ++bj) { x[bj][0] = acc[ai][bj][m][0]; x[bj][1] = acc[ai][bj][m][1]; }
;             if (!is_v) {
;                 float s = 0.f;
; #pragma unroll
;                 for (int bj = 0; bj < 2; ++bj)
; #pragma unroll
;                     for (int n = 0; n < 2; ++n) s += (x[bj][n][0] * x[bj][n][0] + x[bj][n][1] * x[bj][n][1]) + (x[bj][n][2] * x[bj][n][2] + x[bj][n][3] * x[bj][n][3]);
;                 s += shx(s, 16, fr + 16 * fq); s += shx(s, 32, fr + 16 * fq);
;                 const float rstd = 1.f / sqrtf(s * (1.f / 64.f) + EPS);
; #pragma unroll
;                 for (int bj = 0; bj < 2; ++bj)
; #pragma unroll
;                     for (int n = 0; n < 2; ++n) x[bj][n] = x[bj][n] * rstd * gv[bj][n];
;                 if (rope) {
;                     const float* rr = rg + (size_t)(r & 2047) * 64 + 8 * fq;
; #pragma unroll
;                     for (int n = 0; n < 2; ++n) { const f32x4 cs = *(const f32x4*)(rr + 4 * n), sn = *(const f32x4*)(rr + 32 + 4 * n);
;                         const f32x4 x1 = x[0][n], x2 = x[1][n]; x[0][n] = x1 * cs - x2 * sn; x[1][n] = x1 * sn + x2 * cs; }
;                 }
; #pragma unroll
;                 for (int bj = 0; bj < 2; ++bj)
; #pragma unroll
;                     for (int n = 0; n < 2; ++n) x[bj][n] = x[bj][n] * qs;
;             }
; #pragma unroll
;             for (int bj = 0; bj < 2; ++bj) *(u32x4*)(dst + (size_t)r * ld + colb + 32 * bj + 8 * fq) = pk8(x[bj][0], x[bj][1]);
;             if (m == 3) ROW_FENCE;
.LBB0_607:
	s_xor_b64 s[10:11], s[34:35], -1
	s_add_u32 s12, s94, s12
	s_addc_u32 s13, s95, s13
	s_lshl_b64 s[8:9], s[16:17], 1
	s_add_u32 s8, s12, s8
	s_addc_u32 s9, s13, s9
	v_lshlrev_b32_e32 v96, 1, v172
	v_lshl_add_u64 v[98:99], s[8:9], 0, v[96:97]
	v_mad_i64_i32 v[192:193], s[8:9], s42, v199, 0
	v_lshl_add_u64 v[192:193], v[192:193], 1, v[98:99]
	v_cvt_pk_bf16_f32 v152, v152, v153
	v_cvt_pk_bf16_f32 v153, v154, v155
	v_cvt_pk_bf16_f32 v154, v148, v149
	v_cvt_pk_bf16_f32 v155, v150, v151
	v_cvt_pk_bf16_f32 v148, v156, v157
	v_cvt_pk_bf16_f32 v149, v158, v159
	v_cvt_pk_bf16_f32 v150, v160, v161
	v_cvt_pk_bf16_f32 v151, v162, v163
	v_lshlrev_b32_e32 v251, 8, v199
	v_and_b32_e32 v251, 0x7ff00, v251
	v_mov_b32_e32 v249, 0
	v_add_u32_e32 v248, 0x1000, v251
	v_lshl_add_u64 v[252:253], v[176:177], 0, v[248:249]
	global_load_dwordx4 v[202:205], v[252:253], off offset:16
	global_load_dwordx4 v[206:209], v[252:253], off
	global_load_dwordx4 v[226:229], v[252:253], off offset:144
	global_load_dwordx4 v[230:233], v[252:253], off offset:128
	global_store_dwordx4 v[192:193], v[152:155], off sc1
	global_store_dwordx4 v[192:193], v[148:151], off offset:64 sc1
	v_cndmask_b32_e64 v96, 0, 1, s[10:11]
	v_mov_b64_e32 v[154:155], v[122:123]
	v_mov_b64_e32 v[150:151], v[114:115]
	v_mov_b64_e32 v[158:159], v[102:103]
	v_mov_b64_e32 v[162:163], v[90:91]
	v_or_b32_e32 v200, 16, v199
	v_cmp_ne_u32_e64 s[8:9], 1, v96
	s_andn2_b64 vcc, exec, s[10:11]
	v_mov_b64_e32 v[152:153], v[120:121]
	v_mov_b64_e32 v[148:149], v[112:113]
	v_mov_b64_e32 v[156:157], v[100:101]
	v_mov_b64_e32 v[160:161], v[88:89]
	s_cbranch_vccnz .LBB0_611
	v_pk_mul_f32 v[148:149], v[122:123], v[122:123]
	v_pk_mul_f32 v[150:151], v[120:121], v[120:121]
	v_mul_f32_e32 v96, v100, v100
	v_pk_mov_b32 v[152:153], v[150:151], v[148:149] op_sel:[1,0]
	v_mov_b32_e32 v151, v149
	v_pk_add_f32 v[148:149], v[152:153], v[150:151]
	v_pk_mul_f32 v[150:151], v[114:115], v[114:115]
	v_pk_mul_f32 v[152:153], v[112:113], v[112:113]
	v_pk_add_f32 v[148:149], v[148:149], v[148:149] op_sel_hi:[0,1]
	v_pk_mov_b32 v[154:155], v[152:153], v[150:151] op_sel:[1,0]
	v_mov_b32_e32 v153, v151
	v_pk_add_f32 v[150:151], v[154:155], v[152:153]
	v_pk_fma_f32 v[152:153], v[100:101], v[100:101], v[96:97] op_sel_hi:[1,1,0]
	v_mul_f32_e32 v96, v102, v102
	v_pk_add_f32 v[150:151], v[150:151], v[150:151] op_sel_hi:[0,1]
	v_pk_fma_f32 v[154:155], v[102:103], v[102:103], v[96:97] op_sel_hi:[1,1,0]
	v_mul_f32_e32 v152, v88, v88
	v_mul_f32_e32 v154, v89, v89
	v_mul_f32_e32 v150, v90, v90
	v_mul_f32_e32 v148, v91, v91
	v_pk_add_f32 v[152:153], v[152:153], v[154:155]
	v_pk_add_f32 v[148:149], v[150:151], v[148:149]
	s_nop 0
	v_pk_add_f32 v[148:149], v[152:153], v[148:149]
	s_nop 0
	v_add_f32_e32 v96, v148, v149
	ds_bpermute_b32 v148, v194, v96
	s_waitcnt lgkmcnt(0)
	v_add_f32_e32 v96, v96, v148
	ds_bpermute_b32 v148, v195, v96
	s_waitcnt lgkmcnt(0)
	v_add_f32_e32 v96, v96, v148
	v_fmamk_f32 v96, v96, 0x3c800000, v185
	v_mul_f32_e32 v148, 0x4f800000, v96
	v_cmp_gt_f32_e32 vcc, s65, v96
	s_nop 1
	v_cndmask_b32_e32 v96, v96, v148, vcc
	v_sqrt_f32_e32 v148, v96
	s_nop 0
	v_add_u32_e32 v149, -1, v148
	v_fma_f32 v150, -v149, v148, v96
	v_cmp_ge_f32_e64 s[12:13], 0, v150
	v_add_u32_e32 v150, 1, v148
	s_nop 0
	v_cndmask_b32_e64 v149, v148, v149, s[12:13]
	v_fma_f32 v148, -v150, v148, v96
	v_cmp_lt_f32_e64 s[12:13], 0, v148
	s_nop 1
	v_cndmask_b32_e64 v148, v149, v150, s[12:13]
	v_mul_f32_e32 v149, 0x37800000, v148
	v_cndmask_b32_e32 v148, v148, v149, vcc
	v_cmp_class_f32_e32 vcc, v96, v183
	s_nop 1
	v_cndmask_b32_e32 v96, v148, v96, vcc
	v_div_scale_f32 v148, s[10:11], v96, v96, 1.0
	v_rcp_f32_e32 v149, v148
	s_nop 0
	v_fma_f32 v150, -v148, v149, 1.0
	v_fmac_f32_e32 v149, v150, v149
	v_div_scale_f32 v150, vcc, 1.0, v96, 1.0
	v_mul_f32_e32 v151, v150, v149
	v_fma_f32 v152, -v148, v151, v150
	v_fmac_f32_e32 v151, v152, v149
	v_fma_f32 v148, -v148, v151, v150
	v_div_fmas_f32 v148, v148, v149, v151
	v_div_fixup_f32 v96, v148, v96, 1.0
	v_pk_mul_f32 v[148:149], v[120:121], v[96:97] op_sel_hi:[1,0]
	v_pk_mul_f32 v[150:151], v[122:123], v[96:97] op_sel_hi:[1,0]
	s_waitcnt vmcnt(2)
	v_pk_mul_f32 v[152:153], v[144:145], v[148:149]
	v_pk_mul_f32 v[154:155], v[146:147], v[150:151]
	v_pk_mul_f32 v[148:149], v[112:113], v[96:97] op_sel_hi:[1,0]
	v_pk_mul_f32 v[150:151], v[114:115], v[96:97] op_sel_hi:[1,0]
	v_pk_mul_f32 v[156:157], v[100:101], v[96:97] op_sel_hi:[1,0]
	v_pk_mul_f32 v[158:159], v[102:103], v[96:97] op_sel_hi:[1,0]
	v_pk_mul_f32 v[162:163], v[88:89], v[96:97] op_sel_hi:[1,0]
	v_pk_mul_f32 v[160:161], v[90:91], v[96:97] op_sel_hi:[1,0]
	v_pk_mul_f32 v[150:151], v[142:143], v[150:151]
	v_pk_mul_f32 v[148:149], v[140:141], v[148:149]
	v_pk_mul_f32 v[158:159], v[138:139], v[158:159]
	v_pk_mul_f32 v[156:157], v[136:137], v[156:157]
	v_pk_mul_f32 v[160:161], v[134:135], v[160:161]
	s_and_b64 vcc, exec, s[6:7]
	v_pk_mul_f32 v[192:193], v[132:133], v[162:163]
	s_cbranch_vccnz .LBB0_610
	v_pk_mul_f32 v[210:211], v[156:157], v[230:231]
	v_pk_mul_f32 v[162:163], v[158:159], v[232:233]
	v_pk_fma_f32 v[234:235], v[152:153], v[206:207], v[210:211] neg_lo:[0,0,1] neg_hi:[0,0,1]
	v_pk_mul_f32 v[152:153], v[152:153], v[230:231]
	v_pk_fma_f32 v[236:237], v[154:155], v[208:209], v[162:163] neg_lo:[0,0,1] neg_hi:[0,0,1]
	v_pk_mul_f32 v[154:155], v[154:155], v[232:233]
	v_pk_fma_f32 v[156:157], v[156:157], v[206:207], v[152:153]
	v_pk_mul_f32 v[152:153], v[160:161], v[228:229]
	v_pk_mul_f32 v[162:163], v[192:193], v[226:227]
	v_pk_fma_f32 v[158:159], v[158:159], v[208:209], v[154:155]
	v_pk_fma_f32 v[154:155], v[150:151], v[204:205], v[152:153] neg_lo:[0,0,1] neg_hi:[0,0,1]
	v_pk_fma_f32 v[152:153], v[148:149], v[202:203], v[162:163] neg_lo:[0,0,1] neg_hi:[0,0,1]
	v_pk_mul_f32 v[150:151], v[150:151], v[228:229]
	v_pk_mul_f32 v[148:149], v[148:149], v[226:227]
	v_pk_fma_f32 v[160:161], v[160:161], v[204:205], v[150:151]
	v_pk_fma_f32 v[192:193], v[192:193], v[202:203], v[148:149]
	v_mov_b64_e32 v[148:149], v[152:153]
	v_mov_b64_e32 v[150:151], v[154:155]
	v_mov_b64_e32 v[152:153], v[234:235]
	v_mov_b64_e32 v[154:155], v[236:237]

; DI u32x4 pk8(const f32x4& a, const f32x4& b) { u32x4 w; w.x = pk2(a[0], a[1]); w.y = pk2(a[2], a[3]); w.z = pk2(b[0], b[1]); w.w = pk2(b[2], b[3]); return w; }
; DI float shx(float v, int m, int lane) { return __int_as_float(__builtin_amdgcn_ds_bpermute((lane ^ m) << 2, __float_as_int(v))); }
; #define FOR_AI_M _Pragma("unroll") for (int ai = 0; ai < 2; ++ai) _Pragma("unroll") for (int m = 0; m < 4; ++m)
; #define ROW_FENCE asm volatile("" ::: "memory")
;     DI void operator()(Acc& acc, const Unit& u, int wr, int wc, int fr, int fq) const {
;     ...
;         FOR_AI_M { const int r = row0 + EPI_ROWS(ai, m);
;             f32x4 x[2][2];
; #pragma unroll
;             for (int bj = 0; bj < 2; ++bj) { x[bj][0] = acc[ai][bj][m][0]; x[bj][1] = acc[ai][bj][m][1]; }
;             if (!is_v) {
;                 float s = 0.f;
; #pragma unroll
;                 for (int bj = 0; bj < 2; ++bj)
; #pragma unroll
;                     for (int n = 0; n < 2; ++n) s += (x[bj][n][0] * x[bj][n][0] + x[bj][n][1] * x[bj][n][1]) + (x[bj][n][2] * x[bj][n][2] + x[bj][n][3] * x[bj][n][3]);
;                 s += shx(s, 16, fr + 16 * fq); s += shx(s, 32, fr + 16 * fq);
;                 const float rstd = 1.f / sqrtf(s * (1.f / 64.f) + EPS);
; #pragma unroll
;                 for (int bj = 0; bj < 2; ++bj)
; #pragma unroll
;                     for (int n = 0; n < 2; ++n) x[bj][n] = x[bj][n] * rstd * gv[bj][n];
;                 if (rope) {
;                     const float* rr = rg + (size_t)(r & 2047) * 64 + 8 * fq;
; #pragma unroll
;                     for (int n = 0; n < 2; ++n) { const f32x4 cs = *(const f32x4*)(rr + 4 * n), sn = *(const f32x4*)(rr + 32 + 4 * n);
;                         const f32x4 x1 = x[0][n], x2 = x[1][n]; x[0][n] = x1 * cs - x2 * sn; x[1][n] = x1 * sn + x2 * cs; }
;                 }
; #pragma unroll
;                 for (int bj = 0; bj < 2; ++bj)
; #pragma unroll
;                     for (int n = 0; n < 2; ++n) x[bj][n] = x[bj][n] * qs;
;             }
; #pragma unroll
;             for (int bj = 0; bj < 2; ++bj) *(u32x4*)(dst + (size_t)r * ld + colb + 32 * bj + 8 * fq) = pk8(x[bj][0], x[bj][1]);
;             if (m == 3) ROW_FENCE;
.LBB0_611:
	v_mad_i64_i32 v[192:193], s[10:11], s42, v200, 0
	v_lshl_add_u64 v[192:193], v[192:193], 1, v[98:99]
	v_cvt_pk_bf16_f32 v152, v152, v153
	v_cvt_pk_bf16_f32 v153, v154, v155
	v_cvt_pk_bf16_f32 v154, v148, v149
	v_cvt_pk_bf16_f32 v155, v150, v151
	v_cvt_pk_bf16_f32 v148, v156, v157
	v_cvt_pk_bf16_f32 v149, v158, v159
	v_cvt_pk_bf16_f32 v150, v160, v161
	v_cvt_pk_bf16_f32 v151, v162, v163
	v_add_u32_e32 v248, 0x2000, v251
	v_lshl_add_u64 v[252:253], v[176:177], 0, v[248:249]
	global_load_dwordx4 v[202:205], v[252:253], off offset:16
	global_load_dwordx4 v[206:209], v[252:253], off
	global_load_dwordx4 v[226:229], v[252:253], off offset:144
	global_load_dwordx4 v[230:233], v[252:253], off offset:128
	global_store_dwordx4 v[192:193], v[152:155], off sc1
	global_store_dwordx4 v[192:193], v[148:151], off offset:64 sc1
	v_mov_b64_e32 v[158:159], v[82:83]
	v_mov_b64_e32 v[154:155], v[106:107]
	v_mov_b64_e32 v[150:151], v[94:95]
	v_mov_b64_e32 v[162:163], v[74:75]
	v_or_b32_e32 v200, 32, v199
	s_and_b64 vcc, exec, s[8:9]
	v_mov_b64_e32 v[152:153], v[104:105]
	v_mov_b64_e32 v[148:149], v[92:93]
	v_mov_b64_e32 v[156:157], v[80:81]
	v_mov_b64_e32 v[160:161], v[72:73]
	s_cbranch_vccnz .LBB0_615
	v_pk_mul_f32 v[148:149], v[106:107], v[106:107]
	v_pk_mul_f32 v[150:151], v[104:105], v[104:105]
	v_mul_f32_e32 v96, v80, v80
	v_pk_mov_b32 v[152:153], v[150:151], v[148:149] op_sel:[1,0]
	v_mov_b32_e32 v151, v149
	v_pk_add_f32 v[148:149], v[152:153], v[150:151]
	v_pk_mul_f32 v[150:151], v[94:95], v[94:95]
	v_pk_mul_f32 v[152:153], v[92:93], v[92:93]
	v_pk_add_f32 v[148:149], v[148:149], v[148:149] op_sel_hi:[0,1]
	v_pk_mov_b32 v[154:155], v[152:153], v[150:151] op_sel:[1,0]
	v_mov_b32_e32 v153, v151
	v_pk_add_f32 v[150:151], v[154:155], v[152:153]
	v_pk_fma_f32 v[152:153], v[80:81], v[80:81], v[96:97] op_sel_hi:[1,1,0]
	v_mul_f32_e32 v96, v82, v82
	v_pk_add_f32 v[150:151], v[150:151], v[150:151] op_sel_hi:[0,1]
	v_pk_fma_f32 v[154:155], v[82:83], v[82:83], v[96:97] op_sel_hi:[1,1,0]
	v_mul_f32_e32 v152, v72, v72
	v_mul_f32_e32 v154, v73, v73
	v_mul_f32_e32 v150, v74, v74
	v_mul_f32_e32 v148, v75, v75
	v_pk_add_f32 v[152:153], v[152:153], v[154:155]
	v_pk_add_f32 v[148:149], v[150:151], v[148:149]
	s_nop 0
	v_pk_add_f32 v[148:149], v[152:153], v[148:149]
	s_nop 0
	v_add_f32_e32 v96, v148, v149
	ds_bpermute_b32 v148, v194, v96
	s_waitcnt lgkmcnt(0)
	v_add_f32_e32 v96, v96, v148
	ds_bpermute_b32 v148, v195, v96
	s_waitcnt lgkmcnt(0)
	v_add_f32_e32 v96, v96, v148
	v_fmamk_f32 v96, v96, 0x3c800000, v185
	v_mul_f32_e32 v148, 0x4f800000, v96
	v_cmp_gt_f32_e32 vcc, s65, v96
	s_nop 1
	v_cndmask_b32_e32 v96, v96, v148, vcc
	v_sqrt_f32_e32 v148, v96
	s_nop 0
	v_add_u32_e32 v149, -1, v148
	v_fma_f32 v150, -v149, v148, v96
	v_cmp_ge_f32_e64 s[12:13], 0, v150
	v_add_u32_e32 v150, 1, v148
	s_nop 0
	v_cndmask_b32_e64 v149, v148, v149, s[12:13]
	v_fma_f32 v148, -v150, v148, v96
	v_cmp_lt_f32_e64 s[12:13], 0, v148
	s_nop 1
	v_cndmask_b32_e64 v148, v149, v150, s[12:13]
	v_mul_f32_e32 v149, 0x37800000, v148
	v_cndmask_b32_e32 v148, v148, v149, vcc
	v_cmp_class_f32_e32 vcc, v96, v183
	s_nop 1
	v_cndmask_b32_e32 v96, v148, v96, vcc
	v_div_scale_f32 v148, s[10:11], v96, v96, 1.0
	v_rcp_f32_e32 v149, v148
	s_nop 0
	v_fma_f32 v150, -v148, v149, 1.0
	v_fmac_f32_e32 v149, v150, v149
	v_div_scale_f32 v150, vcc, 1.0, v96, 1.0
	v_mul_f32_e32 v151, v150, v149
	v_fma_f32 v152, -v148, v151, v150
	v_fmac_f32_e32 v151, v152, v149
	v_fma_f32 v148, -v148, v151, v150
	v_div_fmas_f32 v148, v148, v149, v151
	v_div_fixup_f32 v96, v148, v96, 1.0
	v_pk_mul_f32 v[148:149], v[104:105], v[96:97] op_sel_hi:[1,0]
	v_pk_mul_f32 v[150:151], v[106:107], v[96:97] op_sel_hi:[1,0]
	s_waitcnt vmcnt(2)
	v_pk_mul_f32 v[152:153], v[144:145], v[148:149]
	v_pk_mul_f32 v[154:155], v[146:147], v[150:151]
	v_pk_mul_f32 v[148:149], v[92:93], v[96:97] op_sel_hi:[1,0]
	v_pk_mul_f32 v[150:151], v[94:95], v[96:97] op_sel_hi:[1,0]
	v_pk_mul_f32 v[156:157], v[80:81], v[96:97] op_sel_hi:[1,0]
	v_pk_mul_f32 v[158:159], v[82:83], v[96:97] op_sel_hi:[1,0]
	v_pk_mul_f32 v[162:163], v[72:73], v[96:97] op_sel_hi:[1,0]
	v_pk_mul_f32 v[160:161], v[74:75], v[96:97] op_sel_hi:[1,0]
	v_pk_mul_f32 v[150:151], v[142:143], v[150:151]
	v_pk_mul_f32 v[148:149], v[140:141], v[148:149]
	v_pk_mul_f32 v[158:159], v[138:139], v[158:159]
	v_pk_mul_f32 v[156:157], v[136:137], v[156:157]
	v_pk_mul_f32 v[160:161], v[134:135], v[160:161]
	s_and_b64 vcc, exec, s[6:7]
	v_pk_mul_f32 v[192:193], v[132:133], v[162:163]
	s_cbranch_vccnz .LBB0_614
	v_pk_mul_f32 v[210:211], v[156:157], v[230:231]
	v_pk_mul_f32 v[162:163], v[158:159], v[232:233]
	v_pk_fma_f32 v[234:235], v[152:153], v[206:207], v[210:211] neg_lo:[0,0,1] neg_hi:[0,0,1]
	v_pk_mul_f32 v[152:153], v[152:153], v[230:231]
	v_pk_fma_f32 v[236:237], v[154:155], v[208:209], v[162:163] neg_lo:[0,0,1] neg_hi:[0,0,1]
	v_pk_mul_f32 v[154:155], v[154:155], v[232:233]
	v_pk_fma_f32 v[156:157], v[156:157], v[206:207], v[152:153]
	v_pk_mul_f32 v[152:153], v[160:161], v[228:229]
	v_pk_mul_f32 v[162:163], v[192:193], v[226:227]
	v_pk_fma_f32 v[158:159], v[158:159], v[208:209], v[154:155]
	v_pk_fma_f32 v[154:155], v[150:151], v[204:205], v[152:153] neg_lo:[0,0,1] neg_hi:[0,0,1]
	v_pk_fma_f32 v[152:153], v[148:149], v[202:203], v[162:163] neg_lo:[0,0,1] neg_hi:[0,0,1]
	v_pk_mul_f32 v[150:151], v[150:151], v[228:229]
	v_pk_mul_f32 v[148:149], v[148:149], v[226:227]
	v_pk_fma_f32 v[160:161], v[160:161], v[204:205], v[150:151]
	v_pk_fma_f32 v[192:193], v[192:193], v[202:203], v[148:149]
	v_mov_b64_e32 v[148:149], v[152:153]
	v_mov_b64_e32 v[150:151], v[154:155]
	v_mov_b64_e32 v[152:153], v[234:235]
	v_mov_b64_e32 v[154:155], v[236:237]

; DI u32x4 pk8(const f32x4& a, const f32x4& b) { u32x4 w; w.x = pk2(a[0], a[1]); w.y = pk2(a[2], a[3]); w.z = pk2(b[0], b[1]); w.w = pk2(b[2], b[3]); return w; }
; DI float shx(float v, int m, int lane) { return __int_as_float(__builtin_amdgcn_ds_bpermute((lane ^ m) << 2, __float_as_int(v))); }
; #define FOR_AI_M _Pragma("unroll") for (int ai = 0; ai < 2; ++ai) _Pragma("unroll") for (int m = 0; m < 4; ++m)
; #define ROW_FENCE asm volatile("" ::: "memory")
;     DI void operator()(Acc& acc, const Unit& u, int wr, int wc, int fr, int fq) const {
;     ...
;         FOR_AI_M { const int r = row0 + EPI_ROWS(ai, m);
;             f32x4 x[2][2];
; #pragma unroll
;             for (int bj = 0; bj < 2; ++bj) { x[bj][0] = acc[ai][bj][m][0]; x[bj][1] = acc[ai][bj][m][1]; }
;             if (!is_v) {
;                 float s = 0.f;
; #pragma unroll
;                 for (int bj = 0; bj < 2; ++bj)
; #pragma unroll
;                     for (int n = 0; n < 2; ++n) s += (x[bj][n][0] * x[bj][n][0] + x[bj][n][1] * x[bj][n][1]) + (x[bj][n][2] * x[bj][n][2] + x[bj][n][3] * x[bj][n][3]);
;                 s += shx(s, 16, fr + 16 * fq); s += shx(s, 32, fr + 16 * fq);
;                 const float rstd = 1.f / sqrtf(s * (1.f / 64.f) + EPS);
; #pragma unroll
;                 for (int bj = 0; bj < 2; ++bj)
; #pragma unroll
;                     for (int n = 0; n < 2; ++n) x[bj][n] = x[bj][n] * rstd * gv[bj][n];
;                 if (rope) {
;                     const float* rr = rg + (size_t)(r & 2047) * 64 + 8 * fq;
; #pragma unroll
;                     for (int n = 0; n < 2; ++n) { const f32x4 cs = *(const f32x4*)(rr + 4 * n), sn = *(const f32x4*)(rr + 32 + 4 * n);
;                         const f32x4 x1 = x[0][n], x2 = x[1][n]; x[0][n] = x1 * cs - x2 * sn; x[1][n] = x1 * sn + x2 * cs; }
;                 }
; #pragma unroll
;                 for (int bj = 0; bj < 2; ++bj)
; #pragma unroll
;                     for (int n = 0; n < 2; ++n) x[bj][n] = x[bj][n] * qs;
;             }
; #pragma unroll
;             for (int bj = 0; bj < 2; ++bj) *(u32x4*)(dst + (size_t)r * ld + colb + 32 * bj + 8 * fq) = pk8(x[bj][0], x[bj][1]);
;             if (m == 3) ROW_FENCE;
.LBB0_615:
	v_mad_i64_i32 v[192:193], s[10:11], s42, v200, 0
	v_lshl_add_u64 v[192:193], v[192:193], 1, v[98:99]
	v_cvt_pk_bf16_f32 v152, v152, v153
	v_cvt_pk_bf16_f32 v153, v154, v155
	v_cvt_pk_bf16_f32 v154, v148, v149
	v_cvt_pk_bf16_f32 v155, v150, v151
	v_cvt_pk_bf16_f32 v148, v156, v157
	v_cvt_pk_bf16_f32 v149, v158, v159
	v_cvt_pk_bf16_f32 v150, v160, v161
	v_cvt_pk_bf16_f32 v151, v162, v163
	v_add_u32_e32 v248, 0x3000, v251
	v_lshl_add_u64 v[252:253], v[176:177], 0, v[248:249]
	global_load_dwordx4 v[202:205], v[252:253], off offset:16
	global_load_dwordx4 v[206:209], v[252:253], off
	global_load_dwordx4 v[226:229], v[252:253], off offset:144
	global_load_dwordx4 v[230:233], v[252:253], off offset:128
	global_store_dwordx4 v[192:193], v[152:155], off sc1
	global_store_dwordx4 v[192:193], v[148:151], off offset:64 sc1
	v_mov_b64_e32 v[158:159], v[70:71]
	v_mov_b64_e32 v[154:155], v[86:87]
	v_mov_b64_e32 v[150:151], v[78:79]
	v_mov_b64_e32 v[162:163], v[66:67]
	v_or_b32_e32 v200, 48, v199
	s_and_b64 vcc, exec, s[8:9]
	v_mov_b64_e32 v[152:153], v[84:85]
	v_mov_b64_e32 v[148:149], v[76:77]
	v_mov_b64_e32 v[156:157], v[68:69]
	v_mov_b64_e32 v[160:161], v[64:65]
	s_cbranch_vccnz .LBB0_619
	v_pk_mul_f32 v[148:149], v[86:87], v[86:87]
	v_pk_mul_f32 v[150:151], v[84:85], v[84:85]
	v_mul_f32_e32 v96, v68, v68
	v_pk_mov_b32 v[152:153], v[150:151], v[148:149] op_sel:[1,0]
	v_mov_b32_e32 v151, v149
	v_pk_add_f32 v[148:149], v[152:153], v[150:151]
	v_pk_mul_f32 v[150:151], v[78:79], v[78:79]
	v_pk_mul_f32 v[152:153], v[76:77], v[76:77]
	v_pk_add_f32 v[148:149], v[148:149], v[148:149] op_sel_hi:[0,1]
	v_pk_mov_b32 v[154:155], v[152:153], v[150:151] op_sel:[1,0]
	v_mov_b32_e32 v153, v151
	v_pk_add_f32 v[150:151], v[154:155], v[152:153]
	v_pk_fma_f32 v[152:153], v[68:69], v[68:69], v[96:97] op_sel_hi:[1,1,0]
	v_mul_f32_e32 v96, v70, v70
	v_pk_add_f32 v[150:151], v[150:151], v[150:151] op_sel_hi:[0,1]
	v_pk_fma_f32 v[154:155], v[70:71], v[70:71], v[96:97] op_sel_hi:[1,1,0]
	v_mul_f32_e32 v152, v64, v64
	v_mul_f32_e32 v154, v65, v65
	v_mul_f32_e32 v150, v66, v66
	v_mul_f32_e32 v148, v67, v67
	v_pk_add_f32 v[152:153], v[152:153], v[154:155]
	v_pk_add_f32 v[148:149], v[150:151], v[148:149]
	s_nop 0
	v_pk_add_f32 v[148:149], v[152:153], v[148:149]
	s_nop 0
	v_add_f32_e32 v96, v148, v149
	ds_bpermute_b32 v148, v194, v96
	s_waitcnt lgkmcnt(0)
	v_add_f32_e32 v96, v96, v148
	ds_bpermute_b32 v148, v195, v96
	s_waitcnt lgkmcnt(0)
	v_add_f32_e32 v96, v96, v148
	v_fmamk_f32 v96, v96, 0x3c800000, v185
	v_mul_f32_e32 v148, 0x4f800000, v96
	v_cmp_gt_f32_e32 vcc, s65, v96
	s_nop 1
	v_cndmask_b32_e32 v96, v96, v148, vcc
	v_sqrt_f32_e32 v148, v96
	s_nop 0
	v_add_u32_e32 v149, -1, v148
	v_fma_f32 v150, -v149, v148, v96
	v_cmp_ge_f32_e64 s[12:13], 0, v150
	v_add_u32_e32 v150, 1, v148
	s_nop 0
	v_cndmask_b32_e64 v149, v148, v149, s[12:13]
	v_fma_f32 v148, -v150, v148, v96
	v_cmp_lt_f32_e64 s[12:13], 0, v148
	s_nop 1
	v_cndmask_b32_e64 v148, v149, v150, s[12:13]
	v_mul_f32_e32 v149, 0x37800000, v148
	v_cndmask_b32_e32 v148, v148, v149, vcc
	v_cmp_class_f32_e32 vcc, v96, v183
	s_nop 1
	v_cndmask_b32_e32 v96, v148, v96, vcc
	v_div_scale_f32 v148, s[10:11], v96, v96, 1.0
	v_rcp_f32_e32 v149, v148
	s_nop 0
	v_fma_f32 v150, -v148, v149, 1.0
	v_fmac_f32_e32 v149, v150, v149
	v_div_scale_f32 v150, vcc, 1.0, v96, 1.0
	v_mul_f32_e32 v151, v150, v149
	v_fma_f32 v152, -v148, v151, v150
	v_fmac_f32_e32 v151, v152, v149
	v_fma_f32 v148, -v148, v151, v150
	v_div_fmas_f32 v148, v148, v149, v151
	v_div_fixup_f32 v96, v148, v96, 1.0
	v_pk_mul_f32 v[148:149], v[84:85], v[96:97] op_sel_hi:[1,0]
	v_pk_mul_f32 v[150:151], v[86:87], v[96:97] op_sel_hi:[1,0]
	s_waitcnt vmcnt(2)
	v_pk_mul_f32 v[152:153], v[144:145], v[148:149]
	v_pk_mul_f32 v[154:155], v[146:147], v[150:151]
	v_pk_mul_f32 v[148:149], v[76:77], v[96:97] op_sel_hi:[1,0]
	v_pk_mul_f32 v[150:151], v[78:79], v[96:97] op_sel_hi:[1,0]
	v_pk_mul_f32 v[156:157], v[68:69], v[96:97] op_sel_hi:[1,0]
	v_pk_mul_f32 v[158:159], v[70:71], v[96:97] op_sel_hi:[1,0]
	v_pk_mul_f32 v[162:163], v[64:65], v[96:97] op_sel_hi:[1,0]
	v_pk_mul_f32 v[160:161], v[66:67], v[96:97] op_sel_hi:[1,0]
	v_pk_mul_f32 v[150:151], v[142:143], v[150:151]
	v_pk_mul_f32 v[148:149], v[140:141], v[148:149]
	v_pk_mul_f32 v[158:159], v[138:139], v[158:159]
	v_pk_mul_f32 v[156:157], v[136:137], v[156:157]
	v_pk_mul_f32 v[160:161], v[134:135], v[160:161]
	s_and_b64 vcc, exec, s[6:7]
	v_pk_mul_f32 v[192:193], v[132:133], v[162:163]
	s_cbranch_vccnz .LBB0_618
	v_pk_mul_f32 v[210:211], v[156:157], v[230:231]
	v_pk_mul_f32 v[162:163], v[158:159], v[232:233]
	v_pk_fma_f32 v[234:235], v[152:153], v[206:207], v[210:211] neg_lo:[0,0,1] neg_hi:[0,0,1]
	v_pk_mul_f32 v[152:153], v[152:153], v[230:231]
	v_pk_fma_f32 v[236:237], v[154:155], v[208:209], v[162:163] neg_lo:[0,0,1] neg_hi:[0,0,1]
	v_pk_mul_f32 v[154:155], v[154:155], v[232:233]
	v_pk_fma_f32 v[156:157], v[156:157], v[206:207], v[152:153]
	v_pk_mul_f32 v[152:153], v[160:161], v[228:229]
	v_pk_mul_f32 v[162:163], v[192:193], v[226:227]
	v_pk_fma_f32 v[158:159], v[158:159], v[208:209], v[154:155]
	v_pk_fma_f32 v[154:155], v[150:151], v[204:205], v[152:153] neg_lo:[0,0,1] neg_hi:[0,0,1]
	v_pk_fma_f32 v[152:153], v[148:149], v[202:203], v[162:163] neg_lo:[0,0,1] neg_hi:[0,0,1]
	v_pk_mul_f32 v[150:151], v[150:151], v[228:229]
	v_pk_mul_f32 v[148:149], v[148:149], v[226:227]
	v_pk_fma_f32 v[160:161], v[160:161], v[204:205], v[150:151]
	v_pk_fma_f32 v[192:193], v[192:193], v[202:203], v[148:149]
	v_mov_b64_e32 v[148:149], v[152:153]
	v_mov_b64_e32 v[150:151], v[154:155]
	v_mov_b64_e32 v[152:153], v[234:235]
	v_mov_b64_e32 v[154:155], v[236:237]

; DI u32x4 pk8(const f32x4& a, const f32x4& b) { u32x4 w; w.x = pk2(a[0], a[1]); w.y = pk2(a[2], a[3]); w.z = pk2(b[0], b[1]); w.w = pk2(b[2], b[3]); return w; }
; DI float shx(float v, int m, int lane) { return __int_as_float(__builtin_amdgcn_ds_bpermute((lane ^ m) << 2, __float_as_int(v))); }
; #define FOR_AI_M _Pragma("unroll") for (int ai = 0; ai < 2; ++ai) _Pragma("unroll") for (int m = 0; m < 4; ++m)
; #define ROW_FENCE asm volatile("" ::: "memory")
;     DI void operator()(Acc& acc, const Unit& u, int wr, int wc, int fr, int fq) const {
;     ...
;         FOR_AI_M { const int r = row0 + EPI_ROWS(ai, m);
;             f32x4 x[2][2];
; #pragma unroll
;             for (int bj = 0; bj < 2; ++bj) { x[bj][0] = acc[ai][bj][m][0]; x[bj][1] = acc[ai][bj][m][1]; }
;             if (!is_v) {
;                 float s = 0.f;
; #pragma unroll
;                 for (int bj = 0; bj < 2; ++bj)
; #pragma unroll
;                     for (int n = 0; n < 2; ++n) s += (x[bj][n][0] * x[bj][n][0] + x[bj][n][1] * x[bj][n][1]) + (x[bj][n][2] * x[bj][n][2] + x[bj][n][3] * x[bj][n][3]);
;                 s += shx(s, 16, fr + 16 * fq); s += shx(s, 32, fr + 16 * fq);
;                 const float rstd = 1.f / sqrtf(s * (1.f / 64.f) + EPS);
; #pragma unroll
;                 for (int bj = 0; bj < 2; ++bj)
; #pragma unroll
;                     for (int n = 0; n < 2; ++n) x[bj][n] = x[bj][n] * rstd * gv[bj][n];
;                 if (rope) {
;                     const float* rr = rg + (size_t)(r & 2047) * 64 + 8 * fq;
; #pragma unroll
;                     for (int n = 0; n < 2; ++n) { const f32x4 cs = *(const f32x4*)(rr + 4 * n), sn = *(const f32x4*)(rr + 32 + 4 * n);
;                         const f32x4 x1 = x[0][n], x2 = x[1][n]; x[0][n] = x1 * cs - x2 * sn; x[1][n] = x1 * sn + x2 * cs; }
;                 }
; #pragma unroll
;                 for (int bj = 0; bj < 2; ++bj)
; #pragma unroll
;                     for (int n = 0; n < 2; ++n) x[bj][n] = x[bj][n] * qs;
;             }
; #pragma unroll
;             for (int bj = 0; bj < 2; ++bj) *(u32x4*)(dst + (size_t)r * ld + colb + 32 * bj + 8 * fq) = pk8(x[bj][0], x[bj][1]);
;             if (m == 3) ROW_FENCE;
.LBB0_619:
	v_mad_i64_i32 v[192:193], s[10:11], s42, v200, 0
	v_lshl_add_u64 v[192:193], v[192:193], 1, v[98:99]
	v_cvt_pk_bf16_f32 v152, v152, v153
	v_cvt_pk_bf16_f32 v153, v154, v155
	v_cvt_pk_bf16_f32 v154, v148, v149
	v_cvt_pk_bf16_f32 v155, v150, v151
	v_cvt_pk_bf16_f32 v148, v156, v157
	v_cvt_pk_bf16_f32 v149, v158, v159
	v_cvt_pk_bf16_f32 v150, v160, v161
	v_cvt_pk_bf16_f32 v151, v162, v163
	v_add_u32_e32 v248, 0x8000, v251
	v_lshl_add_u64 v[252:253], v[176:177], 0, v[248:249]
	global_load_dwordx4 v[202:205], v[252:253], off offset:16
	global_load_dwordx4 v[206:209], v[252:253], off
	global_load_dwordx4 v[226:229], v[252:253], off offset:144
	global_load_dwordx4 v[230:233], v[252:253], off offset:128
	global_store_dwordx4 v[192:193], v[152:155], off sc1
	global_store_dwordx4 v[192:193], v[148:151], off offset:64 sc1
	v_mov_b64_e32 v[158:159], v[50:51]
	v_mov_b64_e32 v[154:155], v[62:63]
	v_mov_b64_e32 v[150:151], v[58:59]
	v_mov_b64_e32 v[162:163], v[42:43]
	v_add_u32_e32 v200, 0x80, v199
	s_and_b64 vcc, exec, s[8:9]
	v_mov_b64_e32 v[152:153], v[60:61]
	v_mov_b64_e32 v[148:149], v[56:57]
	v_mov_b64_e32 v[156:157], v[48:49]
	v_mov_b64_e32 v[160:161], v[40:41]
	s_cbranch_vccnz .LBB0_623
	v_pk_mul_f32 v[148:149], v[62:63], v[62:63]
	v_pk_mul_f32 v[150:151], v[60:61], v[60:61]
	v_mul_f32_e32 v96, v48, v48
	v_pk_mov_b32 v[152:153], v[150:151], v[148:149] op_sel:[1,0]
	v_mov_b32_e32 v151, v149
	v_pk_add_f32 v[148:149], v[152:153], v[150:151]
	v_pk_mul_f32 v[150:151], v[58:59], v[58:59]
	v_pk_mul_f32 v[152:153], v[56:57], v[56:57]
	v_pk_add_f32 v[148:149], v[148:149], v[148:149] op_sel_hi:[0,1]
	v_pk_mov_b32 v[154:155], v[152:153], v[150:151] op_sel:[1,0]
	v_mov_b32_e32 v153, v151
	v_pk_add_f32 v[150:151], v[154:155], v[152:153]
	v_pk_fma_f32 v[152:153], v[48:49], v[48:49], v[96:97] op_sel_hi:[1,1,0]
	v_mul_f32_e32 v96, v50, v50
	v_pk_add_f32 v[150:151], v[150:151], v[150:151] op_sel_hi:[0,1]
	v_pk_fma_f32 v[154:155], v[50:51], v[50:51], v[96:97] op_sel_hi:[1,1,0]
	v_mul_f32_e32 v152, v40, v40
	v_mul_f32_e32 v154, v41, v41
	v_mul_f32_e32 v150, v42, v42
	v_mul_f32_e32 v148, v43, v43
	v_pk_add_f32 v[152:153], v[152:153], v[154:155]
	v_pk_add_f32 v[148:149], v[150:151], v[148:149]
	s_nop 0
	v_pk_add_f32 v[148:149], v[152:153], v[148:149]
	s_nop 0
	v_add_f32_e32 v96, v148, v149
	ds_bpermute_b32 v148, v194, v96
	s_waitcnt lgkmcnt(0)
	v_add_f32_e32 v96, v96, v148
	ds_bpermute_b32 v148, v195, v96
	s_waitcnt lgkmcnt(0)
	v_add_f32_e32 v96, v96, v148
	v_fmamk_f32 v96, v96, 0x3c800000, v185
	v_mul_f32_e32 v148, 0x4f800000, v96
	v_cmp_gt_f32_e32 vcc, s65, v96
	s_nop 1
	v_cndmask_b32_e32 v96, v96, v148, vcc
	v_sqrt_f32_e32 v148, v96
	s_nop 0
	v_add_u32_e32 v149, -1, v148
	v_fma_f32 v150, -v149, v148, v96
	v_cmp_ge_f32_e64 s[12:13], 0, v150
	v_add_u32_e32 v150, 1, v148
	s_nop 0
	v_cndmask_b32_e64 v149, v148, v149, s[12:13]
	v_fma_f32 v148, -v150, v148, v96
	v_cmp_lt_f32_e64 s[12:13], 0, v148
	s_nop 1
	v_cndmask_b32_e64 v148, v149, v150, s[12:13]
	v_mul_f32_e32 v149, 0x37800000, v148
	v_cndmask_b32_e32 v148, v148, v149, vcc
	v_cmp_class_f32_e32 vcc, v96, v183
	s_nop 1
	v_cndmask_b32_e32 v96, v148, v96, vcc
	v_div_scale_f32 v148, s[10:11], v96, v96, 1.0
	v_rcp_f32_e32 v149, v148
	s_nop 0
	v_fma_f32 v150, -v148, v149, 1.0
	v_fmac_f32_e32 v149, v150, v149
	v_div_scale_f32 v150, vcc, 1.0, v96, 1.0
	v_mul_f32_e32 v151, v150, v149
	v_fma_f32 v152, -v148, v151, v150
	v_fmac_f32_e32 v151, v152, v149
	v_fma_f32 v148, -v148, v151, v150
	v_div_fmas_f32 v148, v148, v149, v151
	v_div_fixup_f32 v96, v148, v96, 1.0
	v_pk_mul_f32 v[148:149], v[60:61], v[96:97] op_sel_hi:[1,0]
	v_pk_mul_f32 v[150:151], v[62:63], v[96:97] op_sel_hi:[1,0]
	s_waitcnt vmcnt(2)
	v_pk_mul_f32 v[152:153], v[144:145], v[148:149]
	v_pk_mul_f32 v[154:155], v[146:147], v[150:151]
	v_pk_mul_f32 v[148:149], v[56:57], v[96:97] op_sel_hi:[1,0]
	v_pk_mul_f32 v[150:151], v[58:59], v[96:97] op_sel_hi:[1,0]
	v_pk_mul_f32 v[156:157], v[48:49], v[96:97] op_sel_hi:[1,0]
	v_pk_mul_f32 v[158:159], v[50:51], v[96:97] op_sel_hi:[1,0]
	v_pk_mul_f32 v[162:163], v[40:41], v[96:97] op_sel_hi:[1,0]
	v_pk_mul_f32 v[160:161], v[42:43], v[96:97] op_sel_hi:[1,0]
	v_pk_mul_f32 v[150:151], v[142:143], v[150:151]
	v_pk_mul_f32 v[148:149], v[140:141], v[148:149]
	v_pk_mul_f32 v[158:159], v[138:139], v[158:159]
	v_pk_mul_f32 v[156:157], v[136:137], v[156:157]
	v_pk_mul_f32 v[160:161], v[134:135], v[160:161]
	s_and_b64 vcc, exec, s[6:7]
	v_pk_mul_f32 v[192:193], v[132:133], v[162:163]
	s_cbranch_vccnz .LBB0_622
	v_pk_mul_f32 v[210:211], v[156:157], v[230:231]
	v_pk_mul_f32 v[162:163], v[158:159], v[232:233]
	v_pk_fma_f32 v[234:235], v[152:153], v[206:207], v[210:211] neg_lo:[0,0,1] neg_hi:[0,0,1]
	v_pk_mul_f32 v[152:153], v[152:153], v[230:231]
	v_pk_fma_f32 v[236:237], v[154:155], v[208:209], v[162:163] neg_lo:[0,0,1] neg_hi:[0,0,1]
	v_pk_mul_f32 v[154:155], v[154:155], v[232:233]
	v_pk_fma_f32 v[156:157], v[156:157], v[206:207], v[152:153]
	v_pk_mul_f32 v[152:153], v[160:161], v[228:229]
	v_pk_mul_f32 v[162:163], v[192:193], v[226:227]
	v_pk_fma_f32 v[158:159], v[158:159], v[208:209], v[154:155]
	v_pk_fma_f32 v[154:155], v[150:151], v[204:205], v[152:153] neg_lo:[0,0,1] neg_hi:[0,0,1]
	v_pk_fma_f32 v[152:153], v[148:149], v[202:203], v[162:163] neg_lo:[0,0,1] neg_hi:[0,0,1]
	v_pk_mul_f32 v[150:151], v[150:151], v[228:229]
	v_pk_mul_f32 v[148:149], v[148:149], v[226:227]
	v_pk_fma_f32 v[160:161], v[160:161], v[204:205], v[150:151]
	v_pk_fma_f32 v[192:193], v[192:193], v[202:203], v[148:149]
	v_mov_b64_e32 v[148:149], v[152:153]
	v_mov_b64_e32 v[150:151], v[154:155]
	v_mov_b64_e32 v[152:153], v[234:235]
	v_mov_b64_e32 v[154:155], v[236:237]

; DI u32x4 pk8(const f32x4& a, const f32x4& b) { u32x4 w; w.x = pk2(a[0], a[1]); w.y = pk2(a[2], a[3]); w.z = pk2(b[0], b[1]); w.w = pk2(b[2], b[3]); return w; }
; DI float shx(float v, int m, int lane) { return __int_as_float(__builtin_amdgcn_ds_bpermute((lane ^ m) << 2, __float_as_int(v))); }
; #define FOR_AI_M _Pragma("unroll") for (int ai = 0; ai < 2; ++ai) _Pragma("unroll") for (int m = 0; m < 4; ++m)
; #define ROW_FENCE asm volatile("" ::: "memory")
;     DI void operator()(Acc& acc, const Unit& u, int wr, int wc, int fr, int fq) const {
;     ...
;         FOR_AI_M { const int r = row0 + EPI_ROWS(ai, m);
;             f32x4 x[2][2];
; #pragma unroll
;             for (int bj = 0; bj < 2; ++bj) { x[bj][0] = acc[ai][bj][m][0]; x[bj][1] = acc[ai][bj][m][1]; }
;             if (!is_v) {
;                 float s = 0.f;
; #pragma unroll
;                 for (int bj = 0; bj < 2; ++bj)
; #pragma unroll
;                     for (int n = 0; n < 2; ++n) s += (x[bj][n][0] * x[bj][n][0] + x[bj][n][1] * x[bj][n][1]) + (x[bj][n][2] * x[bj][n][2] + x[bj][n][3] * x[bj][n][3]);
;                 s += shx(s, 16, fr + 16 * fq); s += shx(s, 32, fr + 16 * fq);
;                 const float rstd = 1.f / sqrtf(s * (1.f / 64.f) + EPS);
; #pragma unroll
;                 for (int bj = 0; bj < 2; ++bj)
; #pragma unroll
;                     for (int n = 0; n < 2; ++n) x[bj][n] = x[bj][n] * rstd * gv[bj][n];
;                 if (rope) {
;                     const float* rr = rg + (size_t)(r & 2047) * 64 + 8 * fq;
; #pragma unroll
;                     for (int n = 0; n < 2; ++n) { const f32x4 cs = *(const f32x4*)(rr + 4 * n), sn = *(const f32x4*)(rr + 32 + 4 * n);
;                         const f32x4 x1 = x[0][n], x2 = x[1][n]; x[0][n] = x1 * cs - x2 * sn; x[1][n] = x1 * sn + x2 * cs; }
;                 }
; #pragma unroll
;                 for (int bj = 0; bj < 2; ++bj)
; #pragma unroll
;                     for (int n = 0; n < 2; ++n) x[bj][n] = x[bj][n] * qs;
;             }
; #pragma unroll
;             for (int bj = 0; bj < 2; ++bj) *(u32x4*)(dst + (size_t)r * ld + colb + 32 * bj + 8 * fq) = pk8(x[bj][0], x[bj][1]);
;             if (m == 3) ROW_FENCE;
.LBB0_623:
	v_mad_i64_i32 v[192:193], s[10:11], s42, v200, 0
	v_lshl_add_u64 v[192:193], v[192:193], 1, v[98:99]
	v_cvt_pk_bf16_f32 v152, v152, v153
	v_cvt_pk_bf16_f32 v153, v154, v155
	v_cvt_pk_bf16_f32 v154, v148, v149
	v_cvt_pk_bf16_f32 v155, v150, v151
	v_cvt_pk_bf16_f32 v148, v156, v157
	v_cvt_pk_bf16_f32 v149, v158, v159
	v_cvt_pk_bf16_f32 v150, v160, v161
	v_cvt_pk_bf16_f32 v151, v162, v163
	v_add_u32_e32 v248, 0x9000, v251
	v_lshl_add_u64 v[252:253], v[176:177], 0, v[248:249]
	global_load_dwordx4 v[202:205], v[252:253], off offset:16
	global_load_dwordx4 v[206:209], v[252:253], off
	global_load_dwordx4 v[226:229], v[252:253], off offset:144
	global_load_dwordx4 v[230:233], v[252:253], off offset:128
	global_store_dwordx4 v[192:193], v[152:155], off sc1
	global_store_dwordx4 v[192:193], v[148:151], off offset:64 sc1
	v_mov_b64_e32 v[158:159], v[34:35]
	v_mov_b64_e32 v[154:155], v[54:55]
	v_mov_b64_e32 v[150:151], v[46:47]
	v_mov_b64_e32 v[162:163], v[26:27]
	v_add_u32_e32 v200, 0x90, v199
	s_and_b64 vcc, exec, s[8:9]
	v_mov_b64_e32 v[152:153], v[52:53]
	v_mov_b64_e32 v[148:149], v[44:45]
	v_mov_b64_e32 v[156:157], v[32:33]
	v_mov_b64_e32 v[160:161], v[24:25]
	s_cbranch_vccnz .LBB0_627
	v_pk_mul_f32 v[148:149], v[54:55], v[54:55]
	v_pk_mul_f32 v[150:151], v[52:53], v[52:53]
	v_mul_f32_e32 v96, v32, v32
	v_pk_mov_b32 v[152:153], v[150:151], v[148:149] op_sel:[1,0]
	v_mov_b32_e32 v151, v149
	v_pk_add_f32 v[148:149], v[152:153], v[150:151]
	v_pk_mul_f32 v[150:151], v[46:47], v[46:47]
	v_pk_mul_f32 v[152:153], v[44:45], v[44:45]
	v_pk_add_f32 v[148:149], v[148:149], v[148:149] op_sel_hi:[0,1]
	v_pk_mov_b32 v[154:155], v[152:153], v[150:151] op_sel:[1,0]
	v_mov_b32_e32 v153, v151
	v_pk_add_f32 v[150:151], v[154:155], v[152:153]
	v_pk_fma_f32 v[152:153], v[32:33], v[32:33], v[96:97] op_sel_hi:[1,1,0]
	v_mul_f32_e32 v96, v34, v34
	v_pk_add_f32 v[150:151], v[150:151], v[150:151] op_sel_hi:[0,1]
	v_pk_fma_f32 v[154:155], v[34:35], v[34:35], v[96:97] op_sel_hi:[1,1,0]
	v_mul_f32_e32 v152, v24, v24
	v_mul_f32_e32 v154, v25, v25
	v_mul_f32_e32 v150, v26, v26
	v_mul_f32_e32 v148, v27, v27
	v_pk_add_f32 v[152:153], v[152:153], v[154:155]
	v_pk_add_f32 v[148:149], v[150:151], v[148:149]
	s_nop 0
	v_pk_add_f32 v[148:149], v[152:153], v[148:149]
	s_nop 0
	v_add_f32_e32 v96, v148, v149
	ds_bpermute_b32 v148, v194, v96
	s_waitcnt lgkmcnt(0)
	v_add_f32_e32 v96, v96, v148
	ds_bpermute_b32 v148, v195, v96
	s_waitcnt lgkmcnt(0)
	v_add_f32_e32 v96, v96, v148
	v_fmamk_f32 v96, v96, 0x3c800000, v185
	v_mul_f32_e32 v148, 0x4f800000, v96
	v_cmp_gt_f32_e32 vcc, s65, v96
	s_nop 1
	v_cndmask_b32_e32 v96, v96, v148, vcc
	v_sqrt_f32_e32 v148, v96
	s_nop 0
	v_add_u32_e32 v149, -1, v148
	v_fma_f32 v150, -v149, v148, v96
	v_cmp_ge_f32_e64 s[12:13], 0, v150
	v_add_u32_e32 v150, 1, v148
	s_nop 0
	v_cndmask_b32_e64 v149, v148, v149, s[12:13]
	v_fma_f32 v148, -v150, v148, v96
	v_cmp_lt_f32_e64 s[12:13], 0, v148
	s_nop 1
	v_cndmask_b32_e64 v148, v149, v150, s[12:13]
	v_mul_f32_e32 v149, 0x37800000, v148
	v_cndmask_b32_e32 v148, v148, v149, vcc
	v_cmp_class_f32_e32 vcc, v96, v183
	s_nop 1
	v_cndmask_b32_e32 v96, v148, v96, vcc
	v_div_scale_f32 v148, s[10:11], v96, v96, 1.0
	v_rcp_f32_e32 v149, v148
	s_nop 0
	v_fma_f32 v150, -v148, v149, 1.0
	v_fmac_f32_e32 v149, v150, v149
	v_div_scale_f32 v150, vcc, 1.0, v96, 1.0
	v_mul_f32_e32 v151, v150, v149
	v_fma_f32 v152, -v148, v151, v150
	v_fmac_f32_e32 v151, v152, v149
	v_fma_f32 v148, -v148, v151, v150
	v_div_fmas_f32 v148, v148, v149, v151
	v_div_fixup_f32 v96, v148, v96, 1.0
	v_pk_mul_f32 v[148:149], v[52:53], v[96:97] op_sel_hi:[1,0]
	v_pk_mul_f32 v[150:151], v[54:55], v[96:97] op_sel_hi:[1,0]
	s_waitcnt vmcnt(2)
	v_pk_mul_f32 v[152:153], v[144:145], v[148:149]
	v_pk_mul_f32 v[154:155], v[146:147], v[150:151]
	v_pk_mul_f32 v[148:149], v[44:45], v[96:97] op_sel_hi:[1,0]
	v_pk_mul_f32 v[150:151], v[46:47], v[96:97] op_sel_hi:[1,0]
	v_pk_mul_f32 v[156:157], v[32:33], v[96:97] op_sel_hi:[1,0]
	v_pk_mul_f32 v[158:159], v[34:35], v[96:97] op_sel_hi:[1,0]
	v_pk_mul_f32 v[162:163], v[24:25], v[96:97] op_sel_hi:[1,0]
	v_pk_mul_f32 v[160:161], v[26:27], v[96:97] op_sel_hi:[1,0]
	v_pk_mul_f32 v[150:151], v[142:143], v[150:151]
	v_pk_mul_f32 v[148:149], v[140:141], v[148:149]
	v_pk_mul_f32 v[158:159], v[138:139], v[158:159]
	v_pk_mul_f32 v[156:157], v[136:137], v[156:157]
	v_pk_mul_f32 v[160:161], v[134:135], v[160:161]
	s_and_b64 vcc, exec, s[6:7]
	v_pk_mul_f32 v[192:193], v[132:133], v[162:163]
	s_cbranch_vccnz .LBB0_626
	v_pk_mul_f32 v[210:211], v[156:157], v[230:231]
	v_pk_mul_f32 v[162:163], v[158:159], v[232:233]
	v_pk_fma_f32 v[234:235], v[152:153], v[206:207], v[210:211] neg_lo:[0,0,1] neg_hi:[0,0,1]
	v_pk_mul_f32 v[152:153], v[152:153], v[230:231]
	v_pk_fma_f32 v[236:237], v[154:155], v[208:209], v[162:163] neg_lo:[0,0,1] neg_hi:[0,0,1]
	v_pk_mul_f32 v[154:155], v[154:155], v[232:233]
	v_pk_fma_f32 v[156:157], v[156:157], v[206:207], v[152:153]
	v_pk_mul_f32 v[152:153], v[160:161], v[228:229]
	v_pk_mul_f32 v[162:163], v[192:193], v[226:227]
	v_pk_fma_f32 v[158:159], v[158:159], v[208:209], v[154:155]
	v_pk_fma_f32 v[154:155], v[150:151], v[204:205], v[152:153] neg_lo:[0,0,1] neg_hi:[0,0,1]
	v_pk_fma_f32 v[152:153], v[148:149], v[202:203], v[162:163] neg_lo:[0,0,1] neg_hi:[0,0,1]
	v_pk_mul_f32 v[150:151], v[150:151], v[228:229]
	v_pk_mul_f32 v[148:149], v[148:149], v[226:227]
	v_pk_fma_f32 v[160:161], v[160:161], v[204:205], v[150:151]
	v_pk_fma_f32 v[192:193], v[192:193], v[202:203], v[148:149]
	v_mov_b64_e32 v[148:149], v[152:153]
	v_mov_b64_e32 v[150:151], v[154:155]
	v_mov_b64_e32 v[152:153], v[234:235]
	v_mov_b64_e32 v[154:155], v[236:237]

; DI u32x4 pk8(const f32x4& a, const f32x4& b) { u32x4 w; w.x = pk2(a[0], a[1]); w.y = pk2(a[2], a[3]); w.z = pk2(b[0], b[1]); w.w = pk2(b[2], b[3]); return w; }
; DI float shx(float v, int m, int lane) { return __int_as_float(__builtin_amdgcn_ds_bpermute((lane ^ m) << 2, __float_as_int(v))); }
; #define FOR_AI_M _Pragma("unroll") for (int ai = 0; ai < 2; ++ai) _Pragma("unroll") for (int m = 0; m < 4; ++m)
; #define ROW_FENCE asm volatile("" ::: "memory")
;     DI void operator()(Acc& acc, const Unit& u, int wr, int wc, int fr, int fq) const {
;     ...
;         FOR_AI_M { const int r = row0 + EPI_ROWS(ai, m);
;             f32x4 x[2][2];
; #pragma unroll
;             for (int bj = 0; bj < 2; ++bj) { x[bj][0] = acc[ai][bj][m][0]; x[bj][1] = acc[ai][bj][m][1]; }
;             if (!is_v) {
;                 float s = 0.f;
; #pragma unroll
;                 for (int bj = 0; bj < 2; ++bj)
; #pragma unroll
;                     for (int n = 0; n < 2; ++n) s += (x[bj][n][0] * x[bj][n][0] + x[bj][n][1] * x[bj][n][1]) + (x[bj][n][2] * x[bj][n][2] + x[bj][n][3] * x[bj][n][3]);
;                 s += shx(s, 16, fr + 16 * fq); s += shx(s, 32, fr + 16 * fq);
;                 const float rstd = 1.f / sqrtf(s * (1.f / 64.f) + EPS);
; #pragma unroll
;                 for (int bj = 0; bj < 2; ++bj)
; #pragma unroll
;                     for (int n = 0; n < 2; ++n) x[bj][n] = x[bj][n] * rstd * gv[bj][n];
;                 if (rope) {
;                     const float* rr = rg + (size_t)(r & 2047) * 64 + 8 * fq;
; #pragma unroll
;                     for (int n = 0; n < 2; ++n) { const f32x4 cs = *(const f32x4*)(rr + 4 * n), sn = *(const f32x4*)(rr + 32 + 4 * n);
;                         const f32x4 x1 = x[0][n], x2 = x[1][n]; x[0][n] = x1 * cs - x2 * sn; x[1][n] = x1 * sn + x2 * cs; }
;                 }
; #pragma unroll
;                 for (int bj = 0; bj < 2; ++bj)
; #pragma unroll
;                     for (int n = 0; n < 2; ++n) x[bj][n] = x[bj][n] * qs;
;             }
; #pragma unroll
;             for (int bj = 0; bj < 2; ++bj) *(u32x4*)(dst + (size_t)r * ld + colb + 32 * bj + 8 * fq) = pk8(x[bj][0], x[bj][1]);
;             if (m == 3) ROW_FENCE;
.LBB0_627:
	v_mad_i64_i32 v[192:193], s[10:11], s42, v200, 0
	v_lshl_add_u64 v[192:193], v[192:193], 1, v[98:99]
	v_cvt_pk_bf16_f32 v152, v152, v153
	v_cvt_pk_bf16_f32 v153, v154, v155
	v_cvt_pk_bf16_f32 v154, v148, v149
	v_cvt_pk_bf16_f32 v155, v150, v151
	v_cvt_pk_bf16_f32 v148, v156, v157
	v_cvt_pk_bf16_f32 v149, v158, v159
	v_cvt_pk_bf16_f32 v150, v160, v161
	v_cvt_pk_bf16_f32 v151, v162, v163
	v_add_u32_e32 v248, 0xa000, v251
	v_lshl_add_u64 v[252:253], v[176:177], 0, v[248:249]
	global_load_dwordx4 v[202:205], v[252:253], off offset:16
	global_load_dwordx4 v[206:209], v[252:253], off
	global_load_dwordx4 v[226:229], v[252:253], off offset:144
	global_load_dwordx4 v[230:233], v[252:253], off offset:128
	global_store_dwordx4 v[192:193], v[152:155], off sc1
	global_store_dwordx4 v[192:193], v[148:151], off offset:64 sc1
	v_mov_b64_e32 v[158:159], v[18:19]
	v_mov_b64_e32 v[154:155], v[38:39]
	v_mov_b64_e32 v[150:151], v[30:31]
	v_mov_b64_e32 v[162:163], v[10:11]
	v_add_u32_e32 v200, 0xa0, v199
	s_and_b64 vcc, exec, s[8:9]
	v_mov_b64_e32 v[152:153], v[36:37]
	v_mov_b64_e32 v[148:149], v[28:29]
	v_mov_b64_e32 v[156:157], v[16:17]
	v_mov_b64_e32 v[160:161], v[8:9]
	s_cbranch_vccnz .LBB0_631
	v_pk_mul_f32 v[148:149], v[38:39], v[38:39]
	v_pk_mul_f32 v[150:151], v[36:37], v[36:37]
	v_mul_f32_e32 v96, v16, v16
	v_pk_mov_b32 v[152:153], v[150:151], v[148:149] op_sel:[1,0]
	v_mov_b32_e32 v151, v149
	v_pk_add_f32 v[148:149], v[152:153], v[150:151]
	v_pk_mul_f32 v[150:151], v[30:31], v[30:31]
	v_pk_mul_f32 v[152:153], v[28:29], v[28:29]
	v_pk_add_f32 v[148:149], v[148:149], v[148:149] op_sel_hi:[0,1]
	v_pk_mov_b32 v[154:155], v[152:153], v[150:151] op_sel:[1,0]
	v_mov_b32_e32 v153, v151
	v_pk_add_f32 v[150:151], v[154:155], v[152:153]
	v_pk_fma_f32 v[152:153], v[16:17], v[16:17], v[96:97] op_sel_hi:[1,1,0]
	v_mul_f32_e32 v96, v18, v18
	v_pk_add_f32 v[150:151], v[150:151], v[150:151] op_sel_hi:[0,1]
	v_pk_fma_f32 v[154:155], v[18:19], v[18:19], v[96:97] op_sel_hi:[1,1,0]
	v_mul_f32_e32 v152, v8, v8
	v_mul_f32_e32 v154, v9, v9
	v_mul_f32_e32 v150, v10, v10
	v_mul_f32_e32 v148, v11, v11
	v_pk_add_f32 v[152:153], v[152:153], v[154:155]
	v_pk_add_f32 v[148:149], v[150:151], v[148:149]
	s_nop 0
	v_pk_add_f32 v[148:149], v[152:153], v[148:149]
	s_nop 0
	v_add_f32_e32 v96, v148, v149
	ds_bpermute_b32 v148, v194, v96
	s_waitcnt lgkmcnt(0)
	v_add_f32_e32 v96, v96, v148
	ds_bpermute_b32 v148, v195, v96
	s_waitcnt lgkmcnt(0)
	v_add_f32_e32 v96, v96, v148
	v_fmamk_f32 v96, v96, 0x3c800000, v185
	v_mul_f32_e32 v148, 0x4f800000, v96
	v_cmp_gt_f32_e32 vcc, s65, v96
	s_nop 1
	v_cndmask_b32_e32 v96, v96, v148, vcc
	v_sqrt_f32_e32 v148, v96
	s_nop 0
	v_add_u32_e32 v149, -1, v148
	v_fma_f32 v150, -v149, v148, v96
	v_cmp_ge_f32_e64 s[12:13], 0, v150
	v_add_u32_e32 v150, 1, v148
	s_nop 0
	v_cndmask_b32_e64 v149, v148, v149, s[12:13]
	v_fma_f32 v148, -v150, v148, v96
	v_cmp_lt_f32_e64 s[12:13], 0, v148
	s_nop 1
	v_cndmask_b32_e64 v148, v149, v150, s[12:13]
	v_mul_f32_e32 v149, 0x37800000, v148
	v_cndmask_b32_e32 v148, v148, v149, vcc
	v_cmp_class_f32_e32 vcc, v96, v183
	s_nop 1
	v_cndmask_b32_e32 v96, v148, v96, vcc
	v_div_scale_f32 v148, s[10:11], v96, v96, 1.0
	v_rcp_f32_e32 v149, v148
	s_nop 0
	v_fma_f32 v150, -v148, v149, 1.0
	v_fmac_f32_e32 v149, v150, v149
	v_div_scale_f32 v150, vcc, 1.0, v96, 1.0
	v_mul_f32_e32 v151, v150, v149
	v_fma_f32 v152, -v148, v151, v150
	v_fmac_f32_e32 v151, v152, v149
	v_fma_f32 v148, -v148, v151, v150
	v_div_fmas_f32 v148, v148, v149, v151
	v_div_fixup_f32 v96, v148, v96, 1.0
	v_pk_mul_f32 v[148:149], v[36:37], v[96:97] op_sel_hi:[1,0]
	v_pk_mul_f32 v[150:151], v[38:39], v[96:97] op_sel_hi:[1,0]
	s_waitcnt vmcnt(2)
	v_pk_mul_f32 v[152:153], v[144:145], v[148:149]
	v_pk_mul_f32 v[154:155], v[146:147], v[150:151]
	v_pk_mul_f32 v[148:149], v[28:29], v[96:97] op_sel_hi:[1,0]
	v_pk_mul_f32 v[150:151], v[30:31], v[96:97] op_sel_hi:[1,0]
	v_pk_mul_f32 v[156:157], v[16:17], v[96:97] op_sel_hi:[1,0]
	v_pk_mul_f32 v[158:159], v[18:19], v[96:97] op_sel_hi:[1,0]
	v_pk_mul_f32 v[162:163], v[8:9], v[96:97] op_sel_hi:[1,0]
	v_pk_mul_f32 v[160:161], v[10:11], v[96:97] op_sel_hi:[1,0]
	v_pk_mul_f32 v[150:151], v[142:143], v[150:151]
	v_pk_mul_f32 v[148:149], v[140:141], v[148:149]
	v_pk_mul_f32 v[158:159], v[138:139], v[158:159]
	v_pk_mul_f32 v[156:157], v[136:137], v[156:157]
	v_pk_mul_f32 v[160:161], v[134:135], v[160:161]
	s_and_b64 vcc, exec, s[6:7]
	v_pk_mul_f32 v[192:193], v[132:133], v[162:163]
	s_cbranch_vccnz .LBB0_630
	v_pk_mul_f32 v[210:211], v[156:157], v[230:231]
	v_pk_mul_f32 v[162:163], v[158:159], v[232:233]
	v_pk_fma_f32 v[234:235], v[152:153], v[206:207], v[210:211] neg_lo:[0,0,1] neg_hi:[0,0,1]
	v_pk_mul_f32 v[152:153], v[152:153], v[230:231]
	v_pk_fma_f32 v[236:237], v[154:155], v[208:209], v[162:163] neg_lo:[0,0,1] neg_hi:[0,0,1]
	v_pk_mul_f32 v[154:155], v[154:155], v[232:233]
	v_pk_fma_f32 v[156:157], v[156:157], v[206:207], v[152:153]
	v_pk_mul_f32 v[152:153], v[160:161], v[228:229]
	v_pk_mul_f32 v[162:163], v[192:193], v[226:227]
	v_pk_fma_f32 v[158:159], v[158:159], v[208:209], v[154:155]
	v_pk_fma_f32 v[154:155], v[150:151], v[204:205], v[152:153] neg_lo:[0,0,1] neg_hi:[0,0,1]
	v_pk_fma_f32 v[152:153], v[148:149], v[202:203], v[162:163] neg_lo:[0,0,1] neg_hi:[0,0,1]
	v_pk_mul_f32 v[150:151], v[150:151], v[228:229]
	v_pk_mul_f32 v[148:149], v[148:149], v[226:227]
	v_pk_fma_f32 v[160:161], v[160:161], v[204:205], v[150:151]
	v_pk_fma_f32 v[192:193], v[192:193], v[202:203], v[148:149]
	v_mov_b64_e32 v[148:149], v[152:153]
	v_mov_b64_e32 v[150:151], v[154:155]
	v_mov_b64_e32 v[152:153], v[234:235]
	v_mov_b64_e32 v[154:155], v[236:237]

; DI u32x4 pk8(const f32x4& a, const f32x4& b) { u32x4 w; w.x = pk2(a[0], a[1]); w.y = pk2(a[2], a[3]); w.z = pk2(b[0], b[1]); w.w = pk2(b[2], b[3]); return w; }
; DI float shx(float v, int m, int lane) { return __int_as_float(__builtin_amdgcn_ds_bpermute((lane ^ m) << 2, __float_as_int(v))); }
; #define FOR_AI_M _Pragma("unroll") for (int ai = 0; ai < 2; ++ai) _Pragma("unroll") for (int m = 0; m < 4; ++m)
; #define ROW_FENCE asm volatile("" ::: "memory")
;     DI void operator()(Acc& acc, const Unit& u, int wr, int wc, int fr, int fq) const {
;     ...
;         FOR_AI_M { const int r = row0 + EPI_ROWS(ai, m);
;             f32x4 x[2][2];
; #pragma unroll
;             for (int bj = 0; bj < 2; ++bj) { x[bj][0] = acc[ai][bj][m][0]; x[bj][1] = acc[ai][bj][m][1]; }
;             if (!is_v) {
;                 float s = 0.f;
; #pragma unroll
;                 for (int bj = 0; bj < 2; ++bj)
; #pragma unroll
;                     for (int n = 0; n < 2; ++n) s += (x[bj][n][0] * x[bj][n][0] + x[bj][n][1] * x[bj][n][1]) + (x[bj][n][2] * x[bj][n][2] + x[bj][n][3] * x[bj][n][3]);
;                 s += shx(s, 16, fr + 16 * fq); s += shx(s, 32, fr + 16 * fq);
;                 const float rstd = 1.f / sqrtf(s * (1.f / 64.f) + EPS);
; #pragma unroll
;                 for (int bj = 0; bj < 2; ++bj)
; #pragma unroll
;                     for (int n = 0; n < 2; ++n) x[bj][n] = x[bj][n] * rstd * gv[bj][n];
;                 if (rope) {
;                     const float* rr = rg + (size_t)(r & 2047) * 64 + 8 * fq;
; #pragma unroll
;                     for (int n = 0; n < 2; ++n) { const f32x4 cs = *(const f32x4*)(rr + 4 * n), sn = *(const f32x4*)(rr + 32 + 4 * n);
;                         const f32x4 x1 = x[0][n], x2 = x[1][n]; x[0][n] = x1 * cs - x2 * sn; x[1][n] = x1 * sn + x2 * cs; }
;                 }
; #pragma unroll
;                 for (int bj = 0; bj < 2; ++bj)
; #pragma unroll
;                     for (int n = 0; n < 2; ++n) x[bj][n] = x[bj][n] * qs;
;             }
; #pragma unroll
;             for (int bj = 0; bj < 2; ++bj) *(u32x4*)(dst + (size_t)r * ld + colb + 32 * bj + 8 * fq) = pk8(x[bj][0], x[bj][1]);
;             if (m == 3) ROW_FENCE;
.LBB0_631:
	v_mad_i64_i32 v[192:193], s[10:11], s42, v200, 0
	v_lshl_add_u64 v[192:193], v[192:193], 1, v[98:99]
	v_cvt_pk_bf16_f32 v152, v152, v153
	v_cvt_pk_bf16_f32 v153, v154, v155
	v_cvt_pk_bf16_f32 v154, v148, v149
	v_cvt_pk_bf16_f32 v155, v150, v151
	v_cvt_pk_bf16_f32 v148, v156, v157
	v_cvt_pk_bf16_f32 v149, v158, v159
	v_cvt_pk_bf16_f32 v150, v160, v161
	v_cvt_pk_bf16_f32 v151, v162, v163
	global_store_dwordx4 v[192:193], v[152:155], off sc1
	global_store_dwordx4 v[192:193], v[148:151], off offset:64 sc1
	v_mov_b64_e32 v[158:159], v[6:7]
	v_mov_b64_e32 v[154:155], v[14:15]
	v_mov_b64_e32 v[150:151], v[22:23]
	v_mov_b64_e32 v[162:163], v[2:3]
	v_add_u32_e32 v192, 0xb0, v199
	s_and_b64 vcc, exec, s[8:9]
	v_mov_b64_e32 v[148:149], v[20:21]
	v_mov_b64_e32 v[152:153], v[12:13]
	v_mov_b64_e32 v[156:157], v[4:5]
	v_mov_b64_e32 v[160:161], v[0:1]
	s_cbranch_vccnz .LBB0_635
	v_pk_mul_f32 v[148:149], v[22:23], v[22:23]
	v_pk_mul_f32 v[150:151], v[20:21], v[20:21]
	v_mul_f32_e32 v96, v4, v4
	v_pk_mov_b32 v[152:153], v[150:151], v[148:149] op_sel:[1,0]
	v_mov_b32_e32 v151, v149
	v_pk_add_f32 v[148:149], v[152:153], v[150:151]
	v_pk_mul_f32 v[150:151], v[14:15], v[14:15]
	v_pk_mul_f32 v[152:153], v[12:13], v[12:13]
	v_pk_add_f32 v[148:149], v[148:149], v[148:149] op_sel_hi:[0,1]
	v_pk_mov_b32 v[154:155], v[152:153], v[150:151] op_sel:[1,0]
	v_mov_b32_e32 v153, v151
	v_pk_add_f32 v[150:151], v[154:155], v[152:153]
	v_pk_fma_f32 v[152:153], v[4:5], v[4:5], v[96:97] op_sel_hi:[1,1,0]
	v_mul_f32_e32 v96, v6, v6
	v_pk_add_f32 v[150:151], v[150:151], v[150:151] op_sel_hi:[0,1]
	v_pk_fma_f32 v[154:155], v[6:7], v[6:7], v[96:97] op_sel_hi:[1,1,0]
	v_mul_f32_e32 v152, v0, v0
	v_mul_f32_e32 v154, v1, v1
	v_mul_f32_e32 v150, v2, v2
	v_mul_f32_e32 v148, v3, v3
	v_pk_add_f32 v[152:153], v[152:153], v[154:155]
	v_pk_add_f32 v[148:149], v[150:151], v[148:149]
	s_nop 0
	v_pk_add_f32 v[148:149], v[152:153], v[148:149]
	s_nop 0
	v_add_f32_e32 v96, v148, v149
	ds_bpermute_b32 v148, v194, v96
	s_waitcnt lgkmcnt(0)
	v_add_f32_e32 v96, v96, v148
	ds_bpermute_b32 v148, v195, v96
	s_waitcnt lgkmcnt(0)
	v_add_f32_e32 v96, v96, v148
	v_fmamk_f32 v96, v96, 0x3c800000, v185
	v_mul_f32_e32 v148, 0x4f800000, v96
	v_cmp_gt_f32_e32 vcc, s65, v96
	s_nop 1
	v_cndmask_b32_e32 v96, v96, v148, vcc
	v_sqrt_f32_e32 v148, v96
	s_nop 0
	v_add_u32_e32 v149, -1, v148
	v_fma_f32 v150, -v149, v148, v96
	v_cmp_ge_f32_e64 s[8:9], 0, v150
	v_add_u32_e32 v150, 1, v148
	s_nop 0
	v_cndmask_b32_e64 v149, v148, v149, s[8:9]
	v_fma_f32 v148, -v150, v148, v96
	v_cmp_lt_f32_e64 s[8:9], 0, v148
	s_nop 1
	v_cndmask_b32_e64 v148, v149, v150, s[8:9]
	v_mul_f32_e32 v149, 0x37800000, v148
	v_cndmask_b32_e32 v148, v148, v149, vcc
	v_cmp_class_f32_e32 vcc, v96, v183
	s_nop 1
	v_cndmask_b32_e32 v96, v148, v96, vcc
	v_div_scale_f32 v148, s[8:9], v96, v96, 1.0
	v_rcp_f32_e32 v149, v148
	s_nop 0
	v_fma_f32 v150, -v148, v149, 1.0
	v_fmac_f32_e32 v149, v150, v149
	v_div_scale_f32 v150, vcc, 1.0, v96, 1.0
	v_mul_f32_e32 v151, v150, v149
	v_fma_f32 v152, -v148, v151, v150
	v_fmac_f32_e32 v151, v152, v149
	v_fma_f32 v148, -v148, v151, v150
	v_div_fmas_f32 v148, v148, v149, v151
	v_div_fixup_f32 v96, v148, v96, 1.0
	v_pk_mul_f32 v[148:149], v[20:21], v[96:97] op_sel_hi:[1,0]
	v_pk_mul_f32 v[150:151], v[22:23], v[96:97] op_sel_hi:[1,0]
	s_waitcnt vmcnt(0)
	v_pk_mul_f32 v[144:145], v[144:145], v[148:149]
	v_pk_mul_f32 v[146:147], v[146:147], v[150:151]
	v_pk_mul_f32 v[148:149], v[12:13], v[96:97] op_sel_hi:[1,0]
	v_pk_mul_f32 v[150:151], v[14:15], v[96:97] op_sel_hi:[1,0]
	v_pk_mul_f32 v[140:141], v[140:141], v[148:149]
	v_pk_mul_f32 v[142:143], v[142:143], v[150:151]
	v_pk_mul_f32 v[148:149], v[4:5], v[96:97] op_sel_hi:[1,0]
	v_pk_mul_f32 v[150:151], v[6:7], v[96:97] op_sel_hi:[1,0]
	v_pk_mul_f32 v[136:137], v[136:137], v[148:149]
	v_pk_mul_f32 v[138:139], v[138:139], v[150:151]
	v_pk_mul_f32 v[148:149], v[0:1], v[96:97] op_sel_hi:[1,0]
	v_pk_mul_f32 v[150:151], v[2:3], v[96:97] op_sel_hi:[1,0]
	s_and_b64 vcc, exec, s[6:7]
	v_pk_mul_f32 v[134:135], v[134:135], v[150:151]
	v_pk_mul_f32 v[132:133], v[132:133], v[148:149]
	s_cbranch_vccnz .LBB0_634
	v_lshlrev_b32_e32 v96, 8, v192
	v_and_b32_e32 v96, 0x7ff00, v96
	v_lshl_add_u64 v[160:161], v[176:177], 0, v[96:97]
	global_load_dwordx4 v[148:151], v[160:161], off offset:16
	global_load_dwordx4 v[152:155], v[160:161], off
	global_load_dwordx4 v[156:159], v[160:161], off offset:144
	s_nop 0
	global_load_dwordx4 v[160:163], v[160:161], off offset:128
	s_waitcnt vmcnt(0)
	v_pk_mul_f32 v[200:201], v[138:139], v[162:163]
	v_pk_mul_f32 v[204:205], v[136:137], v[160:161]
	v_pk_fma_f32 v[202:203], v[146:147], v[154:155], v[200:201] neg_lo:[0,0,1] neg_hi:[0,0,1]
	v_pk_fma_f32 v[200:201], v[144:145], v[152:153], v[204:205] neg_lo:[0,0,1] neg_hi:[0,0,1]
	v_pk_mul_f32 v[144:145], v[144:145], v[160:161]
	v_pk_mul_f32 v[146:147], v[146:147], v[162:163]
	v_pk_fma_f32 v[136:137], v[136:137], v[152:153], v[144:145]
	v_pk_mul_f32 v[144:145], v[134:135], v[158:159]
	v_pk_mul_f32 v[152:153], v[132:133], v[156:157]
	v_pk_fma_f32 v[138:139], v[138:139], v[154:155], v[146:147]
	v_pk_fma_f32 v[146:147], v[142:143], v[150:151], v[144:145] neg_lo:[0,0,1] neg_hi:[0,0,1]
	v_pk_fma_f32 v[144:145], v[140:141], v[148:149], v[152:153] neg_lo:[0,0,1] neg_hi:[0,0,1]
	v_pk_mul_f32 v[142:143], v[142:143], v[158:159]
	v_pk_mul_f32 v[140:141], v[140:141], v[156:157]
	v_pk_fma_f32 v[134:135], v[134:135], v[150:151], v[142:143]
	v_pk_fma_f32 v[132:133], v[132:133], v[148:149], v[140:141]
	v_mov_b64_e32 v[140:141], v[144:145]
	v_mov_b64_e32 v[142:143], v[146:147]
	v_mov_b64_e32 v[144:145], v[200:201]
	v_mov_b64_e32 v[146:147], v[202:203]

; DI u32x4 pk8(const f32x4& a, const f32x4& b) { u32x4 w; w.x = pk2(a[0], a[1]); w.y = pk2(a[2], a[3]); w.z = pk2(b[0], b[1]); w.w = pk2(b[2], b[3]); return w; }
; DI const float* inl(const Frame& F, int idx, size_t per_layer) { return pin(F, idx) + (size_t)F.l * per_layer; }
; #define FOR_AI_M _Pragma("unroll") for (int ai = 0; ai < 2; ++ai) _Pragma("unroll") for (int m = 0; m < 4; ++m)
; #define ROW_FENCE asm volatile("" ::: "memory")
;     DI void operator()(Acc& acc, const Unit& u, int wr, int wc, int fr, int fq) const {
;     ...
;         if (u.pn >= 5) {
;             const int cb = (u.pn - 5) * 256; const float* bg = inl(F, I_BGATE, 3072) + cb; bf16_t* dst = (bf16_t*)(ws + WS_GATE) + cb;
;             f32x4 bv[2][2];
; #pragma unroll
;             for (int bj = 0; bj < 2; ++bj) { bv[bj][0] = *(const f32x4*)(bg + EPI_COL8(bj)); bv[bj][1] = *(const f32x4*)(bg + EPI_COL8(bj) + 4); }
;             FOR_AI_M { const int r = row0 + EPI_ROWS(ai, m);
; #pragma unroll
;                 for (int bj = 0; bj < 2; ++bj) { f32x4 a = acc[ai][bj][m][0] + bv[bj][0], b = acc[ai][bj][m][1] + bv[bj][1];
; #pragma unroll
;                     for (int e = 0; e < 4; ++e) { a[e] = __builtin_amdgcn_rcpf(1.f + __builtin_amdgcn_exp2f(-1.4426950408889634f * a[e])); b[e] = __builtin_amdgcn_rcpf(1.f + __builtin_amdgcn_exp2f(-1.4426950408889634f * b[e])); }
;                     *(u32x4*)(dst + (size_t)r * 3072 + EPI_COL8(bj)) = pk8(a, b); } }
;             return;
;     ...
;             for (int bj = 0; bj < 2; ++bj) *(u32x4*)(dst + (size_t)r * ld + colb + 32 * bj + 8 * fq) = pk8(x[bj][0], x[bj][1]);
;             if (m == 3) ROW_FENCE;
.LBB0_635:
	s_waitcnt vmcnt(0)
	v_mad_i64_i32 v[132:133], s[6:7], s42, v192, 0
	v_lshl_add_u64 v[98:99], v[132:133], 1, v[98:99]
	v_cvt_pk_bf16_f32 v132, v148, v149
	v_cvt_pk_bf16_f32 v133, v150, v151
	v_cvt_pk_bf16_f32 v134, v152, v153
	v_cvt_pk_bf16_f32 v135, v154, v155
	global_store_dwordx4 v[98:99], v[132:135], off sc1
	s_mov_b64 s[6:7], 0
	s_nop 0
	v_cvt_pk_bf16_f32 v132, v156, v157
	v_cvt_pk_bf16_f32 v133, v158, v159
	v_cvt_pk_bf16_f32 v134, v160, v161
	v_cvt_pk_bf16_f32 v135, v162, v163
	global_store_dwordx4 v[98:99], v[132:135], off offset:64 sc1
.LBB0_636:
	s_and_b64 vcc, exec, s[6:7]
	s_cbranch_vccz .LBB0_638
	s_lshl_b32 s6, s50, 8
	s_add_i32 s16, s6, 0xfffffb00
	s_load_dwordx2 s[6:7], s[28:29], 0x38
	v_readlane_b32 s8, v255, 40
	v_lshlrev_b32_e32 v96, 2, v174
	v_add_u32_e32 v150, s21, v173
	s_waitcnt lgkmcnt(0)
	s_add_u32 s8, s6, s8
	s_addc_u32 s9, s7, 0
	s_lshl_b64 s[6:7], s[16:17], 2
	s_add_u32 s6, s8, s6
	s_addc_u32 s7, s9, s7
	global_load_dwordx4 v[140:143], v96, s[6:7] offset:16
	global_load_dwordx4 v[144:147], v96, s[6:7]
	global_load_dwordx4 v[132:135], v96, s[6:7] offset:528
	global_load_dwordx4 v[136:139], v96, s[6:7] offset:512
	s_lshl_b64 s[6:7], s[16:17], 1
	v_readlane_b32 s8, v255, 42
	s_add_u32 s6, s8, s6
	v_readlane_b32 s8, v255, 34
	s_addc_u32 s7, s8, s7
	v_mov_b64_e32 v[98:99], s[6:7]
	s_movk_i32 s8, 0x1800
	v_mad_i64_i32 v[148:149], s[6:7], v150, s8, v[98:99]
	s_waitcnt vmcnt(0)
	v_pk_add_f32 v[156:157], v[126:127], v[142:143]
	v_pk_add_f32 v[152:153], v[130:131], v[146:147]
	v_pk_add_f32 v[158:159], v[124:125], v[140:141]
	v_mul_f32_e32 v152, 0xbfb8aa3b, v152
	v_exp_f32_e32 v152, v152
	v_mul_f32_e32 v151, 0xbfb8aa3b, v158
	v_pk_add_f32 v[154:155], v[128:129], v[144:145]
	v_exp_f32_e32 v151, v151
	v_add_f32_e32 v152, 1.0, v152
	v_rcp_f32_e32 v158, v152
	v_mul_f32_e32 v152, 0xbfb8aa3b, v156
	v_exp_f32_e32 v152, v152
	v_mul_f32_e32 v96, 0xbfb8aa3b, v154
	v_mul_f32_e32 v154, 0xbfb8aa3b, v155
	v_exp_f32_e32 v96, v96
	v_add_f32_e32 v152, 1.0, v152
	v_rcp_f32_e32 v156, v152
	v_mul_f32_e32 v152, 0xbfb8aa3b, v153
	v_exp_f32_e32 v152, v152
	v_exp_f32_e32 v154, v154
	v_mul_f32_e32 v155, 0xbfb8aa3b, v159
	v_exp_f32_e32 v155, v155
	v_add_f32_e32 v152, 1.0, v152
	v_rcp_f32_e32 v153, v152
	v_mul_f32_e32 v152, 0xbfb8aa3b, v157
	v_exp_f32_e32 v152, v152
	v_add_f32_e32 v96, 1.0, v96
	v_add_f32_e32 v154, 1.0, v154
	v_rcp_f32_e32 v96, v96
	v_add_f32_e32 v151, 1.0, v151
	v_rcp_f32_e32 v154, v154
	v_add_f32_e32 v155, 1.0, v155
	v_add_f32_e32 v152, 1.0, v152
	v_rcp_f32_e32 v151, v151
	v_rcp_f32_e32 v155, v155
	v_rcp_f32_e32 v157, v152
	v_cvt_pk_bf16_f32 v152, v96, v154
	v_lshlrev_b32_e32 v96, 1, v174
	v_cvt_pk_bf16_f32 v153, v158, v153
	v_cvt_pk_bf16_f32 v154, v151, v155
	v_cvt_pk_bf16_f32 v155, v156, v157
	v_lshl_add_u64 v[148:149], v[148:149], 0, v[96:97]
	global_store_dwordx4 v[148:149], v[152:155], off sc1
	v_pk_add_f32 v[156:157], v[110:111], v[134:135]
	v_pk_add_f32 v[158:159], v[108:109], v[132:133]
	v_pk_add_f32 v[152:153], v[118:119], v[138:139]
	v_pk_add_f32 v[154:155], v[116:117], v[136:137]
	v_mul_f32_e32 v152, 0xbfb8aa3b, v152
	v_exp_f32_e32 v152, v152
	v_mul_f32_e32 v151, 0xbfb8aa3b, v154
	v_mul_f32_e32 v154, 0xbfb8aa3b, v158
	v_mul_f32_e32 v158, 0xbfb8aa3b, v159
	v_add_f32_e32 v152, 1.0, v152
	v_rcp_f32_e32 v159, v152
	v_mul_f32_e32 v152, 0xbfb8aa3b, v156
	v_exp_f32_e32 v152, v152
	v_mul_f32_e32 v155, 0xbfb8aa3b, v155
	v_exp_f32_e32 v151, v151
	v_exp_f32_e32 v154, v154
	v_add_f32_e32 v152, 1.0, v152
	v_rcp_f32_e32 v156, v152
	v_mul_f32_e32 v152, 0xbfb8aa3b, v153
	v_exp_f32_e32 v152, v152
	v_exp_f32_e32 v155, v155
	v_exp_f32_e32 v158, v158
	v_add_f32_e32 v151, 1.0, v151
	v_add_f32_e32 v152, 1.0, v152
	v_rcp_f32_e32 v153, v152
	v_mul_f32_e32 v152, 0xbfb8aa3b, v157
	v_exp_f32_e32 v152, v152
	v_add_f32_e32 v154, 1.0, v154
	v_add_f32_e32 v155, 1.0, v155
	v_add_f32_e32 v158, 1.0, v158
	v_add_f32_e32 v152, 1.0, v152
	v_rcp_f32_e32 v151, v151
	v_rcp_f32_e32 v154, v154
	v_rcp_f32_e32 v155, v155
	v_rcp_f32_e32 v158, v158
	v_rcp_f32_e32 v157, v152
	v_cvt_pk_bf16_f32 v153, v159, v153
	v_cvt_pk_bf16_f32 v152, v151, v155
	v_cvt_pk_bf16_f32 v154, v154, v158
	v_cvt_pk_bf16_f32 v155, v156, v157
	global_store_dwordx4 v[148:149], v[152:155], off offset:256 sc1
	v_pk_add_f32 v[156:157], v[114:115], v[142:143]
	v_pk_add_f32 v[158:159], v[112:113], v[140:141]
	v_pk_add_f32 v[152:153], v[122:123], v[146:147]
	v_pk_add_f32 v[154:155], v[120:121], v[144:145]
	v_mul_f32_e32 v152, 0xbfb8aa3b, v152
	v_exp_f32_e32 v152, v152
	v_mul_f32_e32 v151, 0xbfb8aa3b, v154
	v_mul_f32_e32 v154, 0xbfb8aa3b, v158
	v_mul_f32_e32 v158, 0xbfb8aa3b, v159
	v_add_f32_e32 v152, 1.0, v152
	v_rcp_f32_e32 v159, v152
	v_mul_f32_e32 v152, 0xbfb8aa3b, v156
	v_exp_f32_e32 v152, v152
	v_mul_f32_e32 v155, 0xbfb8aa3b, v155
	v_exp_f32_e32 v151, v151
	v_exp_f32_e32 v154, v154
	v_add_f32_e32 v152, 1.0, v152
	v_rcp_f32_e32 v156, v152
	v_mul_f32_e32 v152, 0xbfb8aa3b, v153
	v_exp_f32_e32 v152, v152
	v_exp_f32_e32 v155, v155
	v_exp_f32_e32 v158, v158
	v_add_f32_e32 v151, 1.0, v151
	v_add_f32_e32 v152, 1.0, v152
	v_rcp_f32_e32 v153, v152
	v_mul_f32_e32 v152, 0xbfb8aa3b, v157
	v_exp_f32_e32 v152, v152
	v_add_f32_e32 v154, 1.0, v154
	v_add_f32_e32 v155, 1.0, v155
	v_add_f32_e32 v158, 1.0, v158
	v_add_f32_e32 v152, 1.0, v152
	v_rcp_f32_e32 v151, v151
	v_rcp_f32_e32 v154, v154
	v_rcp_f32_e32 v155, v155
	v_rcp_f32_e32 v158, v158
	v_rcp_f32_e32 v157, v152
	v_or_b32_e32 v148, 16, v150
	v_mad_i64_i32 v[148:149], s[6:7], v148, s8, v[98:99]
	v_cvt_pk_bf16_f32 v152, v151, v155
	v_cvt_pk_bf16_f32 v153, v159, v153
	v_cvt_pk_bf16_f32 v154, v154, v158
	v_cvt_pk_bf16_f32 v155, v156, v157
; DI u32x4 pk8(const f32x4& a, const f32x4& b) { u32x4 w; w.x = pk2(a[0], a[1]); w.y = pk2(a[2], a[3]); w.z = pk2(b[0], b[1]); w.w = pk2(b[2], b[3]); return w; }
; DI const float* inl(const Frame& F, int idx, size_t per_layer) { return pin(F, idx) + (size_t)F.l * per_layer; }
; #define FOR_AI_M _Pragma("unroll") for (int ai = 0; ai < 2; ++ai) _Pragma("unroll") for (int m = 0; m < 4; ++m)
;     DI void operator()(Acc& acc, const Unit& u, int wr, int wc, int fr, int fq) const {
;     ...
;         if (u.pn >= 5) {
;             const int cb = (u.pn - 5) * 256; const float* bg = inl(F, I_BGATE, 3072) + cb; bf16_t* dst = (bf16_t*)(ws + WS_GATE) + cb;
;             f32x4 bv[2][2];
; #pragma unroll
;             for (int bj = 0; bj < 2; ++bj) { bv[bj][0] = *(const f32x4*)(bg + EPI_COL8(bj)); bv[bj][1] = *(const f32x4*)(bg + EPI_COL8(bj) + 4); }
;             FOR_AI_M { const int r = row0 + EPI_ROWS(ai, m);
; #pragma unroll
;                 for (int bj = 0; bj < 2; ++bj) { f32x4 a = acc[ai][bj][m][0] + bv[bj][0], b = acc[ai][bj][m][1] + bv[bj][1];
; #pragma unroll
;                     for (int e = 0; e < 4; ++e) { a[e] = __builtin_amdgcn_rcpf(1.f + __builtin_amdgcn_exp2f(-1.4426950408889634f * a[e])); b[e] = __builtin_amdgcn_rcpf(1.f + __builtin_amdgcn_exp2f(-1.4426950408889634f * b[e])); }
;                     *(u32x4*)(dst + (size_t)r * 3072 + EPI_COL8(bj)) = pk8(a, b); } }
;             return;
	v_lshl_add_u64 v[148:149], v[148:149], 0, v[96:97]
	global_store_dwordx4 v[148:149], v[152:155], off sc1
	v_pk_add_f32 v[156:157], v[90:91], v[134:135]
	v_pk_add_f32 v[158:159], v[88:89], v[132:133]
	v_pk_add_f32 v[152:153], v[102:103], v[138:139]
	v_pk_add_f32 v[154:155], v[100:101], v[136:137]
	v_mul_f32_e32 v152, 0xbfb8aa3b, v152
	v_exp_f32_e32 v152, v152
	v_mul_f32_e32 v151, 0xbfb8aa3b, v154
	v_mul_f32_e32 v154, 0xbfb8aa3b, v158
	v_mul_f32_e32 v158, 0xbfb8aa3b, v159
	v_add_f32_e32 v152, 1.0, v152
	v_rcp_f32_e32 v159, v152
	v_mul_f32_e32 v152, 0xbfb8aa3b, v156
	v_exp_f32_e32 v152, v152
	v_mul_f32_e32 v155, 0xbfb8aa3b, v155
	v_exp_f32_e32 v151, v151
	v_exp_f32_e32 v154, v154
	v_add_f32_e32 v152, 1.0, v152
	v_rcp_f32_e32 v156, v152
	v_mul_f32_e32 v152, 0xbfb8aa3b, v153
	v_exp_f32_e32 v152, v152
	v_exp_f32_e32 v155, v155
	v_exp_f32_e32 v158, v158
	v_add_f32_e32 v151, 1.0, v151
	v_add_f32_e32 v152, 1.0, v152
	v_rcp_f32_e32 v153, v152
	v_mul_f32_e32 v152, 0xbfb8aa3b, v157
	v_exp_f32_e32 v152, v152
	v_add_f32_e32 v154, 1.0, v154
	v_add_f32_e32 v155, 1.0, v155
	v_add_f32_e32 v158, 1.0, v158
	v_add_f32_e32 v152, 1.0, v152
	v_rcp_f32_e32 v151, v151
	v_rcp_f32_e32 v154, v154
	v_rcp_f32_e32 v155, v155
	v_rcp_f32_e32 v158, v158
	v_rcp_f32_e32 v157, v152
	v_cvt_pk_bf16_f32 v153, v159, v153
	v_cvt_pk_bf16_f32 v152, v151, v155
	v_cvt_pk_bf16_f32 v154, v154, v158
	v_cvt_pk_bf16_f32 v155, v156, v157
	global_store_dwordx4 v[148:149], v[152:155], off offset:256 sc1
	v_pk_add_f32 v[156:157], v[94:95], v[142:143]
	v_pk_add_f32 v[158:159], v[92:93], v[140:141]
	v_pk_add_f32 v[152:153], v[106:107], v[146:147]
	v_pk_add_f32 v[154:155], v[104:105], v[144:145]
	v_mul_f32_e32 v152, 0xbfb8aa3b, v152
	v_exp_f32_e32 v152, v152
	v_mul_f32_e32 v151, 0xbfb8aa3b, v154
	v_mul_f32_e32 v154, 0xbfb8aa3b, v158
	v_mul_f32_e32 v158, 0xbfb8aa3b, v159
	v_add_f32_e32 v152, 1.0, v152
	v_rcp_f32_e32 v159, v152
	v_mul_f32_e32 v152, 0xbfb8aa3b, v156
	v_exp_f32_e32 v152, v152
	v_mul_f32_e32 v155, 0xbfb8aa3b, v155
	v_exp_f32_e32 v151, v151
	v_exp_f32_e32 v154, v154
	v_add_f32_e32 v152, 1.0, v152
	v_rcp_f32_e32 v156, v152
	v_mul_f32_e32 v152, 0xbfb8aa3b, v153
	v_exp_f32_e32 v152, v152
	v_exp_f32_e32 v155, v155
	v_exp_f32_e32 v158, v158
	v_add_f32_e32 v151, 1.0, v151
	v_add_f32_e32 v152, 1.0, v152
	v_rcp_f32_e32 v153, v152
	v_mul_f32_e32 v152, 0xbfb8aa3b, v157
	v_exp_f32_e32 v152, v152
	v_add_f32_e32 v154, 1.0, v154
	v_add_f32_e32 v155, 1.0, v155
	v_add_f32_e32 v158, 1.0, v158
	v_add_f32_e32 v152, 1.0, v152
	v_rcp_f32_e32 v151, v151
	v_rcp_f32_e32 v154, v154
	v_rcp_f32_e32 v155, v155
	v_rcp_f32_e32 v158, v158
	v_rcp_f32_e32 v157, v152
	v_or_b32_e32 v148, 32, v150
	v_mad_i64_i32 v[148:149], s[6:7], v148, s8, v[98:99]
	v_cvt_pk_bf16_f32 v152, v151, v155
	v_cvt_pk_bf16_f32 v153, v159, v153
	v_cvt_pk_bf16_f32 v154, v154, v158
	v_cvt_pk_bf16_f32 v155, v156, v157
	v_lshl_add_u64 v[148:149], v[148:149], 0, v[96:97]
	global_store_dwordx4 v[148:149], v[152:155], off sc1
	v_pk_add_f32 v[156:157], v[74:75], v[134:135]
	v_pk_add_f32 v[158:159], v[72:73], v[132:133]
	v_pk_add_f32 v[152:153], v[82:83], v[138:139]
	v_pk_add_f32 v[154:155], v[80:81], v[136:137]
	v_mul_f32_e32 v152, 0xbfb8aa3b, v152
	v_exp_f32_e32 v152, v152
	v_mul_f32_e32 v151, 0xbfb8aa3b, v154
	v_mul_f32_e32 v154, 0xbfb8aa3b, v158
	v_mul_f32_e32 v158, 0xbfb8aa3b, v159
	v_add_f32_e32 v152, 1.0, v152
	v_rcp_f32_e32 v159, v152
	v_mul_f32_e32 v152, 0xbfb8aa3b, v156
	v_exp_f32_e32 v152, v152
	v_mul_f32_e32 v155, 0xbfb8aa3b, v155
	v_exp_f32_e32 v151, v151
	v_exp_f32_e32 v154, v154
	v_add_f32_e32 v152, 1.0, v152
	v_rcp_f32_e32 v156, v152
	v_mul_f32_e32 v152, 0xbfb8aa3b, v153
	v_exp_f32_e32 v152, v152
	v_exp_f32_e32 v155, v155
	v_exp_f32_e32 v158, v158
	v_add_f32_e32 v151, 1.0, v151
	v_add_f32_e32 v152, 1.0, v152
	v_rcp_f32_e32 v153, v152
	v_mul_f32_e32 v152, 0xbfb8aa3b, v157
	v_exp_f32_e32 v152, v152
	v_add_f32_e32 v154, 1.0, v154
	v_add_f32_e32 v155, 1.0, v155
	v_add_f32_e32 v158, 1.0, v158
	v_add_f32_e32 v152, 1.0, v152
	v_rcp_f32_e32 v151, v151
	v_rcp_f32_e32 v154, v154
	v_rcp_f32_e32 v155, v155
	v_rcp_f32_e32 v158, v158
	v_rcp_f32_e32 v157, v152
	v_cvt_pk_bf16_f32 v153, v159, v153
	v_cvt_pk_bf16_f32 v152, v151, v155
	v_cvt_pk_bf16_f32 v154, v154, v158
	v_cvt_pk_bf16_f32 v155, v156, v157
	global_store_dwordx4 v[148:149], v[152:155], off offset:256 sc1
	v_pk_add_f32 v[156:157], v[78:79], v[142:143]
	v_pk_add_f32 v[158:159], v[76:77], v[140:141]
	v_pk_add_f32 v[152:153], v[86:87], v[146:147]
	v_pk_add_f32 v[154:155], v[84:85], v[144:145]
	v_mul_f32_e32 v152, 0xbfb8aa3b, v152
	v_exp_f32_e32 v152, v152
	v_mul_f32_e32 v151, 0xbfb8aa3b, v154
	v_mul_f32_e32 v154, 0xbfb8aa3b, v158
	v_mul_f32_e32 v158, 0xbfb8aa3b, v159
	v_add_f32_e32 v152, 1.0, v152
	v_rcp_f32_e32 v159, v152
	v_mul_f32_e32 v152, 0xbfb8aa3b, v156
	v_exp_f32_e32 v152, v152
	v_mul_f32_e32 v155, 0xbfb8aa3b, v155
	v_exp_f32_e32 v151, v151
	v_exp_f32_e32 v154, v154
	v_add_f32_e32 v152, 1.0, v152
	v_rcp_f32_e32 v156, v152
	v_mul_f32_e32 v152, 0xbfb8aa3b, v153
	v_exp_f32_e32 v152, v152
	v_exp_f32_e32 v155, v155
	v_exp_f32_e32 v158, v158
	v_add_f32_e32 v151, 1.0, v151
	v_add_f32_e32 v152, 1.0, v152
	v_rcp_f32_e32 v153, v152
	v_mul_f32_e32 v152, 0xbfb8aa3b, v157
	v_exp_f32_e32 v152, v152
	v_add_f32_e32 v154, 1.0, v154
	v_add_f32_e32 v155, 1.0, v155
	v_add_f32_e32 v158, 1.0, v158
	v_add_f32_e32 v152, 1.0, v152
	v_rcp_f32_e32 v151, v151
	v_rcp_f32_e32 v154, v154
	v_rcp_f32_e32 v155, v155
	v_rcp_f32_e32 v158, v158
	v_rcp_f32_e32 v157, v152
	v_or_b32_e32 v148, 48, v150
	v_mad_i64_i32 v[148:149], s[6:7], v148, s8, v[98:99]
	v_cvt_pk_bf16_f32 v152, v151, v155
	v_cvt_pk_bf16_f32 v153, v159, v153
; DI u32x4 pk8(const f32x4& a, const f32x4& b) { u32x4 w; w.x = pk2(a[0], a[1]); w.y = pk2(a[2], a[3]); w.z = pk2(b[0], b[1]); w.w = pk2(b[2], b[3]); return w; }
; DI const float* inl(const Frame& F, int idx, size_t per_layer) { return pin(F, idx) + (size_t)F.l * per_layer; }
; #define FOR_AI_M _Pragma("unroll") for (int ai = 0; ai < 2; ++ai) _Pragma("unroll") for (int m = 0; m < 4; ++m)
;     DI void operator()(Acc& acc, const Unit& u, int wr, int wc, int fr, int fq) const {
;     ...
;         if (u.pn >= 5) {
;             const int cb = (u.pn - 5) * 256; const float* bg = inl(F, I_BGATE, 3072) + cb; bf16_t* dst = (bf16_t*)(ws + WS_GATE) + cb;
;             f32x4 bv[2][2];
; #pragma unroll
;             for (int bj = 0; bj < 2; ++bj) { bv[bj][0] = *(const f32x4*)(bg + EPI_COL8(bj)); bv[bj][1] = *(const f32x4*)(bg + EPI_COL8(bj) + 4); }
;             FOR_AI_M { const int r = row0 + EPI_ROWS(ai, m);
; #pragma unroll
;                 for (int bj = 0; bj < 2; ++bj) { f32x4 a = acc[ai][bj][m][0] + bv[bj][0], b = acc[ai][bj][m][1] + bv[bj][1];
; #pragma unroll
;                     for (int e = 0; e < 4; ++e) { a[e] = __builtin_amdgcn_rcpf(1.f + __builtin_amdgcn_exp2f(-1.4426950408889634f * a[e])); b[e] = __builtin_amdgcn_rcpf(1.f + __builtin_amdgcn_exp2f(-1.4426950408889634f * b[e])); }
;                     *(u32x4*)(dst + (size_t)r * 3072 + EPI_COL8(bj)) = pk8(a, b); } }
;             return;
	v_cvt_pk_bf16_f32 v154, v154, v158
	v_cvt_pk_bf16_f32 v155, v156, v157
	v_lshl_add_u64 v[148:149], v[148:149], 0, v[96:97]
	global_store_dwordx4 v[148:149], v[152:155], off sc1
	v_pk_add_f32 v[156:157], v[66:67], v[134:135]
	v_pk_add_f32 v[158:159], v[64:65], v[132:133]
	v_pk_add_f32 v[152:153], v[70:71], v[138:139]
	v_pk_add_f32 v[154:155], v[68:69], v[136:137]
	v_mul_f32_e32 v152, 0xbfb8aa3b, v152
	v_exp_f32_e32 v152, v152
	v_mul_f32_e32 v151, 0xbfb8aa3b, v154
	v_mul_f32_e32 v154, 0xbfb8aa3b, v158
	v_mul_f32_e32 v158, 0xbfb8aa3b, v159
	v_add_f32_e32 v152, 1.0, v152
	v_rcp_f32_e32 v159, v152
	v_mul_f32_e32 v152, 0xbfb8aa3b, v156
	v_exp_f32_e32 v152, v152
	v_mul_f32_e32 v155, 0xbfb8aa3b, v155
	v_exp_f32_e32 v151, v151
	v_exp_f32_e32 v154, v154
	v_add_f32_e32 v152, 1.0, v152
	v_rcp_f32_e32 v156, v152
	v_mul_f32_e32 v152, 0xbfb8aa3b, v153
	v_exp_f32_e32 v152, v152
	v_exp_f32_e32 v155, v155
	v_exp_f32_e32 v158, v158
	v_add_f32_e32 v151, 1.0, v151
	v_add_f32_e32 v152, 1.0, v152
	v_rcp_f32_e32 v153, v152
	v_mul_f32_e32 v152, 0xbfb8aa3b, v157
	v_exp_f32_e32 v152, v152
	v_add_f32_e32 v154, 1.0, v154
	v_add_f32_e32 v155, 1.0, v155
	v_add_f32_e32 v158, 1.0, v158
	v_add_f32_e32 v152, 1.0, v152
	v_rcp_f32_e32 v151, v151
	v_rcp_f32_e32 v154, v154
	v_rcp_f32_e32 v155, v155
	v_rcp_f32_e32 v158, v158
	v_rcp_f32_e32 v157, v152
	v_cvt_pk_bf16_f32 v153, v159, v153
	v_cvt_pk_bf16_f32 v152, v151, v155
	v_cvt_pk_bf16_f32 v154, v154, v158
	v_cvt_pk_bf16_f32 v155, v156, v157
	global_store_dwordx4 v[148:149], v[152:155], off offset:256 sc1
	v_pk_add_f32 v[156:157], v[58:59], v[142:143]
	v_pk_add_f32 v[158:159], v[56:57], v[140:141]
	v_pk_add_f32 v[152:153], v[62:63], v[146:147]
	v_pk_add_f32 v[154:155], v[60:61], v[144:145]
	v_mul_f32_e32 v152, 0xbfb8aa3b, v152
	v_exp_f32_e32 v152, v152
	v_mul_f32_e32 v151, 0xbfb8aa3b, v154
	v_mul_f32_e32 v154, 0xbfb8aa3b, v158
	v_mul_f32_e32 v158, 0xbfb8aa3b, v159
	v_add_f32_e32 v152, 1.0, v152
	v_rcp_f32_e32 v159, v152
	v_mul_f32_e32 v152, 0xbfb8aa3b, v156
	v_exp_f32_e32 v152, v152
	v_mul_f32_e32 v155, 0xbfb8aa3b, v155
	v_exp_f32_e32 v151, v151
	v_exp_f32_e32 v154, v154
	v_add_f32_e32 v152, 1.0, v152
	v_rcp_f32_e32 v156, v152
	v_mul_f32_e32 v152, 0xbfb8aa3b, v153
	v_exp_f32_e32 v152, v152
	v_exp_f32_e32 v155, v155
	v_exp_f32_e32 v158, v158
	v_add_f32_e32 v151, 1.0, v151
	v_add_f32_e32 v152, 1.0, v152
	v_rcp_f32_e32 v153, v152
	v_mul_f32_e32 v152, 0xbfb8aa3b, v157
	v_exp_f32_e32 v152, v152
	v_add_f32_e32 v154, 1.0, v154
	v_add_f32_e32 v155, 1.0, v155
	v_add_f32_e32 v158, 1.0, v158
	v_add_f32_e32 v152, 1.0, v152
	v_rcp_f32_e32 v151, v151
	v_rcp_f32_e32 v154, v154
	v_rcp_f32_e32 v155, v155
	v_rcp_f32_e32 v158, v158
	v_rcp_f32_e32 v157, v152
	v_add_u32_e32 v148, 0x80, v150
	v_mad_i64_i32 v[148:149], s[6:7], v148, s8, v[98:99]
	v_cvt_pk_bf16_f32 v152, v151, v155
	v_cvt_pk_bf16_f32 v153, v159, v153
	v_cvt_pk_bf16_f32 v154, v154, v158
	v_cvt_pk_bf16_f32 v155, v156, v157
	v_lshl_add_u64 v[148:149], v[148:149], 0, v[96:97]
	global_store_dwordx4 v[148:149], v[152:155], off sc1
	v_pk_add_f32 v[156:157], v[42:43], v[134:135]
	v_pk_add_f32 v[158:159], v[40:41], v[132:133]
	v_pk_add_f32 v[152:153], v[50:51], v[138:139]
	v_pk_add_f32 v[154:155], v[48:49], v[136:137]
	v_mul_f32_e32 v152, 0xbfb8aa3b, v152
	v_exp_f32_e32 v152, v152
	v_mul_f32_e32 v151, 0xbfb8aa3b, v154
	v_mul_f32_e32 v154, 0xbfb8aa3b, v158
	v_mul_f32_e32 v158, 0xbfb8aa3b, v159
	v_add_f32_e32 v152, 1.0, v152
	v_rcp_f32_e32 v159, v152
	v_mul_f32_e32 v152, 0xbfb8aa3b, v156
	v_exp_f32_e32 v152, v152
	v_mul_f32_e32 v155, 0xbfb8aa3b, v155
	v_exp_f32_e32 v151, v151
	v_exp_f32_e32 v154, v154
	v_add_f32_e32 v152, 1.0, v152
	v_rcp_f32_e32 v156, v152
	v_mul_f32_e32 v152, 0xbfb8aa3b, v153
	v_exp_f32_e32 v152, v152
	v_exp_f32_e32 v155, v155
	v_exp_f32_e32 v158, v158
	v_add_f32_e32 v151, 1.0, v151
	v_add_f32_e32 v152, 1.0, v152
	v_rcp_f32_e32 v153, v152
	v_mul_f32_e32 v152, 0xbfb8aa3b, v157
	v_exp_f32_e32 v152, v152
	v_add_f32_e32 v154, 1.0, v154
	v_add_f32_e32 v155, 1.0, v155
	v_add_f32_e32 v158, 1.0, v158
	v_add_f32_e32 v152, 1.0, v152
	v_rcp_f32_e32 v151, v151
	v_rcp_f32_e32 v154, v154
	v_rcp_f32_e32 v155, v155
	v_rcp_f32_e32 v158, v158
	v_rcp_f32_e32 v157, v152
	v_cvt_pk_bf16_f32 v153, v159, v153
	v_cvt_pk_bf16_f32 v152, v151, v155
	v_cvt_pk_bf16_f32 v154, v154, v158
	v_cvt_pk_bf16_f32 v155, v156, v157
	global_store_dwordx4 v[148:149], v[152:155], off offset:256 sc1
	v_pk_add_f32 v[156:157], v[46:47], v[142:143]
	v_pk_add_f32 v[158:159], v[44:45], v[140:141]
	v_pk_add_f32 v[152:153], v[54:55], v[146:147]
	v_pk_add_f32 v[154:155], v[52:53], v[144:145]
	v_mul_f32_e32 v152, 0xbfb8aa3b, v152
	v_exp_f32_e32 v152, v152
	v_mul_f32_e32 v151, 0xbfb8aa3b, v154
	v_mul_f32_e32 v154, 0xbfb8aa3b, v158
	v_mul_f32_e32 v158, 0xbfb8aa3b, v159
	v_add_f32_e32 v152, 1.0, v152
	v_rcp_f32_e32 v159, v152
	v_mul_f32_e32 v152, 0xbfb8aa3b, v156
	v_exp_f32_e32 v152, v152
	v_mul_f32_e32 v155, 0xbfb8aa3b, v155
	v_exp_f32_e32 v151, v151
	v_exp_f32_e32 v154, v154
	v_add_f32_e32 v152, 1.0, v152
	v_rcp_f32_e32 v156, v152
	v_mul_f32_e32 v152, 0xbfb8aa3b, v153
	v_exp_f32_e32 v152, v152
	v_exp_f32_e32 v155, v155
	v_exp_f32_e32 v158, v158
	v_add_f32_e32 v151, 1.0, v151
	v_add_f32_e32 v152, 1.0, v152
	v_rcp_f32_e32 v153, v152
	v_mul_f32_e32 v152, 0xbfb8aa3b, v157
	v_exp_f32_e32 v152, v152
	v_add_f32_e32 v154, 1.0, v154
	v_add_f32_e32 v155, 1.0, v155
	v_add_f32_e32 v158, 1.0, v158
	v_add_f32_e32 v152, 1.0, v152
	v_rcp_f32_e32 v151, v151
	v_rcp_f32_e32 v154, v154
	v_rcp_f32_e32 v155, v155
	v_rcp_f32_e32 v158, v158
	v_rcp_f32_e32 v157, v152
	v_add_u32_e32 v148, 0x90, v150
	v_mad_i64_i32 v[148:149], s[6:7], v148, s8, v[98:99]
; DI u32x4 pk8(const f32x4& a, const f32x4& b) { u32x4 w; w.x = pk2(a[0], a[1]); w.y = pk2(a[2], a[3]); w.z = pk2(b[0], b[1]); w.w = pk2(b[2], b[3]); return w; }
; DI const float* inl(const Frame& F, int idx, size_t per_layer) { return pin(F, idx) + (size_t)F.l * per_layer; }
; #define FOR_AI_M _Pragma("unroll") for (int ai = 0; ai < 2; ++ai) _Pragma("unroll") for (int m = 0; m < 4; ++m)
;     DI void operator()(Acc& acc, const Unit& u, int wr, int wc, int fr, int fq) const {
;     ...
;         if (u.pn >= 5) {
;             const int cb = (u.pn - 5) * 256; const float* bg = inl(F, I_BGATE, 3072) + cb; bf16_t* dst = (bf16_t*)(ws + WS_GATE) + cb;
;             f32x4 bv[2][2];
; #pragma unroll
;             for (int bj = 0; bj < 2; ++bj) { bv[bj][0] = *(const f32x4*)(bg + EPI_COL8(bj)); bv[bj][1] = *(const f32x4*)(bg + EPI_COL8(bj) + 4); }
;             FOR_AI_M { const int r = row0 + EPI_ROWS(ai, m);
; #pragma unroll
;                 for (int bj = 0; bj < 2; ++bj) { f32x4 a = acc[ai][bj][m][0] + bv[bj][0], b = acc[ai][bj][m][1] + bv[bj][1];
; #pragma unroll
;                     for (int e = 0; e < 4; ++e) { a[e] = __builtin_amdgcn_rcpf(1.f + __builtin_amdgcn_exp2f(-1.4426950408889634f * a[e])); b[e] = __builtin_amdgcn_rcpf(1.f + __builtin_amdgcn_exp2f(-1.4426950408889634f * b[e])); }
;                     *(u32x4*)(dst + (size_t)r * 3072 + EPI_COL8(bj)) = pk8(a, b); } }
;             return;
	v_cvt_pk_bf16_f32 v152, v151, v155
	v_cvt_pk_bf16_f32 v153, v159, v153
	v_cvt_pk_bf16_f32 v154, v154, v158
	v_cvt_pk_bf16_f32 v155, v156, v157
	v_lshl_add_u64 v[148:149], v[148:149], 0, v[96:97]
	global_store_dwordx4 v[148:149], v[152:155], off sc1
	v_pk_add_f32 v[156:157], v[26:27], v[134:135]
	v_pk_add_f32 v[158:159], v[24:25], v[132:133]
	v_pk_add_f32 v[152:153], v[34:35], v[138:139]
	v_pk_add_f32 v[154:155], v[32:33], v[136:137]
	v_mul_f32_e32 v152, 0xbfb8aa3b, v152
	v_exp_f32_e32 v152, v152
	v_mul_f32_e32 v151, 0xbfb8aa3b, v154
	v_mul_f32_e32 v154, 0xbfb8aa3b, v158
	v_mul_f32_e32 v158, 0xbfb8aa3b, v159
	v_add_f32_e32 v152, 1.0, v152
	v_rcp_f32_e32 v159, v152
	v_mul_f32_e32 v152, 0xbfb8aa3b, v156
	v_exp_f32_e32 v152, v152
	v_mul_f32_e32 v155, 0xbfb8aa3b, v155
	v_exp_f32_e32 v151, v151
	v_exp_f32_e32 v154, v154
	v_add_f32_e32 v152, 1.0, v152
	v_rcp_f32_e32 v156, v152
	v_mul_f32_e32 v152, 0xbfb8aa3b, v153
	v_exp_f32_e32 v152, v152
	v_exp_f32_e32 v155, v155
	v_exp_f32_e32 v158, v158
	v_add_f32_e32 v151, 1.0, v151
	v_add_f32_e32 v152, 1.0, v152
	v_rcp_f32_e32 v153, v152
	v_mul_f32_e32 v152, 0xbfb8aa3b, v157
	v_exp_f32_e32 v152, v152
	v_add_f32_e32 v154, 1.0, v154
	v_add_f32_e32 v155, 1.0, v155
	v_add_f32_e32 v158, 1.0, v158
	v_add_f32_e32 v152, 1.0, v152
	v_rcp_f32_e32 v151, v151
	v_rcp_f32_e32 v154, v154
	v_rcp_f32_e32 v155, v155
	v_rcp_f32_e32 v158, v158
	v_rcp_f32_e32 v157, v152
	v_cvt_pk_bf16_f32 v153, v159, v153
	v_cvt_pk_bf16_f32 v152, v151, v155
	v_cvt_pk_bf16_f32 v154, v154, v158
	v_cvt_pk_bf16_f32 v155, v156, v157
	global_store_dwordx4 v[148:149], v[152:155], off offset:256 sc1
	v_pk_add_f32 v[156:157], v[30:31], v[142:143]
	v_pk_add_f32 v[158:159], v[28:29], v[140:141]
	v_pk_add_f32 v[152:153], v[38:39], v[146:147]
	v_pk_add_f32 v[154:155], v[36:37], v[144:145]
	v_mul_f32_e32 v152, 0xbfb8aa3b, v152
	v_exp_f32_e32 v152, v152
	v_mul_f32_e32 v151, 0xbfb8aa3b, v154
	v_mul_f32_e32 v154, 0xbfb8aa3b, v158
	v_mul_f32_e32 v158, 0xbfb8aa3b, v159
	v_add_f32_e32 v152, 1.0, v152
	v_rcp_f32_e32 v159, v152
	v_mul_f32_e32 v152, 0xbfb8aa3b, v156
	v_exp_f32_e32 v152, v152
	v_mul_f32_e32 v155, 0xbfb8aa3b, v155
	v_exp_f32_e32 v151, v151
	v_exp_f32_e32 v154, v154
	v_add_f32_e32 v152, 1.0, v152
	v_rcp_f32_e32 v156, v152
	v_mul_f32_e32 v152, 0xbfb8aa3b, v153
	v_exp_f32_e32 v152, v152
	v_exp_f32_e32 v155, v155
	v_exp_f32_e32 v158, v158
	v_add_f32_e32 v151, 1.0, v151
	v_add_f32_e32 v152, 1.0, v152
	v_rcp_f32_e32 v153, v152
	v_mul_f32_e32 v152, 0xbfb8aa3b, v157
	v_exp_f32_e32 v152, v152
	v_add_f32_e32 v154, 1.0, v154
	v_add_f32_e32 v155, 1.0, v155
	v_add_f32_e32 v158, 1.0, v158
	v_add_f32_e32 v152, 1.0, v152
	v_rcp_f32_e32 v151, v151
	v_rcp_f32_e32 v154, v154
	v_rcp_f32_e32 v155, v155
	v_rcp_f32_e32 v158, v158
	v_rcp_f32_e32 v157, v152
	v_add_u32_e32 v148, 0xa0, v150
	v_mad_i64_i32 v[148:149], s[6:7], v148, s8, v[98:99]
	v_cvt_pk_bf16_f32 v152, v151, v155
	v_cvt_pk_bf16_f32 v153, v159, v153
	v_cvt_pk_bf16_f32 v154, v154, v158
	v_cvt_pk_bf16_f32 v155, v156, v157
	v_lshl_add_u64 v[148:149], v[148:149], 0, v[96:97]
	global_store_dwordx4 v[148:149], v[152:155], off sc1
	v_pk_add_f32 v[156:157], v[10:11], v[134:135]
	v_pk_add_f32 v[158:159], v[8:9], v[132:133]
	v_pk_add_f32 v[152:153], v[18:19], v[138:139]
	v_pk_add_f32 v[154:155], v[16:17], v[136:137]
	v_mul_f32_e32 v152, 0xbfb8aa3b, v152
	v_exp_f32_e32 v152, v152
	v_mul_f32_e32 v151, 0xbfb8aa3b, v154
	v_mul_f32_e32 v154, 0xbfb8aa3b, v158
	v_mul_f32_e32 v158, 0xbfb8aa3b, v159
	v_add_f32_e32 v152, 1.0, v152
	v_rcp_f32_e32 v159, v152
	v_mul_f32_e32 v152, 0xbfb8aa3b, v156
	v_exp_f32_e32 v152, v152
	v_mul_f32_e32 v155, 0xbfb8aa3b, v155
	v_exp_f32_e32 v151, v151
; DI u32x4 pk8(const f32x4& a, const f32x4& b) { u32x4 w; w.x = pk2(a[0], a[1]); w.y = pk2(a[2], a[3]); w.z = pk2(b[0], b[1]); w.w = pk2(b[2], b[3]); return w; }
; DI const float* inl(const Frame& F, int idx, size_t per_layer) { return pin(F, idx) + (size_t)F.l * per_layer; }
; #define FOR_AI_M _Pragma("unroll") for (int ai = 0; ai < 2; ++ai) _Pragma("unroll") for (int m = 0; m < 4; ++m)
;     DI void operator()(Acc& acc, const Unit& u, int wr, int wc, int fr, int fq) const {
;     ...
;         if (u.pn >= 5) {
;             const int cb = (u.pn - 5) * 256; const float* bg = inl(F, I_BGATE, 3072) + cb; bf16_t* dst = (bf16_t*)(ws + WS_GATE) + cb;
;             f32x4 bv[2][2];
; #pragma unroll
;             for (int bj = 0; bj < 2; ++bj) { bv[bj][0] = *(const f32x4*)(bg + EPI_COL8(bj)); bv[bj][1] = *(const f32x4*)(bg + EPI_COL8(bj) + 4); }
;             FOR_AI_M { const int r = row0 + EPI_ROWS(ai, m);
; #pragma unroll
;                 for (int bj = 0; bj < 2; ++bj) { f32x4 a = acc[ai][bj][m][0] + bv[bj][0], b = acc[ai][bj][m][1] + bv[bj][1];
; #pragma unroll
;                     for (int e = 0; e < 4; ++e) { a[e] = __builtin_amdgcn_rcpf(1.f + __builtin_amdgcn_exp2f(-1.4426950408889634f * a[e])); b[e] = __builtin_amdgcn_rcpf(1.f + __builtin_amdgcn_exp2f(-1.4426950408889634f * b[e])); }
;                     *(u32x4*)(dst + (size_t)r * 3072 + EPI_COL8(bj)) = pk8(a, b); } }
;             return;
	v_exp_f32_e32 v154, v154
	v_add_f32_e32 v152, 1.0, v152
	v_rcp_f32_e32 v156, v152
	v_mul_f32_e32 v152, 0xbfb8aa3b, v153
	v_exp_f32_e32 v152, v152
	v_exp_f32_e32 v155, v155
	v_exp_f32_e32 v158, v158
	v_add_f32_e32 v151, 1.0, v151
	v_add_f32_e32 v152, 1.0, v152
	v_rcp_f32_e32 v153, v152
	v_mul_f32_e32 v152, 0xbfb8aa3b, v157
	v_exp_f32_e32 v152, v152
	v_add_f32_e32 v154, 1.0, v154
	v_add_f32_e32 v155, 1.0, v155
	v_add_f32_e32 v158, 1.0, v158
	v_add_f32_e32 v152, 1.0, v152
	v_rcp_f32_e32 v151, v151
	v_rcp_f32_e32 v154, v154
	v_rcp_f32_e32 v155, v155
	v_rcp_f32_e32 v158, v158
	v_rcp_f32_e32 v157, v152
	v_pk_add_f32 v[142:143], v[14:15], v[142:143]
	v_pk_add_f32 v[140:141], v[12:13], v[140:141]
	v_pk_add_f32 v[134:135], v[2:3], v[134:135]
	v_pk_add_f32 v[132:133], v[0:1], v[132:133]
	v_mul_f32_e32 v140, 0xbfb8aa3b, v140
	v_mul_f32_e32 v141, 0xbfb8aa3b, v141
	v_mul_f32_e32 v142, 0xbfb8aa3b, v142
	v_mul_f32_e32 v132, 0xbfb8aa3b, v132
	v_mul_f32_e32 v133, 0xbfb8aa3b, v133
	v_mul_f32_e32 v134, 0xbfb8aa3b, v134
	v_exp_f32_e32 v140, v140
	v_exp_f32_e32 v141, v141
	v_exp_f32_e32 v142, v142
	v_exp_f32_e32 v132, v132
	v_exp_f32_e32 v133, v133
	v_exp_f32_e32 v134, v134
	v_cvt_pk_bf16_f32 v152, v151, v155
	v_cvt_pk_bf16_f32 v153, v159, v153
	v_cvt_pk_bf16_f32 v154, v154, v158
	v_cvt_pk_bf16_f32 v155, v156, v157
	global_store_dwordx4 v[148:149], v[152:155], off offset:256 sc1
	v_add_u32_e32 v148, 0xb0, v150
	v_mad_i64_i32 v[98:99], s[6:7], v148, s8, v[98:99]
	v_pk_add_f32 v[146:147], v[22:23], v[146:147]
	v_pk_add_f32 v[144:145], v[20:21], v[144:145]
	v_add_f32_e32 v140, 1.0, v140
	v_add_f32_e32 v141, 1.0, v141
	v_add_f32_e32 v142, 1.0, v142
	v_pk_add_f32 v[138:139], v[6:7], v[138:139]
	v_pk_add_f32 v[136:137], v[4:5], v[136:137]
	v_add_f32_e32 v132, 1.0, v132
	v_add_f32_e32 v133, 1.0, v133
	v_add_f32_e32 v134, 1.0, v134
	v_mul_f32_e32 v144, 0xbfb8aa3b, v144
	v_rcp_f32_e32 v148, v140
	v_mul_f32_e32 v140, 0xbfb8aa3b, v145
	v_rcp_f32_e32 v145, v141
	v_mul_f32_e32 v141, 0xbfb8aa3b, v146
	v_rcp_f32_e32 v146, v142
	v_mul_f32_e32 v142, 0xbfb8aa3b, v147
	v_mul_f32_e32 v143, 0xbfb8aa3b, v143
	v_lshl_add_u64 v[98:99], v[98:99], 0, v[96:97]
	v_mul_f32_e32 v96, 0xbfb8aa3b, v136
	v_rcp_f32_e32 v136, v132
	v_mul_f32_e32 v132, 0xbfb8aa3b, v137
	v_rcp_f32_e32 v137, v133
	v_mul_f32_e32 v133, 0xbfb8aa3b, v138
	v_rcp_f32_e32 v138, v134
	v_mul_f32_e32 v134, 0xbfb8aa3b, v139
	v_mul_f32_e32 v135, 0xbfb8aa3b, v135
	v_exp_f32_e32 v144, v144
	v_exp_f32_e32 v140, v140
	v_exp_f32_e32 v141, v141
	v_exp_f32_e32 v142, v142
	v_exp_f32_e32 v143, v143
	v_exp_f32_e32 v96, v96
	v_exp_f32_e32 v132, v132
	v_exp_f32_e32 v133, v133
	v_exp_f32_e32 v134, v134
	v_exp_f32_e32 v135, v135
	v_add_f32_e32 v144, 1.0, v144
	v_add_f32_e32 v140, 1.0, v140
	v_add_f32_e32 v141, 1.0, v141
	v_add_f32_e32 v142, 1.0, v142
	v_add_f32_e32 v143, 1.0, v143
	v_add_f32_e32 v96, 1.0, v96
	v_add_f32_e32 v132, 1.0, v132
	v_add_f32_e32 v133, 1.0, v133
	v_add_f32_e32 v134, 1.0, v134
	v_add_f32_e32 v135, 1.0, v135
	v_rcp_f32_e32 v144, v144
	v_rcp_f32_e32 v140, v140
	v_rcp_f32_e32 v141, v141
	v_rcp_f32_e32 v142, v142
	v_rcp_f32_e32 v143, v143
	v_rcp_f32_e32 v96, v96
	v_rcp_f32_e32 v132, v132
	v_rcp_f32_e32 v133, v133
	v_rcp_f32_e32 v134, v134
	v_rcp_f32_e32 v135, v135
	v_cvt_pk_bf16_f32 v140, v144, v140
	v_cvt_pk_bf16_f32 v141, v141, v142
	v_cvt_pk_bf16_f32 v142, v148, v145
	v_cvt_pk_bf16_f32 v143, v146, v143
	v_cvt_pk_bf16_f32 v132, v96, v132
	v_cvt_pk_bf16_f32 v133, v133, v134
	v_cvt_pk_bf16_f32 v134, v136, v137
	v_cvt_pk_bf16_f32 v135, v138, v135
	global_store_dwordx4 v[98:99], v[140:143], off sc1
	global_store_dwordx4 v[98:99], v[132:135], off offset:256 sc1

; DI u32x4 pk8(const f32x4& a, const f32x4& b) { u32x4 w; w.x = pk2(a[0], a[1]); w.y = pk2(a[2], a[3]); w.z = pk2(b[0], b[1]); w.w = pk2(b[2], b[3]); return w; }
; DI float shx(float v, int m, int lane) { return __int_as_float(__builtin_amdgcn_ds_bpermute((lane ^ m) << 2, __float_as_int(v))); }
; #define FOR_AI_M _Pragma("unroll") for (int ai = 0; ai < 2; ++ai) _Pragma("unroll") for (int m = 0; m < 4; ++m)
;     DI void operator()(Acc& acc, const Unit& u, int wr, int wc, int fr, int fq) const {
;     ...
;         const int row0 = u.pm * 256;
;         if (u.pn <= 1) {
;             bf16_t* dst = (bf16_t*)(ws + (u.pn == 0 ? WS_CKV : WS_CQ)); float* ss = (float*)(ws + (u.pn == 0 ? WS_SSKV : WS_SSQ));
;             FOR_AI_M { const int r = row0 + EPI_ROWS(ai, m); float s = 0.f;
; #pragma unroll
;                 for (int bj = 0; bj < 2; ++bj) { const f32x4 a = acc[ai][bj][m][0], b = acc[ai][bj][m][1];
;                     s += (a[0] * a[0] + a[1] * a[1]) + (a[2] * a[2] + a[3] * a[3]) + (b[0] * b[0] + b[1] * b[1]) + (b[2] * b[2] + b[3] * b[3]);
;                     *(u32x4*)(dst + (size_t)r * 256 + EPI_COL8(bj)) = pk8(a, b); }
;                 s += shx(s, 16, fr + 16 * fq); s += shx(s, 32, fr + 16 * fq);
;                 if (fq == 0) ss[(size_t)r * 4 + wc] = s; }
;             return;
.LBB0_639:
	s_andn2_b64 vcc, exec, s[6:7]
	s_cbranch_vccnz .LBB0_657
	s_cmp_eq_u32 s50, 0
	s_mov_b32 s6, 0x6200000
	s_cselect_b32 s6, s6, 0x6b00000
	s_mov_b32 s7, 0x300000
	v_add_u32_e32 v98, s21, v173
	s_cselect_b32 s7, s7, 0x380000
	s_add_u32 s8, s94, s6
	v_ashrrev_i32_e32 v99, 31, v98
	s_addc_u32 s9, s95, 0
	s_waitcnt lgkmcnt(0)
	v_lshlrev_b64 v[132:133], 9, v[98:99]
	v_lshl_add_u64 v[136:137], s[8:9], 0, v[132:133]
	v_mul_f32_e32 v96, v129, v129
	v_mul_f32_e32 v132, v131, v131
	v_fmac_f32_e32 v96, v128, v128
	v_fmac_f32_e32 v132, v130, v130
	v_add_f32_e32 v96, v96, v132
	v_mul_f32_e32 v132, v125, v125
	v_fmac_f32_e32 v132, v124, v124
	v_add_f32_e32 v96, v132, v96
	v_mul_f32_e32 v132, v127, v127
	v_fmac_f32_e32 v132, v126, v126
	v_add_f32_e32 v138, v132, v96
	v_lshlrev_b32_e32 v96, 1, v174
	v_cvt_pk_bf16_f32 v132, v128, v129
	v_cvt_pk_bf16_f32 v133, v130, v131
	v_cvt_pk_bf16_f32 v134, v124, v125
	v_cvt_pk_bf16_f32 v135, v126, v127
	v_lshl_add_u64 v[136:137], v[136:137], 0, v[96:97]
	global_store_dwordx4 v[136:137], v[132:135], off sc1
	s_add_u32 s6, s37, s7
	s_addc_u32 s7, s36, 0
	v_mul_f32_e32 v132, v117, v117
	v_mul_f32_e32 v133, v119, v119
	v_fmac_f32_e32 v132, v116, v116
	v_fmac_f32_e32 v133, v118, v118
	v_add_f32_e32 v132, v132, v133
	v_mul_f32_e32 v133, v109, v109
	v_fmac_f32_e32 v133, v108, v108
	v_add_f32_e32 v132, v133, v132
	v_mul_f32_e32 v133, v111, v111
	v_fmac_f32_e32 v133, v110, v110
	v_add_f32_e32 v132, v133, v132
	v_add_f32_e32 v138, v132, v138
	v_cvt_pk_bf16_f32 v132, v116, v117
	v_cvt_pk_bf16_f32 v133, v118, v119
	v_cvt_pk_bf16_f32 v134, v108, v109
	v_cvt_pk_bf16_f32 v135, v110, v111
	global_store_dwordx4 v[136:137], v[132:135], off offset:256 sc1
	ds_bpermute_b32 v132, v194, v138
	s_waitcnt lgkmcnt(0)
	v_add_f32_e32 v132, v138, v132
	ds_bpermute_b32 v133, v195, v132
	s_and_saveexec_b64 s[10:11], s[2:3]
	s_cbranch_execz .LBB0_642
	s_waitcnt lgkmcnt(0)
	v_add_f32_e32 v134, v132, v133
	v_lshl_add_u64 v[132:133], v[98:99], 4, s[6:7]
	global_store_dword v[132:133], v134, off
.LBB0_642:
	s_or_b64 exec, exec, s[10:11]
	v_or_b32_e32 v132, 16, v98
	s_waitcnt lgkmcnt(0)
	v_ashrrev_i32_e32 v133, 31, v132
	v_lshlrev_b64 v[134:135], 9, v[132:133]
	v_lshl_add_u64 v[138:139], s[8:9], 0, v[134:135]
	v_mul_f32_e32 v99, v121, v121
	v_mul_f32_e32 v134, v123, v123
	v_fmac_f32_e32 v99, v120, v120
	v_fmac_f32_e32 v134, v122, v122
	v_add_f32_e32 v99, v99, v134
	v_mul_f32_e32 v134, v113, v113
	v_fmac_f32_e32 v134, v112, v112
	v_add_f32_e32 v99, v134, v99
	v_mul_f32_e32 v134, v115, v115
	v_fmac_f32_e32 v134, v114, v114
	v_add_f32_e32 v99, v134, v99
	v_cvt_pk_bf16_f32 v134, v120, v121
	v_cvt_pk_bf16_f32 v135, v122, v123
	v_cvt_pk_bf16_f32 v136, v112, v113
	v_cvt_pk_bf16_f32 v137, v114, v115
	v_lshl_add_u64 v[138:139], v[138:139], 0, v[96:97]
	global_store_dwordx4 v[138:139], v[134:137], off sc1
	s_nop 1
	v_mul_f32_e32 v134, v101, v101
	v_mul_f32_e32 v135, v103, v103
	v_fmac_f32_e32 v134, v100, v100
	v_fmac_f32_e32 v135, v102, v102
	v_add_f32_e32 v134, v134, v135
	v_mul_f32_e32 v135, v89, v89
	v_fmac_f32_e32 v135, v88, v88
	v_add_f32_e32 v134, v135, v134
	v_mul_f32_e32 v135, v91, v91
	v_fmac_f32_e32 v135, v90, v90
	v_add_f32_e32 v134, v135, v134
	v_add_f32_e32 v99, v134, v99
	v_cvt_pk_bf16_f32 v134, v100, v101
	v_cvt_pk_bf16_f32 v135, v102, v103
	v_cvt_pk_bf16_f32 v136, v88, v89
	v_cvt_pk_bf16_f32 v137, v90, v91
	global_store_dwordx4 v[138:139], v[134:137], off offset:256 sc1
	ds_bpermute_b32 v134, v194, v99
	s_waitcnt lgkmcnt(0)
	v_add_f32_e32 v99, v99, v134
	ds_bpermute_b32 v134, v195, v99
	s_and_saveexec_b64 s[10:11], s[2:3]
	s_cbranch_execz .LBB0_644
	s_waitcnt lgkmcnt(0)
	v_add_f32_e32 v99, v99, v134
	v_lshl_add_u64 v[132:133], v[132:133], 4, s[6:7]
	global_store_dword v[132:133], v99, off
.LBB0_644:
	s_or_b64 exec, exec, s[10:11]
	v_or_b32_e32 v132, 32, v98
	v_ashrrev_i32_e32 v133, 31, v132
	s_waitcnt lgkmcnt(0)
	v_lshlrev_b64 v[134:135], 9, v[132:133]
	v_lshl_add_u64 v[138:139], s[8:9], 0, v[134:135]
	v_mul_f32_e32 v99, v105, v105
	v_mul_f32_e32 v134, v107, v107
	v_fmac_f32_e32 v99, v104, v104
	v_fmac_f32_e32 v134, v106, v106
	v_add_f32_e32 v99, v99, v134
	v_mul_f32_e32 v134, v93, v93
	v_fmac_f32_e32 v134, v92, v92
	v_add_f32_e32 v99, v134, v99
	v_mul_f32_e32 v134, v95, v95
	v_fmac_f32_e32 v134, v94, v94
	v_add_f32_e32 v99, v134, v99
	v_cvt_pk_bf16_f32 v134, v104, v105
	v_cvt_pk_bf16_f32 v135, v106, v107
	v_cvt_pk_bf16_f32 v136, v92, v93
	v_cvt_pk_bf16_f32 v137, v94, v95
	v_lshl_add_u64 v[138:139], v[138:139], 0, v[96:97]
	global_store_dwordx4 v[138:139], v[134:137], off sc1
	s_nop 1
	v_mul_f32_e32 v134, v81, v81
	v_mul_f32_e32 v135, v83, v83
	v_fmac_f32_e32 v134, v80, v80
	v_fmac_f32_e32 v135, v82, v82
	v_add_f32_e32 v134, v134, v135
	v_mul_f32_e32 v135, v73, v73
	v_fmac_f32_e32 v135, v72, v72
	v_add_f32_e32 v134, v135, v134
	v_mul_f32_e32 v135, v75, v75
	v_fmac_f32_e32 v135, v74, v74
	v_add_f32_e32 v134, v135, v134
	v_add_f32_e32 v99, v134, v99
	v_cvt_pk_bf16_f32 v134, v80, v81
	v_cvt_pk_bf16_f32 v135, v82, v83
	v_cvt_pk_bf16_f32 v136, v72, v73
	v_cvt_pk_bf16_f32 v137, v74, v75
	global_store_dwordx4 v[138:139], v[134:137], off offset:256 sc1
	ds_bpermute_b32 v134, v194, v99
	s_waitcnt lgkmcnt(0)
	v_add_f32_e32 v99, v99, v134
	ds_bpermute_b32 v134, v195, v99
	s_and_saveexec_b64 s[10:11], s[2:3]
	s_cbranch_execz .LBB0_646
	s_waitcnt lgkmcnt(0)
	v_add_f32_e32 v99, v99, v134
	v_lshl_add_u64 v[132:133], v[132:133], 4, s[6:7]
	global_store_dword v[132:133], v99, off
; DI u32x4 pk8(const f32x4& a, const f32x4& b) { u32x4 w; w.x = pk2(a[0], a[1]); w.y = pk2(a[2], a[3]); w.z = pk2(b[0], b[1]); w.w = pk2(b[2], b[3]); return w; }
; DI float shx(float v, int m, int lane) { return __int_as_float(__builtin_amdgcn_ds_bpermute((lane ^ m) << 2, __float_as_int(v))); }
; #define FOR_AI_M _Pragma("unroll") for (int ai = 0; ai < 2; ++ai) _Pragma("unroll") for (int m = 0; m < 4; ++m)
;     DI void operator()(Acc& acc, const Unit& u, int wr, int wc, int fr, int fq) const {
;     ...
;             FOR_AI_M { const int r = row0 + EPI_ROWS(ai, m); float s = 0.f;
; #pragma unroll
;                 for (int bj = 0; bj < 2; ++bj) { const f32x4 a = acc[ai][bj][m][0], b = acc[ai][bj][m][1];
;                     s += (a[0] * a[0] + a[1] * a[1]) + (a[2] * a[2] + a[3] * a[3]) + (b[0] * b[0] + b[1] * b[1]) + (b[2] * b[2] + b[3] * b[3]);
;                     *(u32x4*)(dst + (size_t)r * 256 + EPI_COL8(bj)) = pk8(a, b); }
;                 s += shx(s, 16, fr + 16 * fq); s += shx(s, 32, fr + 16 * fq);
;                 if (fq == 0) ss[(size_t)r * 4 + wc] = s; }
.LBB0_646:
	s_or_b64 exec, exec, s[10:11]
	v_or_b32_e32 v132, 48, v98
	v_ashrrev_i32_e32 v133, 31, v132
	s_waitcnt lgkmcnt(0)
	v_lshlrev_b64 v[134:135], 9, v[132:133]
	v_lshl_add_u64 v[138:139], s[8:9], 0, v[134:135]
	v_mul_f32_e32 v99, v85, v85
	v_mul_f32_e32 v134, v87, v87
	v_fmac_f32_e32 v99, v84, v84
	v_fmac_f32_e32 v134, v86, v86
	v_add_f32_e32 v99, v99, v134
	v_mul_f32_e32 v134, v77, v77
	v_fmac_f32_e32 v134, v76, v76
	v_add_f32_e32 v99, v134, v99
	v_mul_f32_e32 v134, v79, v79
	v_fmac_f32_e32 v134, v78, v78
	v_add_f32_e32 v99, v134, v99
	v_cvt_pk_bf16_f32 v134, v84, v85
	v_cvt_pk_bf16_f32 v135, v86, v87
	v_cvt_pk_bf16_f32 v136, v76, v77
	v_cvt_pk_bf16_f32 v137, v78, v79
	v_lshl_add_u64 v[138:139], v[138:139], 0, v[96:97]
	global_store_dwordx4 v[138:139], v[134:137], off sc1
	s_nop 1
	v_mul_f32_e32 v134, v69, v69
	v_mul_f32_e32 v135, v71, v71
	v_fmac_f32_e32 v134, v68, v68
	v_fmac_f32_e32 v135, v70, v70
	v_add_f32_e32 v134, v134, v135
	v_mul_f32_e32 v135, v65, v65
	v_fmac_f32_e32 v135, v64, v64
	v_add_f32_e32 v134, v135, v134
	v_mul_f32_e32 v135, v67, v67
	v_fmac_f32_e32 v135, v66, v66
	v_add_f32_e32 v134, v135, v134
	v_add_f32_e32 v99, v134, v99
	v_cvt_pk_bf16_f32 v134, v68, v69
	v_cvt_pk_bf16_f32 v135, v70, v71
	v_cvt_pk_bf16_f32 v136, v64, v65
	v_cvt_pk_bf16_f32 v137, v66, v67
	global_store_dwordx4 v[138:139], v[134:137], off offset:256 sc1
	ds_bpermute_b32 v134, v194, v99
	s_waitcnt lgkmcnt(0)
	v_add_f32_e32 v99, v99, v134
	ds_bpermute_b32 v134, v195, v99
	s_and_saveexec_b64 s[10:11], s[2:3]
	s_cbranch_execz .LBB0_648
	s_waitcnt lgkmcnt(0)
	v_add_f32_e32 v99, v99, v134
	v_lshl_add_u64 v[132:133], v[132:133], 4, s[6:7]
	global_store_dword v[132:133], v99, off
.LBB0_648:
	s_or_b64 exec, exec, s[10:11]
	v_add_u32_e32 v132, 0x80, v98
	v_ashrrev_i32_e32 v133, 31, v132
	s_waitcnt lgkmcnt(0)
	v_lshlrev_b64 v[134:135], 9, v[132:133]
	v_lshl_add_u64 v[138:139], s[8:9], 0, v[134:135]
	v_mul_f32_e32 v99, v61, v61
	v_mul_f32_e32 v134, v63, v63
	v_fmac_f32_e32 v99, v60, v60
	v_fmac_f32_e32 v134, v62, v62
	v_add_f32_e32 v99, v99, v134
	v_mul_f32_e32 v134, v57, v57
	v_fmac_f32_e32 v134, v56, v56
	v_add_f32_e32 v99, v134, v99
	v_mul_f32_e32 v134, v59, v59
	v_fmac_f32_e32 v134, v58, v58
	v_add_f32_e32 v99, v134, v99
	v_cvt_pk_bf16_f32 v134, v60, v61
	v_cvt_pk_bf16_f32 v135, v62, v63
	v_cvt_pk_bf16_f32 v136, v56, v57
	v_cvt_pk_bf16_f32 v137, v58, v59
	v_lshl_add_u64 v[138:139], v[138:139], 0, v[96:97]
	global_store_dwordx4 v[138:139], v[134:137], off sc1
	s_nop 1
	v_mul_f32_e32 v134, v49, v49
	v_mul_f32_e32 v135, v51, v51
	v_fmac_f32_e32 v134, v48, v48
	v_fmac_f32_e32 v135, v50, v50
	v_add_f32_e32 v134, v134, v135
	v_mul_f32_e32 v135, v41, v41
	v_fmac_f32_e32 v135, v40, v40
	v_add_f32_e32 v134, v135, v134
	v_mul_f32_e32 v135, v43, v43
	v_fmac_f32_e32 v135, v42, v42
	v_add_f32_e32 v134, v135, v134
	v_add_f32_e32 v99, v134, v99
	v_cvt_pk_bf16_f32 v134, v48, v49
	v_cvt_pk_bf16_f32 v135, v50, v51
	v_cvt_pk_bf16_f32 v136, v40, v41
	v_cvt_pk_bf16_f32 v137, v42, v43
	global_store_dwordx4 v[138:139], v[134:137], off offset:256 sc1
	ds_bpermute_b32 v134, v194, v99
	s_waitcnt lgkmcnt(0)
	v_add_f32_e32 v99, v99, v134
	ds_bpermute_b32 v134, v195, v99
	s_and_saveexec_b64 s[10:11], s[2:3]
	s_cbranch_execz .LBB0_650
	s_waitcnt lgkmcnt(0)
	v_add_f32_e32 v99, v99, v134
	v_lshl_add_u64 v[132:133], v[132:133], 4, s[6:7]
	global_store_dword v[132:133], v99, off
; DI u32x4 pk8(const f32x4& a, const f32x4& b) { u32x4 w; w.x = pk2(a[0], a[1]); w.y = pk2(a[2], a[3]); w.z = pk2(b[0], b[1]); w.w = pk2(b[2], b[3]); return w; }
; DI float shx(float v, int m, int lane) { return __int_as_float(__builtin_amdgcn_ds_bpermute((lane ^ m) << 2, __float_as_int(v))); }
; #define FOR_AI_M _Pragma("unroll") for (int ai = 0; ai < 2; ++ai) _Pragma("unroll") for (int m = 0; m < 4; ++m)
;     DI void operator()(Acc& acc, const Unit& u, int wr, int wc, int fr, int fq) const {
;     ...
;             FOR_AI_M { const int r = row0 + EPI_ROWS(ai, m); float s = 0.f;
; #pragma unroll
;                 for (int bj = 0; bj < 2; ++bj) { const f32x4 a = acc[ai][bj][m][0], b = acc[ai][bj][m][1];
;                     s += (a[0] * a[0] + a[1] * a[1]) + (a[2] * a[2] + a[3] * a[3]) + (b[0] * b[0] + b[1] * b[1]) + (b[2] * b[2] + b[3] * b[3]);
;                     *(u32x4*)(dst + (size_t)r * 256 + EPI_COL8(bj)) = pk8(a, b); }
;                 s += shx(s, 16, fr + 16 * fq); s += shx(s, 32, fr + 16 * fq);
;                 if (fq == 0) ss[(size_t)r * 4 + wc] = s; }
.LBB0_650:
	s_or_b64 exec, exec, s[10:11]
	v_add_u32_e32 v132, 0x90, v98
	v_ashrrev_i32_e32 v133, 31, v132
	s_waitcnt lgkmcnt(0)
	v_lshlrev_b64 v[134:135], 9, v[132:133]
	v_lshl_add_u64 v[138:139], s[8:9], 0, v[134:135]
	v_mul_f32_e32 v99, v53, v53
	v_mul_f32_e32 v134, v55, v55
	v_fmac_f32_e32 v99, v52, v52
	v_fmac_f32_e32 v134, v54, v54
	v_add_f32_e32 v99, v99, v134
	v_mul_f32_e32 v134, v45, v45
	v_fmac_f32_e32 v134, v44, v44
	v_add_f32_e32 v99, v134, v99
	v_mul_f32_e32 v134, v47, v47
	v_fmac_f32_e32 v134, v46, v46
	v_add_f32_e32 v99, v134, v99
	v_cvt_pk_bf16_f32 v134, v52, v53
	v_cvt_pk_bf16_f32 v135, v54, v55
	v_cvt_pk_bf16_f32 v136, v44, v45
	v_cvt_pk_bf16_f32 v137, v46, v47
	v_lshl_add_u64 v[138:139], v[138:139], 0, v[96:97]
	global_store_dwordx4 v[138:139], v[134:137], off sc1
	s_nop 1
	v_mul_f32_e32 v134, v33, v33
	v_mul_f32_e32 v135, v35, v35
	v_fmac_f32_e32 v134, v32, v32
	v_fmac_f32_e32 v135, v34, v34
	v_add_f32_e32 v134, v134, v135
	v_mul_f32_e32 v135, v25, v25
	v_fmac_f32_e32 v135, v24, v24
	v_add_f32_e32 v134, v135, v134
	v_mul_f32_e32 v135, v27, v27
	v_fmac_f32_e32 v135, v26, v26
	v_add_f32_e32 v134, v135, v134
	v_add_f32_e32 v99, v134, v99
	v_cvt_pk_bf16_f32 v134, v32, v33
	v_cvt_pk_bf16_f32 v135, v34, v35
	v_cvt_pk_bf16_f32 v136, v24, v25
	v_cvt_pk_bf16_f32 v137, v26, v27
	global_store_dwordx4 v[138:139], v[134:137], off offset:256 sc1
	ds_bpermute_b32 v134, v194, v99
	s_waitcnt lgkmcnt(0)
	v_add_f32_e32 v99, v99, v134
	ds_bpermute_b32 v134, v195, v99
	s_and_saveexec_b64 s[10:11], s[2:3]
	s_cbranch_execz .LBB0_652
	s_waitcnt lgkmcnt(0)
	v_add_f32_e32 v99, v99, v134
	v_lshl_add_u64 v[132:133], v[132:133], 4, s[6:7]
	global_store_dword v[132:133], v99, off
.LBB0_652:
	s_or_b64 exec, exec, s[10:11]
	v_add_u32_e32 v132, 0xa0, v98
	v_ashrrev_i32_e32 v133, 31, v132
	s_waitcnt lgkmcnt(0)
	v_lshlrev_b64 v[134:135], 9, v[132:133]
	v_lshl_add_u64 v[138:139], s[8:9], 0, v[134:135]
	v_mul_f32_e32 v99, v37, v37
	v_mul_f32_e32 v134, v39, v39
	v_fmac_f32_e32 v99, v36, v36
	v_fmac_f32_e32 v134, v38, v38
	v_add_f32_e32 v99, v99, v134
	v_mul_f32_e32 v134, v29, v29
	v_fmac_f32_e32 v134, v28, v28
	v_add_f32_e32 v99, v134, v99
	v_mul_f32_e32 v134, v31, v31
	v_fmac_f32_e32 v134, v30, v30
	v_add_f32_e32 v99, v134, v99
	v_cvt_pk_bf16_f32 v134, v36, v37
	v_cvt_pk_bf16_f32 v135, v38, v39
	v_cvt_pk_bf16_f32 v136, v28, v29
	v_cvt_pk_bf16_f32 v137, v30, v31
	v_lshl_add_u64 v[138:139], v[138:139], 0, v[96:97]
	global_store_dwordx4 v[138:139], v[134:137], off sc1
	s_nop 1
	v_mul_f32_e32 v134, v17, v17
	v_mul_f32_e32 v135, v19, v19
	v_fmac_f32_e32 v134, v16, v16
	v_fmac_f32_e32 v135, v18, v18
	v_add_f32_e32 v134, v134, v135
	v_mul_f32_e32 v135, v9, v9
	v_fmac_f32_e32 v135, v8, v8
	v_add_f32_e32 v134, v135, v134
	v_mul_f32_e32 v135, v11, v11
	v_fmac_f32_e32 v135, v10, v10
	v_add_f32_e32 v134, v135, v134
	v_add_f32_e32 v99, v134, v99
	v_cvt_pk_bf16_f32 v134, v16, v17
	v_cvt_pk_bf16_f32 v135, v18, v19
	v_cvt_pk_bf16_f32 v136, v8, v9
	v_cvt_pk_bf16_f32 v137, v10, v11
	global_store_dwordx4 v[138:139], v[134:137], off offset:256 sc1
	ds_bpermute_b32 v134, v194, v99
	s_waitcnt lgkmcnt(0)
	v_add_f32_e32 v99, v99, v134
	ds_bpermute_b32 v134, v195, v99
	s_and_saveexec_b64 s[10:11], s[2:3]
	s_cbranch_execz .LBB0_654
	s_waitcnt lgkmcnt(0)
	v_add_f32_e32 v99, v99, v134
	v_lshl_add_u64 v[132:133], v[132:133], 4, s[6:7]
	global_store_dword v[132:133], v99, off
.LBB0_654:
	s_or_b64 exec, exec, s[10:11]
	v_add_u32_e32 v98, 0xb0, v98
	v_ashrrev_i32_e32 v99, 31, v98
	v_lshlrev_b64 v[132:133], 9, v[98:99]
	v_lshl_add_u64 v[136:137], s[8:9], 0, v[132:133]
	v_mul_f32_e32 v132, v21, v21
	v_mul_f32_e32 v133, v23, v23
	v_fmac_f32_e32 v132, v20, v20
	v_fmac_f32_e32 v133, v22, v22
	v_add_f32_e32 v132, v132, v133
	v_mul_f32_e32 v133, v13, v13
	v_fmac_f32_e32 v133, v12, v12
	v_add_f32_e32 v132, v133, v132
	v_mul_f32_e32 v133, v15, v15
	v_fmac_f32_e32 v133, v14, v14
	v_add_f32_e32 v138, v133, v132
	v_cvt_pk_bf16_f32 v132, v20, v21
	v_cvt_pk_bf16_f32 v133, v22, v23
	s_waitcnt lgkmcnt(0)
	v_cvt_pk_bf16_f32 v134, v12, v13
	v_cvt_pk_bf16_f32 v135, v14, v15
	v_lshl_add_u64 v[136:137], v[136:137], 0, v[96:97]
	global_store_dwordx4 v[136:137], v[132:135], off sc1
	v_mul_f32_e32 v96, v5, v5
	v_fmac_f32_e32 v96, v4, v4
	v_mul_f32_e32 v132, v7, v7
	v_fmac_f32_e32 v132, v6, v6
	v_add_f32_e32 v96, v96, v132
	v_mul_f32_e32 v132, v1, v1
	v_fmac_f32_e32 v132, v0, v0
	v_add_f32_e32 v96, v132, v96
	v_mul_f32_e32 v132, v3, v3
	v_fmac_f32_e32 v132, v2, v2
	v_add_f32_e32 v96, v132, v96
	v_add_f32_e32 v96, v96, v138
	v_cvt_pk_bf16_f32 v132, v4, v5
	v_cvt_pk_bf16_f32 v133, v6, v7
	v_cvt_pk_bf16_f32 v134, v0, v1
	v_cvt_pk_bf16_f32 v135, v2, v3
	global_store_dwordx4 v[136:137], v[132:135], off offset:256 sc1
	ds_bpermute_b32 v132, v194, v96
	s_waitcnt lgkmcnt(0)
	v_add_f32_e32 v96, v96, v132
	ds_bpermute_b32 v132, v195, v96
	s_and_saveexec_b64 s[8:9], s[2:3]
	s_cbranch_execz .LBB0_656
	s_waitcnt lgkmcnt(0)
	v_add_f32_e32 v96, v96, v132
	v_lshl_add_u64 v[98:99], v[98:99], 4, s[6:7]
	global_store_dword v[98:99], v96, off

; DI u32x4 pk8(const f32x4& a, const f32x4& b) { u32x4 w; w.x = pk2(a[0], a[1]); w.y = pk2(a[2], a[3]); w.z = pk2(b[0], b[1]); w.w = pk2(b[2], b[3]); return w; }
; #define FOR_AI_M _Pragma("unroll") for (int ai = 0; ai < 2; ++ai) _Pragma("unroll") for (int m = 0; m < 4; ++m)
; #define ROW_FENCE asm volatile("" ::: "memory")
;     DI void operator()(Acc& acc, const Unit& u, int wr, int wc, int fr, int fq) const {
;     ...
;         FOR_AI_M { const int r = row0 + EPI_ROWS(ai, m);
;             const f32x4 s4 = *(const f32x4*)(ss + (size_t)r * 4);
;             const float rstd = sc * __builtin_amdgcn_rsqf(((s4[0] + s4[1]) + (s4[2] + s4[3])) * (1.f / 256.f) + EPS);
;             f32x4 cs = {1.f, 1.f, 1.f, 1.f}, sn = {0.f, 0.f, 0.f, 0.f};
;             if (rope) { const float* rr = rm + (size_t)(r & 2047) * 32; cs = *(const f32x4*)rr; sn = *(const f32x4*)(rr + 16); }
; #pragma unroll
;             for (int bj = 0; bj < 2; ++bj) {
;                 const f32x4 x1 = acc[ai][bj][m][0] * rstd, x2 = acc[ai][bj][m][1] * rstd;
;                 f32x4 a = x1, b = x2;
;                 if (ropet) { a = x1 * cs - x2 * sn; b = x1 * sn + x2 * cs; }
;                 *(u32x4*)(dst + (size_t)r * ld + colv[bj]) = pk8(a, b);
;             }
;             if (m & 1) ROW_FENCE;
;         }
.LBB0_823:
	s_waitcnt vmcnt(7)
	v_add_f32_e32 v133, v192, v193
	v_add_f32_e32 v135, v194, v195
	v_add_f32_e32 v133, v133, v135
	s_or_b32 s9, s9, s54
	v_fmamk_f32 v133, v133, 0x3b800000, v185
	s_ashr_i32 s9, s9, 6
	v_rsq_f32_e32 v133, v133
	s_mulk_i32 s9, 0x60
	v_add_u32_e32 v96, s9, v166
	s_or_b64 vcc, s[10:11], s[4:5]
	v_cndmask_b32_e32 v146, v96, v132, vcc
	v_add_u32_e32 v96, s9, v169
	v_cndmask_b32_e32 v144, v96, v131, vcc
	v_mul_f32_e32 v96, s8, v133
	v_pk_mul_f32 v[126:127], v[126:127], v[96:97] op_sel_hi:[1,0]
	v_pk_mul_f32 v[128:129], v[128:129], v[96:97] op_sel_hi:[1,0]
	v_pk_mul_f32 v[122:123], v[122:123], v[96:97] op_sel_hi:[1,0]
	v_pk_mul_f32 v[124:125], v[124:125], v[96:97] op_sel_hi:[1,0]
	v_pk_mul_f32 v[176:177], v[122:123], v[140:141]
	v_pk_mul_f32 v[174:175], v[124:125], v[142:143]
	v_pk_mul_f32 v[188:189], v[128:129], v[142:143]
	v_pk_mul_f32 v[190:191], v[126:127], v[140:141]
	v_mad_i64_i32 v[132:133], s[10:11], s30, v162, 0
	v_pk_fma_f32 v[176:177], v[126:127], v[136:137], v[176:177] neg_lo:[0,0,1] neg_hi:[0,0,1]
	v_pk_fma_f32 v[174:175], v[128:129], v[138:139], v[174:175] neg_lo:[0,0,1] neg_hi:[0,0,1]
	v_pk_fma_f32 v[190:191], v[122:123], v[136:137], v[190:191]
	v_pk_fma_f32 v[188:189], v[124:125], v[138:139], v[188:189]
	v_lshl_add_u64 v[132:133], v[132:133], 1, s[42:43]
	v_cndmask_b32_e64 v125, v125, v189, s[4:5]
	v_cndmask_b32_e64 v131, v124, v188, s[4:5]
	v_cndmask_b32_e64 v124, v123, v191, s[4:5]
	v_cndmask_b32_e64 v135, v122, v190, s[4:5]
	v_cndmask_b32_e64 v123, v129, v175, s[4:5]
	v_cndmask_b32_e64 v128, v128, v174, s[4:5]
	v_cndmask_b32_e64 v122, v127, v177, s[4:5]
	v_cndmask_b32_e64 v126, v126, v176, s[4:5]
	v_ashrrev_i32_e32 v147, 31, v146
	v_cvt_pk_bf16_f32 v122, v126, v122
	v_cvt_pk_bf16_f32 v123, v128, v123
	v_cvt_pk_bf16_f32 v124, v135, v124
	v_cvt_pk_bf16_f32 v125, v131, v125
	v_lshl_add_u64 v[126:127], v[146:147], 1, v[132:133]
	v_pk_mul_f32 v[118:119], v[118:119], v[96:97] op_sel_hi:[1,0]
	v_pk_mul_f32 v[120:121], v[120:121], v[96:97] op_sel_hi:[1,0]
	v_pk_mul_f32 v[114:115], v[114:115], v[96:97] op_sel_hi:[1,0]
	v_pk_mul_f32 v[116:117], v[116:117], v[96:97] op_sel_hi:[1,0]
	global_store_dwordx4 v[126:127], v[122:125], off sc1
	v_pk_mul_f32 v[126:127], v[120:121], v[142:143]
	v_pk_mul_f32 v[128:129], v[118:119], v[140:141]
	v_pk_mul_f32 v[122:123], v[116:117], v[142:143]
	v_pk_mul_f32 v[124:125], v[114:115], v[140:141]
	v_pk_fma_f32 v[122:123], v[120:121], v[138:139], v[122:123] neg_lo:[0,0,1] neg_hi:[0,0,1]
	v_pk_fma_f32 v[124:125], v[118:119], v[136:137], v[124:125] neg_lo:[0,0,1] neg_hi:[0,0,1]
	v_pk_fma_f32 v[128:129], v[114:115], v[136:137], v[128:129]
	v_pk_fma_f32 v[126:127], v[116:117], v[138:139], v[126:127]
	v_cndmask_b32_e64 v120, v120, v122, s[4:5]
	v_cndmask_b32_e64 v96, v117, v127, s[4:5]
	v_cndmask_b32_e64 v117, v116, v126, s[4:5]
	v_cndmask_b32_e64 v116, v115, v129, s[4:5]
	v_cndmask_b32_e64 v126, v114, v128, s[4:5]
	v_cndmask_b32_e64 v115, v121, v123, s[4:5]
	v_cndmask_b32_e64 v114, v119, v125, s[4:5]
	v_cndmask_b32_e64 v118, v118, v124, s[4:5]
	v_ashrrev_i32_e32 v145, 31, v144
	v_cvt_pk_bf16_f32 v114, v118, v114
	v_cvt_pk_bf16_f32 v115, v120, v115
	v_cvt_pk_bf16_f32 v116, v126, v116
	v_cvt_pk_bf16_f32 v117, v117, v96
	v_lshl_add_u64 v[118:119], v[144:145], 1, v[132:133]
	global_store_dwordx4 v[118:119], v[114:117], off sc1
	v_or_b32_e32 v118, 16, v162
	v_ashrrev_i32_e32 v119, 31, v118
	v_lshl_add_u64 v[114:115], v[118:119], 4, s[50:51]
	s_and_b64 vcc, exec, s[6:7]
	v_mov_b32_e32 v131, 1.0
	v_mov_b32_e32 v132, 1.0
	v_mov_b32_e32 v133, 1.0
	v_mov_b32_e32 v135, 0
	v_mov_b32_e32 v136, 0
	v_mov_b32_e32 v137, 0
	s_mov_b32 s31, 0x26000
	s_cbranch_vccnz .LBB0_825
	v_lshlrev_b32_e32 v96, 7, v118
	v_and_b32_e32 v96, 0x3ef80, v96
	v_lshl_add_u64 v[120:121], v[156:157], 0, v[96:97]
	global_load_dwordx4 v[130:133], v[120:121], off
	global_load_dwordx4 v[134:137], v[120:121], off offset:64
	s_waitcnt vmcnt(0)
.LBB0_825:
	s_waitcnt vmcnt(8)
	v_add_f32_e32 v96, v196, v197
	v_add_f32_e32 v114, v198, v199
	v_add_f32_e32 v96, v96, v114
	v_fmamk_f32 v96, v96, 0x3b800000, v185
	v_rsq_f32_e32 v96, v96
	v_mad_i64_i32 v[114:115], s[10:11], s30, v118, 0
	v_lshl_add_u64 v[114:115], v[114:115], 1, s[42:43]
	v_mul_f32_e32 v96, s8, v96
	v_pk_mul_f32 v[110:111], v[110:111], v[96:97] op_sel_hi:[1,0]
	v_pk_mul_f32 v[112:113], v[112:113], v[96:97] op_sel_hi:[1,0]
	v_pk_mul_f32 v[106:107], v[106:107], v[96:97] op_sel_hi:[1,0]
	v_pk_mul_f32 v[108:109], v[108:109], v[96:97] op_sel_hi:[1,0]
	v_pk_mul_f32 v[118:119], v[106:107], v[134:135]
	v_pk_mul_f32 v[116:117], v[108:109], v[136:137]
	v_pk_mul_f32 v[120:121], v[112:113], v[136:137]
	v_pk_mul_f32 v[122:123], v[110:111], v[134:135]
	v_pk_fma_f32 v[118:119], v[110:111], v[130:131], v[118:119] neg_lo:[0,0,1] neg_hi:[0,0,1]
	v_pk_fma_f32 v[116:117], v[112:113], v[132:133], v[116:117] neg_lo:[0,0,1] neg_hi:[0,0,1]
	v_pk_fma_f32 v[122:123], v[106:107], v[130:131], v[122:123]
	v_pk_fma_f32 v[120:121], v[108:109], v[132:133], v[120:121]
	v_cndmask_b32_e64 v112, v112, v116, s[4:5]
	v_cndmask_b32_e64 v109, v109, v121, s[4:5]
	v_cndmask_b32_e64 v120, v108, v120, s[4:5]
	v_cndmask_b32_e64 v108, v107, v123, s[4:5]
	v_cndmask_b32_e64 v121, v106, v122, s[4:5]
	v_cndmask_b32_e64 v107, v113, v117, s[4:5]
	v_cndmask_b32_e64 v106, v111, v119, s[4:5]
	v_cndmask_b32_e64 v110, v110, v118, s[4:5]
	v_cvt_pk_bf16_f32 v106, v110, v106
	v_cvt_pk_bf16_f32 v107, v112, v107
	v_cvt_pk_bf16_f32 v108, v121, v108
	v_cvt_pk_bf16_f32 v109, v120, v109
	v_lshl_add_u64 v[110:111], v[146:147], 1, v[114:115]
	v_pk_mul_f32 v[102:103], v[102:103], v[96:97] op_sel_hi:[1,0]
	v_pk_mul_f32 v[104:105], v[104:105], v[96:97] op_sel_hi:[1,0]
; DI u32x4 pk8(const f32x4& a, const f32x4& b) { u32x4 w; w.x = pk2(a[0], a[1]); w.y = pk2(a[2], a[3]); w.z = pk2(b[0], b[1]); w.w = pk2(b[2], b[3]); return w; }
; #define FOR_AI_M _Pragma("unroll") for (int ai = 0; ai < 2; ++ai) _Pragma("unroll") for (int m = 0; m < 4; ++m)
; #define ROW_FENCE asm volatile("" ::: "memory")
;     DI void operator()(Acc& acc, const Unit& u, int wr, int wc, int fr, int fq) const {
;     ...
;         FOR_AI_M { const int r = row0 + EPI_ROWS(ai, m);
;             const f32x4 s4 = *(const f32x4*)(ss + (size_t)r * 4);
;             const float rstd = sc * __builtin_amdgcn_rsqf(((s4[0] + s4[1]) + (s4[2] + s4[3])) * (1.f / 256.f) + EPS);
;             f32x4 cs = {1.f, 1.f, 1.f, 1.f}, sn = {0.f, 0.f, 0.f, 0.f};
;             if (rope) { const float* rr = rm + (size_t)(r & 2047) * 32; cs = *(const f32x4*)rr; sn = *(const f32x4*)(rr + 16); }
; #pragma unroll
;             for (int bj = 0; bj < 2; ++bj) {
;                 const f32x4 x1 = acc[ai][bj][m][0] * rstd, x2 = acc[ai][bj][m][1] * rstd;
;                 f32x4 a = x1, b = x2;
;                 if (ropet) { a = x1 * cs - x2 * sn; b = x1 * sn + x2 * cs; }
;                 *(u32x4*)(dst + (size_t)r * ld + colv[bj]) = pk8(a, b);
;             }
;             if (m & 1) ROW_FENCE;
;         }
	v_pk_mul_f32 v[98:99], v[98:99], v[96:97] op_sel_hi:[1,0]
	v_pk_mul_f32 v[100:101], v[100:101], v[96:97] op_sel_hi:[1,0]
	global_store_dwordx4 v[110:111], v[106:109], off sc1
	v_pk_mul_f32 v[110:111], v[104:105], v[136:137]
	v_pk_mul_f32 v[112:113], v[102:103], v[134:135]
	v_pk_mul_f32 v[106:107], v[100:101], v[136:137]
	v_pk_mul_f32 v[108:109], v[98:99], v[134:135]
	v_pk_fma_f32 v[106:107], v[104:105], v[132:133], v[106:107] neg_lo:[0,0,1] neg_hi:[0,0,1]
	v_pk_fma_f32 v[108:109], v[102:103], v[130:131], v[108:109] neg_lo:[0,0,1] neg_hi:[0,0,1]
	v_pk_fma_f32 v[112:113], v[98:99], v[130:131], v[112:113]
	v_pk_fma_f32 v[110:111], v[100:101], v[132:133], v[110:111]
	v_cndmask_b32_e64 v104, v104, v106, s[4:5]
	v_cndmask_b32_e64 v96, v101, v111, s[4:5]
	v_cndmask_b32_e64 v101, v100, v110, s[4:5]
	v_cndmask_b32_e64 v100, v99, v113, s[4:5]
	v_cndmask_b32_e64 v110, v98, v112, s[4:5]
	v_cndmask_b32_e64 v99, v105, v107, s[4:5]
	v_cndmask_b32_e64 v98, v103, v109, s[4:5]
	v_cndmask_b32_e64 v102, v102, v108, s[4:5]
	v_cvt_pk_bf16_f32 v98, v102, v98
	v_cvt_pk_bf16_f32 v99, v104, v99
	v_cvt_pk_bf16_f32 v100, v110, v100
	v_cvt_pk_bf16_f32 v101, v101, v96
	v_lshl_add_u64 v[102:103], v[144:145], 1, v[114:115]
	global_store_dwordx4 v[102:103], v[98:101], off sc1
	v_mov_b32_e32 v102, 0
	s_and_b64 vcc, exec, s[6:7]
	v_or_b32_e32 v100, 32, v162
	v_ashrrev_i32_e32 v101, 31, v100
	v_lshl_add_u64 v[98:99], v[100:101], 4, s[50:51]
	v_mov_b32_e32 v98, 1.0
	v_mov_b32_e32 v104, 1.0
	v_mov_b32_e32 v105, 1.0
	v_mov_b32_e32 v106, 1.0
	v_mov_b32_e32 v107, 1.0
	v_mov_b32_e32 v108, 0
	v_mov_b32_e32 v109, 0
	v_mov_b32_e32 v110, 0
	v_mov_b32_e32 v111, 0
	s_cbranch_vccnz .LBB0_827
	v_lshlrev_b32_e32 v96, 7, v100
	v_and_b32_e32 v96, 0x3f780, v96
	v_lshl_add_u64 v[108:109], v[156:157], 0, v[96:97]
	global_load_dwordx4 v[104:107], v[108:109], off
	s_nop 0
	global_load_dwordx4 v[108:111], v[108:109], off offset:64
	s_waitcnt vmcnt(0)
.LBB0_827:
	s_waitcnt vmcnt(9)
	v_add_f32_e32 v96, v200, v201
	v_add_f32_e32 v99, v202, v203
	v_add_f32_e32 v96, v96, v99
	v_fmamk_f32 v96, v96, 0x3b800000, v185
	v_rsq_f32_e32 v96, v96
	v_mad_i64_i32 v[100:101], s[10:11], s30, v100, 0
	v_lshl_add_u64 v[100:101], v[100:101], 1, s[42:43]
	v_mul_f32_e32 v96, s8, v96
	v_pk_mul_f32 v[92:93], v[92:93], v[96:97] op_sel_hi:[1,0]
	v_pk_mul_f32 v[94:95], v[94:95], v[96:97] op_sel_hi:[1,0]
	v_pk_mul_f32 v[88:89], v[88:89], v[96:97] op_sel_hi:[1,0]
	v_pk_mul_f32 v[90:91], v[90:91], v[96:97] op_sel_hi:[1,0]
	v_pk_mul_f32 v[114:115], v[88:89], v[108:109]
	v_pk_mul_f32 v[112:113], v[90:91], v[110:111]
	v_pk_mul_f32 v[116:117], v[94:95], v[110:111]
	v_pk_mul_f32 v[118:119], v[92:93], v[108:109]
	v_pk_fma_f32 v[114:115], v[92:93], v[104:105], v[114:115] neg_lo:[0,0,1] neg_hi:[0,0,1]
	v_pk_fma_f32 v[112:113], v[94:95], v[106:107], v[112:113] neg_lo:[0,0,1] neg_hi:[0,0,1]
	v_pk_fma_f32 v[118:119], v[88:89], v[104:105], v[118:119]
	v_pk_fma_f32 v[116:117], v[90:91], v[106:107], v[116:117]
	v_cndmask_b32_e64 v103, v88, v118, s[4:5]
	v_cndmask_b32_e64 v91, v91, v117, s[4:5]
	v_cndmask_b32_e64 v99, v90, v116, s[4:5]
	v_cndmask_b32_e64 v90, v89, v119, s[4:5]
	v_cndmask_b32_e64 v89, v95, v113, s[4:5]
	v_cndmask_b32_e64 v94, v94, v112, s[4:5]
	v_cndmask_b32_e64 v88, v93, v115, s[4:5]
	v_cndmask_b32_e64 v92, v92, v114, s[4:5]
	v_cvt_pk_bf16_f32 v88, v92, v88
	v_cvt_pk_bf16_f32 v89, v94, v89
	v_cvt_pk_bf16_f32 v90, v103, v90
	v_cvt_pk_bf16_f32 v91, v99, v91
	v_lshl_add_u64 v[92:93], v[146:147], 1, v[100:101]
	v_pk_mul_f32 v[84:85], v[84:85], v[96:97] op_sel_hi:[1,0]
	v_pk_mul_f32 v[86:87], v[86:87], v[96:97] op_sel_hi:[1,0]
	v_pk_mul_f32 v[80:81], v[80:81], v[96:97] op_sel_hi:[1,0]
	v_pk_mul_f32 v[82:83], v[82:83], v[96:97] op_sel_hi:[1,0]
	global_store_dwordx4 v[92:93], v[88:91], off sc1
	v_pk_mul_f32 v[92:93], v[86:87], v[110:111]
	v_pk_mul_f32 v[94:95], v[84:85], v[108:109]
	v_pk_mul_f32 v[88:89], v[82:83], v[110:111]
	v_pk_mul_f32 v[90:91], v[80:81], v[108:109]
	v_pk_fma_f32 v[88:89], v[86:87], v[106:107], v[88:89] neg_lo:[0,0,1] neg_hi:[0,0,1]
	v_pk_fma_f32 v[90:91], v[84:85], v[104:105], v[90:91] neg_lo:[0,0,1] neg_hi:[0,0,1]
	v_pk_fma_f32 v[94:95], v[80:81], v[104:105], v[94:95]
	v_pk_fma_f32 v[92:93], v[82:83], v[106:107], v[92:93]
	v_cndmask_b32_e64 v86, v86, v88, s[4:5]
	v_cndmask_b32_e64 v83, v83, v93, s[4:5]
	v_cndmask_b32_e64 v92, v82, v92, s[4:5]
	v_cndmask_b32_e64 v82, v81, v95, s[4:5]
	v_cndmask_b32_e64 v93, v80, v94, s[4:5]
	v_cndmask_b32_e64 v81, v87, v89, s[4:5]
	v_cndmask_b32_e64 v80, v85, v91, s[4:5]
	v_cndmask_b32_e64 v84, v84, v90, s[4:5]
	v_cvt_pk_bf16_f32 v80, v84, v80
	v_cvt_pk_bf16_f32 v81, v86, v81
	v_cvt_pk_bf16_f32 v82, v93, v82
	v_cvt_pk_bf16_f32 v83, v92, v83
	v_lshl_add_u64 v[84:85], v[144:145], 1, v[100:101]
	global_store_dwordx4 v[84:85], v[80:83], off sc1
	v_or_b32_e32 v84, 48, v162
	v_ashrrev_i32_e32 v85, 31, v84
	v_lshl_add_u64 v[80:81], v[84:85], 4, s[50:51]
	s_and_b64 vcc, exec, s[6:7]
	v_mov_b32_e32 v99, 1.0
	v_mov_b32_e32 v100, 1.0
	v_mov_b32_e32 v101, 1.0
	v_mov_b32_e32 v103, 0
	v_mov_b32_e32 v104, 0
	v_mov_b32_e32 v105, 0
	s_cbranch_vccnz .LBB0_829
	v_lshlrev_b32_e32 v85, 7, v84
	v_and_b32_e32 v96, 0x3ff80, v85
	v_lshl_add_u64 v[86:87], v[156:157], 0, v[96:97]
	global_load_dwordx4 v[98:101], v[86:87], off
	global_load_dwordx4 v[102:105], v[86:87], off offset:64
	s_waitcnt vmcnt(0)
; DI u32x4 pk8(const f32x4& a, const f32x4& b) { u32x4 w; w.x = pk2(a[0], a[1]); w.y = pk2(a[2], a[3]); w.z = pk2(b[0], b[1]); w.w = pk2(b[2], b[3]); return w; }
; #define FOR_AI_M _Pragma("unroll") for (int ai = 0; ai < 2; ++ai) _Pragma("unroll") for (int m = 0; m < 4; ++m)
; #define ROW_FENCE asm volatile("" ::: "memory")
;     DI void operator()(Acc& acc, const Unit& u, int wr, int wc, int fr, int fq) const {
;     ...
;         FOR_AI_M { const int r = row0 + EPI_ROWS(ai, m);
;             const f32x4 s4 = *(const f32x4*)(ss + (size_t)r * 4);
;             const float rstd = sc * __builtin_amdgcn_rsqf(((s4[0] + s4[1]) + (s4[2] + s4[3])) * (1.f / 256.f) + EPS);
;             f32x4 cs = {1.f, 1.f, 1.f, 1.f}, sn = {0.f, 0.f, 0.f, 0.f};
;             if (rope) { const float* rr = rm + (size_t)(r & 2047) * 32; cs = *(const f32x4*)rr; sn = *(const f32x4*)(rr + 16); }
; #pragma unroll
;             for (int bj = 0; bj < 2; ++bj) {
;                 const f32x4 x1 = acc[ai][bj][m][0] * rstd, x2 = acc[ai][bj][m][1] * rstd;
;                 f32x4 a = x1, b = x2;
;                 if (ropet) { a = x1 * cs - x2 * sn; b = x1 * sn + x2 * cs; }
;                 *(u32x4*)(dst + (size_t)r * ld + colv[bj]) = pk8(a, b);
;             }
;             if (m & 1) ROW_FENCE;
;         }
.LBB0_829:
	s_waitcnt vmcnt(10)
	v_add_f32_e32 v80, v204, v205
	v_add_f32_e32 v81, v206, v207
	v_add_f32_e32 v80, v80, v81
	v_fmamk_f32 v80, v80, 0x3b800000, v185
	v_rsq_f32_e32 v82, v80
	v_mad_i64_i32 v[80:81], s[10:11], s30, v84, 0
	v_lshl_add_u64 v[80:81], v[80:81], 1, s[42:43]
	v_mul_f32_e32 v82, s8, v82
	v_pk_mul_f32 v[76:77], v[76:77], v[82:83] op_sel_hi:[1,0]
	v_pk_mul_f32 v[78:79], v[78:79], v[82:83] op_sel_hi:[1,0]
	v_pk_mul_f32 v[72:73], v[72:73], v[82:83] op_sel_hi:[1,0]
	v_pk_mul_f32 v[74:75], v[74:75], v[82:83] op_sel_hi:[1,0]
	v_pk_mul_f32 v[86:87], v[72:73], v[102:103]
	v_pk_mul_f32 v[84:85], v[74:75], v[104:105]
	v_pk_mul_f32 v[88:89], v[78:79], v[104:105]
	v_pk_mul_f32 v[90:91], v[76:77], v[102:103]
	v_pk_fma_f32 v[86:87], v[76:77], v[98:99], v[86:87] neg_lo:[0,0,1] neg_hi:[0,0,1]
	v_pk_fma_f32 v[84:85], v[78:79], v[100:101], v[84:85] neg_lo:[0,0,1] neg_hi:[0,0,1]
	v_pk_fma_f32 v[90:91], v[72:73], v[98:99], v[90:91]
	v_pk_fma_f32 v[88:89], v[74:75], v[100:101], v[88:89]
	v_cndmask_b32_e64 v78, v78, v84, s[4:5]
	v_cndmask_b32_e64 v75, v75, v89, s[4:5]
	v_cndmask_b32_e64 v83, v74, v88, s[4:5]
	v_cndmask_b32_e64 v74, v73, v91, s[4:5]
	v_cndmask_b32_e64 v88, v72, v90, s[4:5]
	v_cndmask_b32_e64 v73, v79, v85, s[4:5]
	v_cndmask_b32_e64 v72, v77, v87, s[4:5]
	v_cndmask_b32_e64 v76, v76, v86, s[4:5]
	v_cvt_pk_bf16_f32 v72, v76, v72
	v_cvt_pk_bf16_f32 v73, v78, v73
	v_cvt_pk_bf16_f32 v74, v88, v74
	v_cvt_pk_bf16_f32 v75, v83, v75
	v_lshl_add_u64 v[76:77], v[146:147], 1, v[80:81]
	v_pk_mul_f32 v[68:69], v[68:69], v[82:83] op_sel_hi:[1,0]
	v_pk_mul_f32 v[70:71], v[70:71], v[82:83] op_sel_hi:[1,0]
	v_pk_mul_f32 v[64:65], v[64:65], v[82:83] op_sel_hi:[1,0]
	v_pk_mul_f32 v[66:67], v[66:67], v[82:83] op_sel_hi:[1,0]
	global_store_dwordx4 v[76:77], v[72:75], off sc1
	v_pk_mul_f32 v[76:77], v[70:71], v[104:105]
	v_pk_mul_f32 v[78:79], v[68:69], v[102:103]
	v_pk_mul_f32 v[72:73], v[66:67], v[104:105]
	v_pk_mul_f32 v[74:75], v[64:65], v[102:103]
	v_pk_fma_f32 v[72:73], v[70:71], v[100:101], v[72:73] neg_lo:[0,0,1] neg_hi:[0,0,1]
	v_pk_fma_f32 v[74:75], v[68:69], v[98:99], v[74:75] neg_lo:[0,0,1] neg_hi:[0,0,1]
	v_pk_fma_f32 v[78:79], v[64:65], v[98:99], v[78:79]
	v_pk_fma_f32 v[76:77], v[66:67], v[100:101], v[76:77]
	v_cndmask_b32_e64 v70, v70, v72, s[4:5]
	v_cndmask_b32_e64 v67, v67, v77, s[4:5]
	v_cndmask_b32_e64 v76, v66, v76, s[4:5]
	v_cndmask_b32_e64 v66, v65, v79, s[4:5]
	v_cndmask_b32_e64 v77, v64, v78, s[4:5]
	v_cndmask_b32_e64 v65, v71, v73, s[4:5]
	v_cndmask_b32_e64 v64, v69, v75, s[4:5]
	v_cndmask_b32_e64 v68, v68, v74, s[4:5]
	v_cvt_pk_bf16_f32 v64, v68, v64
	v_cvt_pk_bf16_f32 v65, v70, v65
	v_cvt_pk_bf16_f32 v66, v77, v66
	v_cvt_pk_bf16_f32 v67, v76, v67
	v_lshl_add_u64 v[68:69], v[144:145], 1, v[80:81]
	global_store_dwordx4 v[68:69], v[64:67], off sc1
	v_mov_b32_e32 v68, 0
	s_and_b64 vcc, exec, s[6:7]
	v_add_u32_e32 v66, 0x80, v162
	v_ashrrev_i32_e32 v67, 31, v66
	v_lshl_add_u64 v[64:65], v[66:67], 4, s[50:51]
	v_mov_b32_e32 v64, 1.0
	v_mov_b32_e32 v70, 1.0
	v_mov_b32_e32 v71, 1.0
	v_mov_b32_e32 v72, 1.0
	v_mov_b32_e32 v73, 1.0
	v_mov_b32_e32 v74, 0
	v_mov_b32_e32 v75, 0
	v_mov_b32_e32 v76, 0
	v_mov_b32_e32 v77, 0
	s_cbranch_vccnz .LBB0_831
	v_lshlrev_b32_e32 v65, 7, v66
	v_and_b32_e32 v96, 0x3e780, v65
	v_lshl_add_u64 v[74:75], v[156:157], 0, v[96:97]
	global_load_dwordx4 v[70:73], v[74:75], off
	s_nop 0
	global_load_dwordx4 v[74:77], v[74:75], off offset:64
	s_waitcnt vmcnt(0)
.LBB0_831:
	s_waitcnt vmcnt(11)
	v_add_f32_e32 v65, v208, v209
	v_add_f32_e32 v67, v210, v211
	v_add_f32_e32 v65, v65, v67
	v_fmamk_f32 v65, v65, 0x3b800000, v185
	v_rsq_f32_e32 v65, v65
	v_mad_i64_i32 v[66:67], s[10:11], s30, v66, 0
	v_lshl_add_u64 v[66:67], v[66:67], 1, s[42:43]
	v_mul_f32_e32 v78, s8, v65
	v_pk_mul_f32 v[60:61], v[60:61], v[78:79] op_sel_hi:[1,0]
	v_pk_mul_f32 v[62:63], v[62:63], v[78:79] op_sel_hi:[1,0]
	v_pk_mul_f32 v[56:57], v[56:57], v[78:79] op_sel_hi:[1,0]
	v_pk_mul_f32 v[58:59], v[58:59], v[78:79] op_sel_hi:[1,0]
	v_pk_mul_f32 v[82:83], v[56:57], v[74:75]
	v_pk_mul_f32 v[80:81], v[58:59], v[76:77]
	v_pk_mul_f32 v[84:85], v[62:63], v[76:77]
	v_pk_mul_f32 v[86:87], v[60:61], v[74:75]
	v_pk_fma_f32 v[82:83], v[60:61], v[70:71], v[82:83] neg_lo:[0,0,1] neg_hi:[0,0,1]
	v_pk_fma_f32 v[80:81], v[62:63], v[72:73], v[80:81] neg_lo:[0,0,1] neg_hi:[0,0,1]
	v_pk_fma_f32 v[86:87], v[56:57], v[70:71], v[86:87]
	v_pk_fma_f32 v[84:85], v[58:59], v[72:73], v[84:85]
	v_cndmask_b32_e64 v69, v56, v86, s[4:5]
	v_cndmask_b32_e64 v59, v59, v85, s[4:5]
	v_cndmask_b32_e64 v65, v58, v84, s[4:5]
	v_cndmask_b32_e64 v58, v57, v87, s[4:5]
	v_cndmask_b32_e64 v57, v63, v81, s[4:5]
	v_cndmask_b32_e64 v62, v62, v80, s[4:5]
	v_cndmask_b32_e64 v56, v61, v83, s[4:5]
	v_cndmask_b32_e64 v60, v60, v82, s[4:5]
	v_cvt_pk_bf16_f32 v56, v60, v56
	v_cvt_pk_bf16_f32 v57, v62, v57
	v_cvt_pk_bf16_f32 v58, v69, v58
	v_cvt_pk_bf16_f32 v59, v65, v59
	v_lshl_add_u64 v[60:61], v[146:147], 1, v[66:67]
	v_pk_mul_f32 v[52:53], v[52:53], v[78:79] op_sel_hi:[1,0]
	v_pk_mul_f32 v[54:55], v[54:55], v[78:79] op_sel_hi:[1,0]
	v_pk_mul_f32 v[48:49], v[48:49], v[78:79] op_sel_hi:[1,0]
	v_pk_mul_f32 v[50:51], v[50:51], v[78:79] op_sel_hi:[1,0]
	global_store_dwordx4 v[60:61], v[56:59], off sc1
	v_pk_mul_f32 v[60:61], v[54:55], v[76:77]
	v_pk_mul_f32 v[62:63], v[52:53], v[74:75]
	v_pk_mul_f32 v[56:57], v[50:51], v[76:77]
	v_pk_mul_f32 v[58:59], v[48:49], v[74:75]
	v_pk_fma_f32 v[56:57], v[54:55], v[72:73], v[56:57] neg_lo:[0,0,1] neg_hi:[0,0,1]
	v_pk_fma_f32 v[58:59], v[52:53], v[70:71], v[58:59] neg_lo:[0,0,1] neg_hi:[0,0,1]
	v_pk_fma_f32 v[62:63], v[48:49], v[70:71], v[62:63]
	v_pk_fma_f32 v[60:61], v[50:51], v[72:73], v[60:61]
	v_cndmask_b32_e64 v54, v54, v56, s[4:5]
	v_cndmask_b32_e64 v51, v51, v61, s[4:5]
	v_cndmask_b32_e64 v60, v50, v60, s[4:5]
	v_cndmask_b32_e64 v50, v49, v63, s[4:5]
	v_cndmask_b32_e64 v61, v48, v62, s[4:5]
	v_cndmask_b32_e64 v49, v55, v57, s[4:5]
	v_cndmask_b32_e64 v48, v53, v59, s[4:5]
	v_cndmask_b32_e64 v52, v52, v58, s[4:5]
	v_cvt_pk_bf16_f32 v48, v52, v48
	v_cvt_pk_bf16_f32 v49, v54, v49
	v_cvt_pk_bf16_f32 v50, v61, v50
	v_cvt_pk_bf16_f32 v51, v60, v51
	v_lshl_add_u64 v[52:53], v[144:145], 1, v[66:67]
	global_store_dwordx4 v[52:53], v[48:51], off sc1
	v_add_u32_e32 v52, 0x90, v162
	v_ashrrev_i32_e32 v53, 31, v52
	v_lshl_add_u64 v[48:49], v[52:53], 4, s[50:51]
	s_and_b64 vcc, exec, s[6:7]
	v_mov_b32_e32 v65, 1.0
	v_mov_b32_e32 v66, 1.0
	v_mov_b32_e32 v67, 1.0
	v_mov_b32_e32 v69, 0
	v_mov_b32_e32 v70, 0
	v_mov_b32_e32 v71, 0
	s_cbranch_vccnz .LBB0_833
	v_lshlrev_b32_e32 v53, 7, v52
	v_and_b32_e32 v96, 0x3ef80, v53
	v_lshl_add_u64 v[54:55], v[156:157], 0, v[96:97]
	global_load_dwordx4 v[64:67], v[54:55], off
	global_load_dwordx4 v[68:71], v[54:55], off offset:64
	s_waitcnt vmcnt(0)
; DI u32x4 pk8(const f32x4& a, const f32x4& b) { u32x4 w; w.x = pk2(a[0], a[1]); w.y = pk2(a[2], a[3]); w.z = pk2(b[0], b[1]); w.w = pk2(b[2], b[3]); return w; }
; #define FOR_AI_M _Pragma("unroll") for (int ai = 0; ai < 2; ++ai) _Pragma("unroll") for (int m = 0; m < 4; ++m)
;     DI void operator()(Acc& acc, const Unit& u, int wr, int wc, int fr, int fq) const {
;     ...
;         FOR_AI_M { const int r = row0 + EPI_ROWS(ai, m);
;             const f32x4 s4 = *(const f32x4*)(ss + (size_t)r * 4);
;             const float rstd = sc * __builtin_amdgcn_rsqf(((s4[0] + s4[1]) + (s4[2] + s4[3])) * (1.f / 256.f) + EPS);
;             f32x4 cs = {1.f, 1.f, 1.f, 1.f}, sn = {0.f, 0.f, 0.f, 0.f};
;             if (rope) { const float* rr = rm + (size_t)(r & 2047) * 32; cs = *(const f32x4*)rr; sn = *(const f32x4*)(rr + 16); }
; #pragma unroll
;             for (int bj = 0; bj < 2; ++bj) {
;                 const f32x4 x1 = acc[ai][bj][m][0] * rstd, x2 = acc[ai][bj][m][1] * rstd;
;                 f32x4 a = x1, b = x2;
;                 if (ropet) { a = x1 * cs - x2 * sn; b = x1 * sn + x2 * cs; }
;                 *(u32x4*)(dst + (size_t)r * ld + colv[bj]) = pk8(a, b);
;             }
.LBB0_833:
	s_waitcnt vmcnt(12)
	v_add_f32_e32 v48, v226, v227
	v_add_f32_e32 v49, v228, v229
	v_add_f32_e32 v48, v48, v49
	v_fmamk_f32 v48, v48, 0x3b800000, v185
	v_rsq_f32_e32 v50, v48
	v_mad_i64_i32 v[48:49], s[10:11], s30, v52, 0
	v_lshl_add_u64 v[48:49], v[48:49], 1, s[42:43]
	v_mul_f32_e32 v50, s8, v50
	v_pk_mul_f32 v[44:45], v[44:45], v[50:51] op_sel_hi:[1,0]
	v_pk_mul_f32 v[46:47], v[46:47], v[50:51] op_sel_hi:[1,0]
	v_pk_mul_f32 v[40:41], v[40:41], v[50:51] op_sel_hi:[1,0]
	v_pk_mul_f32 v[42:43], v[42:43], v[50:51] op_sel_hi:[1,0]
	v_pk_mul_f32 v[54:55], v[40:41], v[68:69]
	v_pk_mul_f32 v[52:53], v[42:43], v[70:71]
	v_pk_mul_f32 v[56:57], v[46:47], v[70:71]
	v_pk_mul_f32 v[58:59], v[44:45], v[68:69]
	v_pk_fma_f32 v[54:55], v[44:45], v[64:65], v[54:55] neg_lo:[0,0,1] neg_hi:[0,0,1]
	v_pk_fma_f32 v[52:53], v[46:47], v[66:67], v[52:53] neg_lo:[0,0,1] neg_hi:[0,0,1]
	v_pk_fma_f32 v[58:59], v[40:41], v[64:65], v[58:59]
	v_pk_fma_f32 v[56:57], v[42:43], v[66:67], v[56:57]
	v_cndmask_b32_e64 v46, v46, v52, s[4:5]
	v_cndmask_b32_e64 v43, v43, v57, s[4:5]
	v_cndmask_b32_e64 v51, v42, v56, s[4:5]
	v_cndmask_b32_e64 v42, v41, v59, s[4:5]
	v_cndmask_b32_e64 v56, v40, v58, s[4:5]
	v_cndmask_b32_e64 v41, v47, v53, s[4:5]
	v_cndmask_b32_e64 v40, v45, v55, s[4:5]
	v_cndmask_b32_e64 v44, v44, v54, s[4:5]
	v_cvt_pk_bf16_f32 v40, v44, v40
	v_cvt_pk_bf16_f32 v41, v46, v41
	v_cvt_pk_bf16_f32 v42, v56, v42
	v_cvt_pk_bf16_f32 v43, v51, v43
	v_lshl_add_u64 v[44:45], v[146:147], 1, v[48:49]
	v_pk_mul_f32 v[36:37], v[36:37], v[50:51] op_sel_hi:[1,0]
	v_pk_mul_f32 v[38:39], v[38:39], v[50:51] op_sel_hi:[1,0]
	v_pk_mul_f32 v[32:33], v[32:33], v[50:51] op_sel_hi:[1,0]
	v_pk_mul_f32 v[34:35], v[34:35], v[50:51] op_sel_hi:[1,0]
	global_store_dwordx4 v[44:45], v[40:43], off sc1
	v_pk_mul_f32 v[44:45], v[38:39], v[70:71]
	v_pk_mul_f32 v[46:47], v[36:37], v[68:69]
	v_pk_mul_f32 v[40:41], v[34:35], v[70:71]
	v_pk_mul_f32 v[42:43], v[32:33], v[68:69]
	v_pk_fma_f32 v[40:41], v[38:39], v[66:67], v[40:41] neg_lo:[0,0,1] neg_hi:[0,0,1]
	v_pk_fma_f32 v[42:43], v[36:37], v[64:65], v[42:43] neg_lo:[0,0,1] neg_hi:[0,0,1]
	v_pk_fma_f32 v[46:47], v[32:33], v[64:65], v[46:47]
	v_pk_fma_f32 v[44:45], v[34:35], v[66:67], v[44:45]
	v_cndmask_b32_e64 v38, v38, v40, s[4:5]
	v_cndmask_b32_e64 v35, v35, v45, s[4:5]
	v_cndmask_b32_e64 v44, v34, v44, s[4:5]
	v_cndmask_b32_e64 v34, v33, v47, s[4:5]
	v_cndmask_b32_e64 v45, v32, v46, s[4:5]
	v_cndmask_b32_e64 v33, v39, v41, s[4:5]
	v_cndmask_b32_e64 v32, v37, v43, s[4:5]
	v_cndmask_b32_e64 v36, v36, v42, s[4:5]
	v_cvt_pk_bf16_f32 v32, v36, v32
	v_cvt_pk_bf16_f32 v33, v38, v33
	v_cvt_pk_bf16_f32 v34, v45, v34
	v_cvt_pk_bf16_f32 v35, v44, v35
	v_lshl_add_u64 v[36:37], v[144:145], 1, v[48:49]
	global_store_dwordx4 v[36:37], v[32:35], off sc1
	v_mov_b32_e32 v36, 0
	s_and_b64 vcc, exec, s[6:7]
	v_add_u32_e32 v34, 0xa0, v162
	v_ashrrev_i32_e32 v35, 31, v34
	v_lshl_add_u64 v[32:33], v[34:35], 4, s[50:51]
	v_mov_b32_e32 v32, 1.0
	v_mov_b32_e32 v38, 1.0
	v_mov_b32_e32 v39, 1.0
	v_mov_b32_e32 v40, 1.0
	v_mov_b32_e32 v41, 1.0
	v_mov_b32_e32 v42, 0
	v_mov_b32_e32 v43, 0
	v_mov_b32_e32 v44, 0
	v_mov_b32_e32 v45, 0
	s_cbranch_vccnz .LBB0_835
	v_lshlrev_b32_e32 v33, 7, v34
	v_and_b32_e32 v96, 0x3f780, v33
	v_lshl_add_u64 v[42:43], v[156:157], 0, v[96:97]
	global_load_dwordx4 v[38:41], v[42:43], off
	s_nop 0
	global_load_dwordx4 v[42:45], v[42:43], off offset:64
	s_waitcnt vmcnt(0)
; DI u32x4 pk8(const f32x4& a, const f32x4& b) { u32x4 w; w.x = pk2(a[0], a[1]); w.y = pk2(a[2], a[3]); w.z = pk2(b[0], b[1]); w.w = pk2(b[2], b[3]); return w; }
; #define PG8_BAR __builtin_amdgcn_s_barrier()
; #define FOR_AI_M _Pragma("unroll") for (int ai = 0; ai < 2; ++ai) _Pragma("unroll") for (int m = 0; m < 4; ++m)
; #define ROW_FENCE asm volatile("" ::: "memory")
;     ...
;         if (!has_next) break;
;         if (cur.last) {
; #pragma unroll
;             for (int a = 0; a < 2; ++a)
; #pragma unroll
;                 for (int b = 0; b < 2; ++b)
; #pragma unroll
;                     for (int m = 0; m < 4; ++m)
; #pragma unroll
;                         for (int n = 0; n < 2; ++n) acc[a][b][m][n] = (f32x4){0.f, 0.f, 0.f, 0.f};
;         }
;         cur = nxt; cA = nA; cB = nB; ++ui;
;         if (wr == 1) PG8_BAR;
;     DI void operator()(Acc& acc, const Unit& u, int wr, int wc, int fr, int fq) const {
;     ...
;         FOR_AI_M { const int r = row0 + EPI_ROWS(ai, m);
;             const f32x4 s4 = *(const f32x4*)(ss + (size_t)r * 4);
;             const float rstd = sc * __builtin_amdgcn_rsqf(((s4[0] + s4[1]) + (s4[2] + s4[3])) * (1.f / 256.f) + EPS);
;             f32x4 cs = {1.f, 1.f, 1.f, 1.f}, sn = {0.f, 0.f, 0.f, 0.f};
;             if (rope) { const float* rr = rm + (size_t)(r & 2047) * 32; cs = *(const f32x4*)rr; sn = *(const f32x4*)(rr + 16); }
; #pragma unroll
;             for (int bj = 0; bj < 2; ++bj) {
;                 const f32x4 x1 = acc[ai][bj][m][0] * rstd, x2 = acc[ai][bj][m][1] * rstd;
;                 f32x4 a = x1, b = x2;
;                 if (ropet) { a = x1 * cs - x2 * sn; b = x1 * sn + x2 * cs; }
;                 *(u32x4*)(dst + (size_t)r * ld + colv[bj]) = pk8(a, b);
;             }
;             if (m & 1) ROW_FENCE;
;         }
.LBB0_835:
	s_waitcnt vmcnt(13)
	v_add_f32_e32 v33, v230, v231
	v_add_f32_e32 v35, v232, v233
	v_add_f32_e32 v33, v33, v35
	v_fmamk_f32 v33, v33, 0x3b800000, v185
	v_rsq_f32_e32 v33, v33
	v_mad_i64_i32 v[34:35], s[10:11], s30, v34, 0
	v_lshl_add_u64 v[34:35], v[34:35], 1, s[42:43]
	v_mul_f32_e32 v46, s8, v33
	v_pk_mul_f32 v[28:29], v[28:29], v[46:47] op_sel_hi:[1,0]
	v_pk_mul_f32 v[30:31], v[30:31], v[46:47] op_sel_hi:[1,0]
	v_pk_mul_f32 v[24:25], v[24:25], v[46:47] op_sel_hi:[1,0]
	v_pk_mul_f32 v[26:27], v[26:27], v[46:47] op_sel_hi:[1,0]
	v_pk_mul_f32 v[50:51], v[24:25], v[42:43]
	v_pk_mul_f32 v[48:49], v[26:27], v[44:45]
	v_pk_mul_f32 v[52:53], v[30:31], v[44:45]
	v_pk_mul_f32 v[54:55], v[28:29], v[42:43]
	v_pk_fma_f32 v[50:51], v[28:29], v[38:39], v[50:51] neg_lo:[0,0,1] neg_hi:[0,0,1]
	v_pk_fma_f32 v[48:49], v[30:31], v[40:41], v[48:49] neg_lo:[0,0,1] neg_hi:[0,0,1]
	v_pk_fma_f32 v[54:55], v[24:25], v[38:39], v[54:55]
	v_pk_fma_f32 v[52:53], v[26:27], v[40:41], v[52:53]
	v_cndmask_b32_e64 v37, v24, v54, s[4:5]
	v_cndmask_b32_e64 v27, v27, v53, s[4:5]
	v_cndmask_b32_e64 v33, v26, v52, s[4:5]
	v_cndmask_b32_e64 v26, v25, v55, s[4:5]
	v_cndmask_b32_e64 v25, v31, v49, s[4:5]
	v_cndmask_b32_e64 v30, v30, v48, s[4:5]
	v_cndmask_b32_e64 v24, v29, v51, s[4:5]
	v_cndmask_b32_e64 v28, v28, v50, s[4:5]
	v_cvt_pk_bf16_f32 v24, v28, v24
	v_cvt_pk_bf16_f32 v25, v30, v25
	v_cvt_pk_bf16_f32 v26, v37, v26
	v_cvt_pk_bf16_f32 v27, v33, v27
	v_lshl_add_u64 v[28:29], v[146:147], 1, v[34:35]
	v_pk_mul_f32 v[20:21], v[20:21], v[46:47] op_sel_hi:[1,0]
	v_pk_mul_f32 v[22:23], v[22:23], v[46:47] op_sel_hi:[1,0]
	v_pk_mul_f32 v[16:17], v[16:17], v[46:47] op_sel_hi:[1,0]
	v_pk_mul_f32 v[18:19], v[18:19], v[46:47] op_sel_hi:[1,0]
	global_store_dwordx4 v[28:29], v[24:27], off sc1
	v_pk_mul_f32 v[28:29], v[22:23], v[44:45]
	v_pk_mul_f32 v[30:31], v[20:21], v[42:43]
	v_pk_mul_f32 v[24:25], v[18:19], v[44:45]
	v_pk_mul_f32 v[26:27], v[16:17], v[42:43]
	v_pk_fma_f32 v[24:25], v[22:23], v[40:41], v[24:25] neg_lo:[0,0,1] neg_hi:[0,0,1]
	v_pk_fma_f32 v[26:27], v[20:21], v[38:39], v[26:27] neg_lo:[0,0,1] neg_hi:[0,0,1]
	v_pk_fma_f32 v[30:31], v[16:17], v[38:39], v[30:31]
	v_pk_fma_f32 v[28:29], v[18:19], v[40:41], v[28:29]
	v_cndmask_b32_e64 v22, v22, v24, s[4:5]
	v_cndmask_b32_e64 v19, v19, v29, s[4:5]
	v_cndmask_b32_e64 v28, v18, v28, s[4:5]
	v_cndmask_b32_e64 v18, v17, v31, s[4:5]
	v_cndmask_b32_e64 v29, v16, v30, s[4:5]
	v_cndmask_b32_e64 v17, v23, v25, s[4:5]
	v_cndmask_b32_e64 v16, v21, v27, s[4:5]
	v_cndmask_b32_e64 v20, v20, v26, s[4:5]
	v_cvt_pk_bf16_f32 v16, v20, v16
	v_cvt_pk_bf16_f32 v17, v22, v17
	v_cvt_pk_bf16_f32 v18, v29, v18
	v_cvt_pk_bf16_f32 v19, v28, v19
	v_lshl_add_u64 v[20:21], v[144:145], 1, v[34:35]
	global_store_dwordx4 v[20:21], v[16:19], off sc1
	v_add_u32_e32 v20, 0xb0, v162
	v_ashrrev_i32_e32 v21, 31, v20
	v_lshl_add_u64 v[16:17], v[20:21], 4, s[50:51]
	s_and_b64 vcc, exec, s[6:7]
	v_mov_b32_e32 v33, 1.0
	v_mov_b32_e32 v34, 1.0
	v_mov_b32_e32 v35, 1.0
	v_mov_b32_e32 v37, 0
	v_mov_b32_e32 v38, 0
	v_mov_b32_e32 v39, 0
	s_cbranch_vccnz .LBB0_837
	v_lshlrev_b32_e32 v21, 7, v20
	v_and_b32_e32 v96, 0x3ff80, v21
	v_lshl_add_u64 v[22:23], v[156:157], 0, v[96:97]
	global_load_dwordx4 v[32:35], v[22:23], off
	global_load_dwordx4 v[36:39], v[22:23], off offset:64
	s_waitcnt vmcnt(0)
.LBB0_837:
	s_waitcnt vmcnt(14)
	v_add_f32_e32 v16, v234, v235
	v_add_f32_e32 v17, v236, v237
	v_mad_i64_i32 v[18:19], s[6:7], s30, v20, 0
	v_add_f32_e32 v16, v16, v17
	v_fmamk_f32 v16, v16, 0x3b800000, v185
	v_rsq_f32_e32 v16, v16
	v_lshl_add_u64 v[18:19], v[18:19], 1, s[42:43]
	s_andn2_b64 vcc, exec, s[2:3]
	s_mov_b64 s[2:3], -1
	v_mul_f32_e32 v16, s8, v16
	v_pk_mul_f32 v[12:13], v[12:13], v[16:17] op_sel_hi:[1,0]
	v_pk_mul_f32 v[14:15], v[14:15], v[16:17] op_sel_hi:[1,0]
	v_pk_mul_f32 v[8:9], v[8:9], v[16:17] op_sel_hi:[1,0]
	v_pk_mul_f32 v[10:11], v[10:11], v[16:17] op_sel_hi:[1,0]
	v_pk_mul_f32 v[22:23], v[8:9], v[36:37]
	v_pk_mul_f32 v[20:21], v[10:11], v[38:39]
	v_pk_mul_f32 v[24:25], v[14:15], v[38:39]
	v_pk_mul_f32 v[26:27], v[12:13], v[36:37]
	v_pk_fma_f32 v[22:23], v[12:13], v[32:33], v[22:23] neg_lo:[0,0,1] neg_hi:[0,0,1]
	v_pk_fma_f32 v[20:21], v[14:15], v[34:35], v[20:21] neg_lo:[0,0,1] neg_hi:[0,0,1]
	v_pk_fma_f32 v[26:27], v[8:9], v[32:33], v[26:27]
	v_pk_fma_f32 v[24:25], v[10:11], v[34:35], v[24:25]
	v_cndmask_b32_e64 v14, v14, v20, s[4:5]
	v_cndmask_b32_e64 v11, v11, v25, s[4:5]
	v_cndmask_b32_e64 v17, v10, v24, s[4:5]
	v_cndmask_b32_e64 v10, v9, v27, s[4:5]
	v_cndmask_b32_e64 v24, v8, v26, s[4:5]
	v_cndmask_b32_e64 v9, v15, v21, s[4:5]
	v_cndmask_b32_e64 v8, v13, v23, s[4:5]
	v_cndmask_b32_e64 v12, v12, v22, s[4:5]
	v_cvt_pk_bf16_f32 v8, v12, v8
	v_cvt_pk_bf16_f32 v9, v14, v9
	v_cvt_pk_bf16_f32 v10, v24, v10
	v_cvt_pk_bf16_f32 v11, v17, v11
	v_lshl_add_u64 v[12:13], v[146:147], 1, v[18:19]
	v_pk_mul_f32 v[4:5], v[4:5], v[16:17] op_sel_hi:[1,0]
	v_pk_mul_f32 v[6:7], v[6:7], v[16:17] op_sel_hi:[1,0]
	v_pk_mul_f32 v[0:1], v[0:1], v[16:17] op_sel_hi:[1,0]
	v_pk_mul_f32 v[2:3], v[2:3], v[16:17] op_sel_hi:[1,0]
	global_store_dwordx4 v[12:13], v[8:11], off sc1
	v_pk_mul_f32 v[12:13], v[6:7], v[38:39]
	v_pk_mul_f32 v[14:15], v[4:5], v[36:37]
	v_pk_mul_f32 v[8:9], v[2:3], v[38:39]
	v_pk_mul_f32 v[10:11], v[0:1], v[36:37]
	v_pk_fma_f32 v[8:9], v[6:7], v[34:35], v[8:9] neg_lo:[0,0,1] neg_hi:[0,0,1]
	v_pk_fma_f32 v[10:11], v[4:5], v[32:33], v[10:11] neg_lo:[0,0,1] neg_hi:[0,0,1]
	v_pk_fma_f32 v[14:15], v[0:1], v[32:33], v[14:15]
	v_pk_fma_f32 v[12:13], v[2:3], v[34:35], v[12:13]
	v_cndmask_b32_e64 v6, v6, v8, s[4:5]
	v_cndmask_b32_e64 v3, v3, v13, s[4:5]
	v_cndmask_b32_e64 v12, v2, v12, s[4:5]
	v_cndmask_b32_e64 v2, v1, v15, s[4:5]
	v_cndmask_b32_e64 v13, v0, v14, s[4:5]
	v_cndmask_b32_e64 v1, v7, v9, s[4:5]
	v_cndmask_b32_e64 v0, v5, v11, s[4:5]
	v_cndmask_b32_e64 v4, v4, v10, s[4:5]
	v_cvt_pk_bf16_f32 v0, v4, v0
	v_cvt_pk_bf16_f32 v1, v6, v1
	v_cvt_pk_bf16_f32 v2, v13, v2
	v_cvt_pk_bf16_f32 v3, v12, v3
	v_lshl_add_u64 v[4:5], v[144:145], 1, v[18:19]
	global_store_dwordx4 v[4:5], v[0:3], off sc1
	s_mov_b32 s50, 0x1c000
	s_mov_b32 s51, 0xf800000
	s_cbranch_vccnz .LBB0_805
	s_andn2_b64 vcc, exec, s[12:13]
	s_cbranch_vccnz .LBB0_804
	s_barrier
	s_branch .LBB0_804
